# GEMM K-loops: all per-block s_setprio flips and the already-satisfied post-barrier lgkmcnt wait removed; on top of P0 split order + nt loads
# speedup vs baseline: 1.0118x; 1.0118x over previous
; #define PG8_STAGE(bufoff, gbase, voff) do { _Pragma("unroll") for (int _i = 0; _i < 2; ++_i) \
;         __builtin_amdgcn_global_load_lds((const unsigned*)((const char*)(gbase) + (voff)[_i]), (PG8_LAS unsigned*)(lds + (bufoff) + ldsw + _i * 8192), 16, 0, 0); } while (0)
; #define PG8_LDA(dst, b, h) do { _Pragma("unroll") for (int m = 0; m < 4; ++m) _Pragma("unroll") for (int k = 0; k < 2; ++k) dst[m][k] = *(const PG8_LAS bf16x8*)(lds + PG8_SA(b, h) + aoff + m * 2048 + k * 1024); } while (0)
; #define PG8_LDB(dst, b, h) do { _Pragma("unroll") for (int n = 0; n < 2; ++n) _Pragma("unroll") for (int k = 0; k < 2; ++k) dst[n][k] = *(const PG8_LAS bf16x8*)(lds + PG8_SB(b, h) + boff + n * 2048 + k * 1024); } while (0)
; #define PG8_MMA(ai, bj, At, Bt) do { __builtin_amdgcn_s_setprio(1); _Pragma("unroll") for (int m = 0; m < 4; ++m) _Pragma("unroll") for (int n = 0; n < 2; ++n) _Pragma("unroll") for (int k = 0; k < 2; ++k) \
;         acc[ai][bj][m][n] = __builtin_amdgcn_mfma_f32_16x16x32_bf16(Bt[n][k], At[m][k], acc[ai][bj][m][n], 0, 0, 0); __builtin_amdgcn_s_setprio(0); } while (0)
; #define PG8_WAIT_V(n) asm volatile("s_waitcnt vmcnt(" #n ")" ::: "memory")
; #define PG8_WAIT_L(n) asm volatile("s_waitcnt lgkmcnt(" #n ")" ::: "memory")
; #define PG8_BAR __builtin_amdgcn_s_barrier()
; #define PG8_SCHED __builtin_amdgcn_sched_barrier(0)
; template <class Epi, class Sched, bool ALIGN_EPI = false, bool SP2 = false, bool A_TILED = false, bool B_TILED = false>
; __device__ __forceinline__ void gemm_phase(PG8_LAS unsigned char* lds, const Gemm g, const Sched& S, const Epi& E) {
;     ...
;             PG8_LDB(B0, 0, 0); PG8_LDB(B1, 0, 1); PG8_SCHED; PG8_LDA(At, 0, 0); PG8_STAGE(PG8_SA(1, 1), a1 + hstepA, voffA);
;             PG8_WAIT_V(8); PG8_WAIT_L(0); PG8_BAR; PG8_MMA(0, 0, At, B0); PG8_MMA(0, 1, At, B1); PG8_BAR; PG8_SCHED;
;             PG8_LDA(At, 0, 1); PG8_STAGE(PG8_SB(0, 0), b2, voffB); PG8_STAGE(PG8_SB(0, 1), b2 + hstepB, voffB); PG8_STAGE(PG8_SA(0, 0), a2, voffA);
;             PG8_WAIT_V(8); PG8_WAIT_L(0); PG8_BAR; PG8_MMA(1, 0, At, B0); PG8_MMA(1, 1, At, B1); PG8_BAR; PG8_SCHED;
.LBB0_102:
	ds_read_b128 v[142:145], v148
	ds_read_b128 v[152:155], v148 offset:1024
	ds_read_b128 v[156:159], v148 offset:2048
	ds_read_b128 v[160:163], v148 offset:3072
	ds_read_b128 v[164:167], v149
	ds_read_b128 v[168:171], v149 offset:1024
	ds_read_b128 v[172:175], v149 offset:2048
	ds_read_b128 v[176:179], v149 offset:3072
	s_add_u32 s36, s34, 0xfff00080
	s_addc_u32 s37, s35, -1
	s_cmp_eq_u32 s68, 60
	s_cselect_b32 s39, s21, s37
	s_cselect_b32 s38, s23, s36
	s_cselect_b32 s37, s19, s67
	s_cselect_b32 s36, s65, s66
	v_lshl_add_u64 v[214:215], s[34:35], 0, v[138:139]
	s_add_i32 m0, s25, 0xc000
	ds_read_b128 v[180:183], v150
	ds_read_b128 v[184:187], v150 offset:1024
	ds_read_b128 v[190:193], v150 offset:2048
	ds_read_b128 v[194:197], v150 offset:3072
	ds_read_b128 v[198:201], v150 offset:4096
	ds_read_b128 v[202:205], v150 offset:5120
	ds_read_b128 v[206:209], v150 offset:6144
	ds_read_b128 v[210:213], v150 offset:7168
	global_load_lds_dwordx4 v[214:215], off
	v_lshl_add_u64 v[214:215], s[34:35], 0, v[140:141]
	s_add_i32 m0, s25, 0xe000
	s_nop 0
	global_load_lds_dwordx4 v[214:215], off
	s_waitcnt vmcnt(8)
	s_waitcnt lgkmcnt(0)
	s_barrier
	v_mfma_f32_16x16x32_bf16 v[126:129], v[142:145], v[180:183], v[126:129]
	v_mfma_f32_16x16x32_bf16 v[122:125], v[156:159], v[180:183], v[122:125]
	v_mfma_f32_16x16x32_bf16 v[118:121], v[142:145], v[190:193], v[118:121]
	v_mfma_f32_16x16x32_bf16 v[110:113], v[156:159], v[190:193], v[110:113]
	v_mfma_f32_16x16x32_bf16 v[102:105], v[142:145], v[198:201], v[102:105]
	v_mfma_f32_16x16x32_bf16 v[94:97], v[156:159], v[198:201], v[94:97]
	v_mfma_f32_16x16x32_bf16 v[86:89], v[142:145], v[206:209], v[86:89]
	v_mfma_f32_16x16x32_bf16 v[78:81], v[156:159], v[206:209], v[78:81]
	v_mfma_f32_16x16x32_bf16 v[126:129], v[152:155], v[184:187], v[126:129]
	v_mfma_f32_16x16x32_bf16 v[122:125], v[160:163], v[184:187], v[122:125]
	v_mfma_f32_16x16x32_bf16 v[118:121], v[152:155], v[194:197], v[118:121]
	v_mfma_f32_16x16x32_bf16 v[110:113], v[160:163], v[194:197], v[110:113]
	v_mfma_f32_16x16x32_bf16 v[102:105], v[152:155], v[202:205], v[102:105]
	v_mfma_f32_16x16x32_bf16 v[94:97], v[160:163], v[202:205], v[94:97]
	v_mfma_f32_16x16x32_bf16 v[86:89], v[152:155], v[210:213], v[86:89]
	v_mfma_f32_16x16x32_bf16 v[78:81], v[160:163], v[210:213], v[78:81]
	v_mfma_f32_16x16x32_bf16 v[114:117], v[164:167], v[180:183], v[114:117]
	v_mfma_f32_16x16x32_bf16 v[106:109], v[172:175], v[180:183], v[106:109]
	v_mfma_f32_16x16x32_bf16 v[98:101], v[164:167], v[190:193], v[98:101]
	v_mfma_f32_16x16x32_bf16 v[90:93], v[172:175], v[190:193], v[90:93]
	v_mfma_f32_16x16x32_bf16 v[82:85], v[164:167], v[198:201], v[82:85]
	v_mfma_f32_16x16x32_bf16 v[74:77], v[172:175], v[198:201], v[74:77]
	v_mfma_f32_16x16x32_bf16 v[70:73], v[164:167], v[206:209], v[70:73]
	v_mfma_f32_16x16x32_bf16 v[66:69], v[172:175], v[206:209], v[66:69]
	v_mfma_f32_16x16x32_bf16 v[114:117], v[168:171], v[184:187], v[114:117]
	v_mfma_f32_16x16x32_bf16 v[106:109], v[176:179], v[184:187], v[106:109]
	v_mfma_f32_16x16x32_bf16 v[98:101], v[168:171], v[194:197], v[98:101]
	v_mfma_f32_16x16x32_bf16 v[90:93], v[176:179], v[194:197], v[90:93]
	v_mfma_f32_16x16x32_bf16 v[82:85], v[168:171], v[202:205], v[82:85]
	v_mfma_f32_16x16x32_bf16 v[74:77], v[176:179], v[202:205], v[74:77]
	v_mfma_f32_16x16x32_bf16 v[70:73], v[168:171], v[210:213], v[70:73]
	v_mfma_f32_16x16x32_bf16 v[66:69], v[176:179], v[210:213], v[66:69]
	s_barrier
	s_add_i32 s69, s61, s43
	v_lshl_add_u64 v[214:215], s[36:37], 0, v[132:133]
	s_mov_b32 m0, s69
	ds_read_b128 v[180:183], v150 offset:16384
	ds_read_b128 v[184:187], v150 offset:17408
	ds_read_b128 v[190:193], v150 offset:18432
	ds_read_b128 v[194:197], v150 offset:19456
	ds_read_b128 v[198:201], v150 offset:20480
	ds_read_b128 v[202:205], v150 offset:21504
	ds_read_b128 v[206:209], v150 offset:22528
	ds_read_b128 v[210:213], v150 offset:23552
	global_load_lds_dwordx4 v[214:215], off
	s_add_i32 m0, s69, 0x2000
	s_add_u32 s70, s36, 0x100000
	v_lshl_add_u64 v[216:217], s[36:37], 0, v[136:137]
	s_addc_u32 s71, s37, 0
	s_add_i32 s69, s62, s43
	global_load_lds_dwordx4 v[216:217], off
	v_lshl_add_u64 v[218:219], s[70:71], 0, v[132:133]
	s_mov_b32 m0, s69
	v_lshl_add_u64 v[220:221], s[38:39], 0, v[134:135]
	global_load_lds_dwordx4 v[218:219], off
	v_lshl_add_u64 v[218:219], s[70:71], 0, v[136:137]
	s_add_i32 m0, s69, 0x2000
	s_nop 0
	global_load_lds_dwordx4 v[218:219], off
	v_lshl_add_u64 v[218:219], s[38:39], 0, v[130:131]
	s_mov_b32 m0, s25
	s_nop 0
	global_load_lds_dwordx4 v[218:219], off
	s_mov_b32 m0, s44
	s_nop 0
	global_load_lds_dwordx4 v[220:221], off
	s_waitcnt vmcnt(8)
	s_waitcnt lgkmcnt(0)
	s_barrier
; #define PG8_STAGE(bufoff, gbase, voff) do { _Pragma("unroll") for (int _i = 0; _i < 2; ++_i) \
;         __builtin_amdgcn_global_load_lds((const unsigned*)((const char*)(gbase) + (voff)[_i]), (PG8_LAS unsigned*)(lds + (bufoff) + ldsw + _i * 8192), 16, 0, 0); } while (0)
; #define PG8_LDA(dst, b, h) do { _Pragma("unroll") for (int m = 0; m < 4; ++m) _Pragma("unroll") for (int k = 0; k < 2; ++k) dst[m][k] = *(const PG8_LAS bf16x8*)(lds + PG8_SA(b, h) + aoff + m * 2048 + k * 1024); } while (0)
; #define PG8_LDB(dst, b, h) do { _Pragma("unroll") for (int n = 0; n < 2; ++n) _Pragma("unroll") for (int k = 0; k < 2; ++k) dst[n][k] = *(const PG8_LAS bf16x8*)(lds + PG8_SB(b, h) + boff + n * 2048 + k * 1024); } while (0)
; #define PG8_MMA(ai, bj, At, Bt) do { __builtin_amdgcn_s_setprio(1); _Pragma("unroll") for (int m = 0; m < 4; ++m) _Pragma("unroll") for (int n = 0; n < 2; ++n) _Pragma("unroll") for (int k = 0; k < 2; ++k) \
;         acc[ai][bj][m][n] = __builtin_amdgcn_mfma_f32_16x16x32_bf16(Bt[n][k], At[m][k], acc[ai][bj][m][n], 0, 0, 0); __builtin_amdgcn_s_setprio(0); } while (0)
; #define PG8_WAIT_V(n) asm volatile("s_waitcnt vmcnt(" #n ")" ::: "memory")
; #define PG8_WAIT_L(n) asm volatile("s_waitcnt lgkmcnt(" #n ")" ::: "memory")
; #define PG8_BAR __builtin_amdgcn_s_barrier()
; #define PG8_SCHED __builtin_amdgcn_sched_barrier(0)
; template <class Epi, class Sched, bool ALIGN_EPI = false, bool SP2 = false, bool A_TILED = false, bool B_TILED = false>
; __device__ __forceinline__ void gemm_phase(PG8_LAS unsigned char* lds, const Gemm g, const Sched& S, const Epi& E) {
;     ...
;             PG8_WAIT_V(8); PG8_WAIT_L(0); PG8_BAR; PG8_MMA(1, 0, At, B0); PG8_MMA(1, 1, At, B1); PG8_BAR; PG8_SCHED;
;             PG8_LDB(B0, 1, 0); PG8_LDB(B1, 1, 1); PG8_SCHED; PG8_LDA(At, 1, 0); PG8_STAGE(PG8_SA(0, 1), a2 + hstepA, voffA);
;             PG8_WAIT_V(8); PG8_WAIT_L(0); PG8_BAR; PG8_MMA(0, 0, At, B0); PG8_MMA(0, 1, At, B1); PG8_BAR; PG8_SCHED;
	v_mfma_f32_16x16x32_bf16 v[62:65], v[142:145], v[180:183], v[62:65]
	v_mfma_f32_16x16x32_bf16 v[58:61], v[156:159], v[180:183], v[58:61]
	v_mfma_f32_16x16x32_bf16 v[54:57], v[142:145], v[190:193], v[54:57]
	v_mfma_f32_16x16x32_bf16 v[46:49], v[156:159], v[190:193], v[46:49]
	v_mfma_f32_16x16x32_bf16 v[38:41], v[142:145], v[198:201], v[38:41]
	v_mfma_f32_16x16x32_bf16 v[30:33], v[156:159], v[198:201], v[30:33]
	v_mfma_f32_16x16x32_bf16 v[22:25], v[142:145], v[206:209], v[22:25]
	v_mfma_f32_16x16x32_bf16 v[14:17], v[156:159], v[206:209], v[14:17]
	v_mfma_f32_16x16x32_bf16 v[62:65], v[152:155], v[184:187], v[62:65]
	v_mfma_f32_16x16x32_bf16 v[58:61], v[160:163], v[184:187], v[58:61]
	v_mfma_f32_16x16x32_bf16 v[54:57], v[152:155], v[194:197], v[54:57]
	v_mfma_f32_16x16x32_bf16 v[46:49], v[160:163], v[194:197], v[46:49]
	v_mfma_f32_16x16x32_bf16 v[38:41], v[152:155], v[202:205], v[38:41]
	v_mfma_f32_16x16x32_bf16 v[30:33], v[160:163], v[202:205], v[30:33]
	v_mfma_f32_16x16x32_bf16 v[22:25], v[152:155], v[210:213], v[22:25]
	v_mfma_f32_16x16x32_bf16 v[14:17], v[160:163], v[210:213], v[14:17]
	v_mfma_f32_16x16x32_bf16 v[50:53], v[164:167], v[180:183], v[50:53]
	v_mfma_f32_16x16x32_bf16 v[42:45], v[172:175], v[180:183], v[42:45]
	v_mfma_f32_16x16x32_bf16 v[34:37], v[164:167], v[190:193], v[34:37]
	v_mfma_f32_16x16x32_bf16 v[26:29], v[172:175], v[190:193], v[26:29]
	v_mfma_f32_16x16x32_bf16 v[18:21], v[164:167], v[198:201], v[18:21]
	v_mfma_f32_16x16x32_bf16 v[10:13], v[172:175], v[198:201], v[10:13]
	v_mfma_f32_16x16x32_bf16 v[6:9], v[164:167], v[206:209], v[6:9]
	v_mfma_f32_16x16x32_bf16 v[2:5], v[172:175], v[206:209], v[2:5]
	v_mfma_f32_16x16x32_bf16 v[50:53], v[168:171], v[184:187], v[50:53]
	v_mfma_f32_16x16x32_bf16 v[42:45], v[176:179], v[184:187], v[42:45]
	v_mfma_f32_16x16x32_bf16 v[34:37], v[168:171], v[194:197], v[34:37]
	v_mfma_f32_16x16x32_bf16 v[26:29], v[176:179], v[194:197], v[26:29]
	v_mfma_f32_16x16x32_bf16 v[18:21], v[168:171], v[202:205], v[18:21]
	v_mfma_f32_16x16x32_bf16 v[10:13], v[176:179], v[202:205], v[10:13]
	v_mfma_f32_16x16x32_bf16 v[6:9], v[168:171], v[210:213], v[6:9]
	v_mfma_f32_16x16x32_bf16 v[2:5], v[176:179], v[210:213], v[2:5]
	s_barrier
	s_add_i32 s69, 0, 0x18000
	v_add_u32_e32 v151, s69, v146
	s_add_i32 s70, 0, 0x1c000
	ds_read_b128 v[142:145], v151
	ds_read_b128 v[152:155], v151 offset:1024
	ds_read_b128 v[156:159], v151 offset:2048
	ds_read_b128 v[160:163], v151 offset:3072
	v_add_u32_e32 v151, s70, v146
	ds_read_b128 v[164:167], v151
	ds_read_b128 v[168:171], v151 offset:1024
	ds_read_b128 v[172:175], v151 offset:2048
	ds_read_b128 v[176:179], v151 offset:3072
	s_add_u32 s38, s38, 0x100000
	s_addc_u32 s39, s39, 0
	s_mov_b32 m0, s45
	v_lshl_add_u64 v[222:223], s[38:39], 0, v[130:131]
	ds_read_b128 v[180:183], v150 offset:32768
	ds_read_b128 v[184:187], v150 offset:33792
	ds_read_b128 v[190:193], v150 offset:34816
	ds_read_b128 v[194:197], v150 offset:35840
	ds_read_b128 v[198:201], v150 offset:36864
	ds_read_b128 v[202:205], v150 offset:37888
	ds_read_b128 v[206:209], v150 offset:38912
	ds_read_b128 v[210:213], v150 offset:39936
	global_load_lds_dwordx4 v[222:223], off
	v_lshl_add_u64 v[222:223], s[38:39], 0, v[134:135]
	s_mov_b32 m0, s46
	s_nop 0
	global_load_lds_dwordx4 v[222:223], off
	s_waitcnt vmcnt(8)
	s_waitcnt lgkmcnt(0)
	s_barrier
	v_mfma_f32_16x16x32_bf16 v[126:129], v[142:145], v[180:183], v[126:129]
	v_mfma_f32_16x16x32_bf16 v[122:125], v[156:159], v[180:183], v[122:125]
	v_mfma_f32_16x16x32_bf16 v[118:121], v[142:145], v[190:193], v[118:121]
	v_mfma_f32_16x16x32_bf16 v[110:113], v[156:159], v[190:193], v[110:113]
	v_mfma_f32_16x16x32_bf16 v[102:105], v[142:145], v[198:201], v[102:105]
	v_mfma_f32_16x16x32_bf16 v[94:97], v[156:159], v[198:201], v[94:97]
	v_mfma_f32_16x16x32_bf16 v[86:89], v[142:145], v[206:209], v[86:89]
	v_mfma_f32_16x16x32_bf16 v[78:81], v[156:159], v[206:209], v[78:81]
	v_mfma_f32_16x16x32_bf16 v[126:129], v[152:155], v[184:187], v[126:129]
	v_mfma_f32_16x16x32_bf16 v[122:125], v[160:163], v[184:187], v[122:125]
	v_mfma_f32_16x16x32_bf16 v[118:121], v[152:155], v[194:197], v[118:121]
	v_mfma_f32_16x16x32_bf16 v[110:113], v[160:163], v[194:197], v[110:113]
	v_mfma_f32_16x16x32_bf16 v[102:105], v[152:155], v[202:205], v[102:105]
	v_mfma_f32_16x16x32_bf16 v[94:97], v[160:163], v[202:205], v[94:97]
	v_mfma_f32_16x16x32_bf16 v[86:89], v[152:155], v[210:213], v[86:89]
	v_mfma_f32_16x16x32_bf16 v[78:81], v[160:163], v[210:213], v[78:81]
	v_mfma_f32_16x16x32_bf16 v[114:117], v[164:167], v[180:183], v[114:117]
	v_mfma_f32_16x16x32_bf16 v[106:109], v[172:175], v[180:183], v[106:109]
	v_mfma_f32_16x16x32_bf16 v[98:101], v[164:167], v[190:193], v[98:101]
	v_mfma_f32_16x16x32_bf16 v[90:93], v[172:175], v[190:193], v[90:93]
	v_mfma_f32_16x16x32_bf16 v[82:85], v[164:167], v[198:201], v[82:85]
	v_mfma_f32_16x16x32_bf16 v[74:77], v[172:175], v[198:201], v[74:77]
	v_mfma_f32_16x16x32_bf16 v[70:73], v[164:167], v[206:209], v[70:73]
	v_mfma_f32_16x16x32_bf16 v[66:69], v[172:175], v[206:209], v[66:69]
	v_mfma_f32_16x16x32_bf16 v[114:117], v[168:171], v[184:187], v[114:117]
	v_mfma_f32_16x16x32_bf16 v[106:109], v[176:179], v[184:187], v[106:109]
	v_mfma_f32_16x16x32_bf16 v[98:101], v[168:171], v[194:197], v[98:101]
	v_mfma_f32_16x16x32_bf16 v[90:93], v[176:179], v[194:197], v[90:93]
	v_mfma_f32_16x16x32_bf16 v[82:85], v[168:171], v[202:205], v[82:85]
	v_mfma_f32_16x16x32_bf16 v[74:77], v[176:179], v[202:205], v[74:77]
	v_mfma_f32_16x16x32_bf16 v[70:73], v[168:171], v[210:213], v[70:73]
	v_mfma_f32_16x16x32_bf16 v[66:69], v[176:179], v[210:213], v[66:69]
	s_barrier
; #define PG8_STAGE(bufoff, gbase, voff) do { _Pragma("unroll") for (int _i = 0; _i < 2; ++_i) \
;         __builtin_amdgcn_global_load_lds((const unsigned*)((const char*)(gbase) + (voff)[_i]), (PG8_LAS unsigned*)(lds + (bufoff) + ldsw + _i * 8192), 16, 0, 0); } while (0)
; #define PG8_LDA(dst, b, h) do { _Pragma("unroll") for (int m = 0; m < 4; ++m) _Pragma("unroll") for (int k = 0; k < 2; ++k) dst[m][k] = *(const PG8_LAS bf16x8*)(lds + PG8_SA(b, h) + aoff + m * 2048 + k * 1024); } while (0)
; #define PG8_MMA(ai, bj, At, Bt) do { __builtin_amdgcn_s_setprio(1); _Pragma("unroll") for (int m = 0; m < 4; ++m) _Pragma("unroll") for (int n = 0; n < 2; ++n) _Pragma("unroll") for (int k = 0; k < 2; ++k) \
;         acc[ai][bj][m][n] = __builtin_amdgcn_mfma_f32_16x16x32_bf16(Bt[n][k], At[m][k], acc[ai][bj][m][n], 0, 0, 0); __builtin_amdgcn_s_setprio(0); } while (0)
; #define PG8_WAIT_V(n) asm volatile("s_waitcnt vmcnt(" #n ")" ::: "memory")
; #define PG8_WAIT_L(n) asm volatile("s_waitcnt lgkmcnt(" #n ")" ::: "memory")
; #define PG8_BAR __builtin_amdgcn_s_barrier()
; #define PG8_SCHED __builtin_amdgcn_sched_barrier(0)
; template <class Epi, class Sched, bool ALIGN_EPI = false, bool SP2 = false, bool A_TILED = false, bool B_TILED = false>
; __device__ __forceinline__ void gemm_phase(PG8_LAS unsigned char* lds, const Gemm g, const Sched& S, const Epi& E) {
;     ...
;         for (int t = 0; t < nt; t += 2) {
;             const bool last = (t == nt - 2);
;             const char* a1 = cA + (size_t)(t + 1) * kstepA;
;             const char* a2 = last ? nA : cA + (size_t)(t + 2) * kstepA; const char* b2 = last ? nB : cB + (size_t)(t + 2) * kstepB;
;             const char* a3 = a2 + kstepA; const char* b3 = b2 + kstepB;
;             if (last && has_next) S.a_ready(nxt);
;     ...
;             PG8_LDA(At, 1, 1); PG8_STAGE(PG8_SB(1, 0), b3, voffB); PG8_STAGE(PG8_SB(1, 1), b3 + hstepB, voffB); PG8_STAGE(PG8_SA(1, 0), a3, voffA);
;             PG8_WAIT_V(8); PG8_WAIT_L(0); PG8_BAR; PG8_MMA(1, 0, At, B0); PG8_MMA(1, 1, At, B1); PG8_BAR; PG8_SCHED;
	s_add_i32 s38, s69, s43
	v_lshl_add_u64 v[214:215], v[214:215], 0, s[12:13]
	s_mov_b32 m0, s38
	ds_read_b128 v[180:183], v150 offset:49152
	ds_read_b128 v[184:187], v150 offset:50176
	ds_read_b128 v[190:193], v150 offset:51200
	ds_read_b128 v[194:197], v150 offset:52224
	ds_read_b128 v[198:201], v150 offset:53248
	ds_read_b128 v[202:205], v150 offset:54272
	ds_read_b128 v[206:209], v150 offset:55296
	ds_read_b128 v[210:213], v150 offset:56320
	global_load_lds_dwordx4 v[214:215], off
	s_add_i32 m0, s38, 0x2000
	s_add_u32 s36, s36, 0x100080
	v_lshl_add_u64 v[214:215], v[216:217], 0, s[12:13]
	s_addc_u32 s37, s37, 0
	s_add_i32 s38, s70, s43
	global_load_lds_dwordx4 v[214:215], off
	v_lshl_add_u64 v[214:215], s[36:37], 0, v[132:133]
	s_mov_b32 m0, s38
	s_nop 0
	global_load_lds_dwordx4 v[214:215], off
	v_lshl_add_u64 v[214:215], s[36:37], 0, v[136:137]
	s_add_i32 m0, s38, 0x2000
	s_nop 0
	global_load_lds_dwordx4 v[214:215], off
	v_lshl_add_u64 v[214:215], v[218:219], 0, s[12:13]
	s_mov_b32 m0, s47
	s_nop 0
	global_load_lds_dwordx4 v[214:215], off
	v_lshl_add_u64 v[214:215], v[220:221], 0, s[12:13]
	s_mov_b32 m0, s52
	s_nop 0
	global_load_lds_dwordx4 v[214:215], off
	s_waitcnt vmcnt(8)
	s_waitcnt lgkmcnt(0)
	s_barrier
	v_mfma_f32_16x16x32_bf16 v[62:65], v[142:145], v[180:183], v[62:65]
	v_mfma_f32_16x16x32_bf16 v[58:61], v[156:159], v[180:183], v[58:61]
	v_mfma_f32_16x16x32_bf16 v[54:57], v[142:145], v[190:193], v[54:57]
	v_mfma_f32_16x16x32_bf16 v[46:49], v[156:159], v[190:193], v[46:49]
	v_mfma_f32_16x16x32_bf16 v[38:41], v[142:145], v[198:201], v[38:41]
	v_mfma_f32_16x16x32_bf16 v[30:33], v[156:159], v[198:201], v[30:33]
	v_mfma_f32_16x16x32_bf16 v[22:25], v[142:145], v[206:209], v[22:25]
	v_mfma_f32_16x16x32_bf16 v[14:17], v[156:159], v[206:209], v[14:17]
	v_mfma_f32_16x16x32_bf16 v[62:65], v[152:155], v[184:187], v[62:65]
	v_mfma_f32_16x16x32_bf16 v[58:61], v[160:163], v[184:187], v[58:61]
	v_mfma_f32_16x16x32_bf16 v[54:57], v[152:155], v[194:197], v[54:57]
	v_mfma_f32_16x16x32_bf16 v[46:49], v[160:163], v[194:197], v[46:49]
	v_mfma_f32_16x16x32_bf16 v[38:41], v[152:155], v[202:205], v[38:41]
	v_mfma_f32_16x16x32_bf16 v[30:33], v[160:163], v[202:205], v[30:33]
	v_mfma_f32_16x16x32_bf16 v[22:25], v[152:155], v[210:213], v[22:25]
	v_mfma_f32_16x16x32_bf16 v[14:17], v[160:163], v[210:213], v[14:17]
	v_mfma_f32_16x16x32_bf16 v[50:53], v[164:167], v[180:183], v[50:53]
	v_mfma_f32_16x16x32_bf16 v[42:45], v[172:175], v[180:183], v[42:45]
	v_mfma_f32_16x16x32_bf16 v[34:37], v[164:167], v[190:193], v[34:37]
	v_mfma_f32_16x16x32_bf16 v[26:29], v[172:175], v[190:193], v[26:29]
	v_mfma_f32_16x16x32_bf16 v[18:21], v[164:167], v[198:201], v[18:21]
	v_mfma_f32_16x16x32_bf16 v[10:13], v[172:175], v[198:201], v[10:13]
	v_mfma_f32_16x16x32_bf16 v[6:9], v[164:167], v[206:209], v[6:9]
	v_mfma_f32_16x16x32_bf16 v[2:5], v[172:175], v[206:209], v[2:5]
	v_mfma_f32_16x16x32_bf16 v[50:53], v[168:171], v[184:187], v[50:53]
	v_mfma_f32_16x16x32_bf16 v[42:45], v[176:179], v[184:187], v[42:45]
	v_mfma_f32_16x16x32_bf16 v[34:37], v[168:171], v[194:197], v[34:37]
	v_mfma_f32_16x16x32_bf16 v[26:29], v[176:179], v[194:197], v[26:29]
	v_mfma_f32_16x16x32_bf16 v[18:21], v[168:171], v[202:205], v[18:21]
	v_mfma_f32_16x16x32_bf16 v[10:13], v[176:179], v[202:205], v[10:13]
	v_mfma_f32_16x16x32_bf16 v[6:9], v[168:171], v[210:213], v[6:9]
	v_mfma_f32_16x16x32_bf16 v[2:5], v[176:179], v[210:213], v[2:5]
	s_barrier
	s_add_i32 s68, s68, 2
	s_add_u32 s34, s34, 0x100
	s_addc_u32 s35, s35, 0
	s_add_u32 s66, s66, 0x100
	s_addc_u32 s67, s67, 0
	s_cmp_gt_u32 s68, 61
	s_cbranch_scc0 .LBB0_102
	s_and_b64 vcc, exec, s[14:15]
	s_cbranch_vccz .LBB0_105
	s_barrier

; #define PG8_STAGE(bufoff, gbase, voff) do { _Pragma("unroll") for (int _i = 0; _i < 2; ++_i) \
;         __builtin_amdgcn_global_load_lds((const unsigned*)((const char*)(gbase) + (voff)[_i]), (PG8_LAS unsigned*)(lds + (bufoff) + ldsw + _i * 8192), 16, 0, 0); } while (0)
; #define PG8_LDA(dst, b, h) do { _Pragma("unroll") for (int m = 0; m < 4; ++m) _Pragma("unroll") for (int k = 0; k < 2; ++k) dst[m][k] = *(const PG8_LAS bf16x8*)(lds + PG8_SA(b, h) + aoff + m * 2048 + k * 1024); } while (0)
; #define PG8_LDB(dst, b, h) do { _Pragma("unroll") for (int n = 0; n < 2; ++n) _Pragma("unroll") for (int k = 0; k < 2; ++k) dst[n][k] = *(const PG8_LAS bf16x8*)(lds + PG8_SB(b, h) + boff + n * 2048 + k * 1024); } while (0)
; #define PG8_MMA(ai, bj, At, Bt) do { __builtin_amdgcn_s_setprio(1); _Pragma("unroll") for (int m = 0; m < 4; ++m) _Pragma("unroll") for (int n = 0; n < 2; ++n) _Pragma("unroll") for (int k = 0; k < 2; ++k) \
;         acc[ai][bj][m][n] = __builtin_amdgcn_mfma_f32_16x16x32_bf16(Bt[n][k], At[m][k], acc[ai][bj][m][n], 0, 0, 0); __builtin_amdgcn_s_setprio(0); } while (0)
; #define PG8_WAIT_V(n) asm volatile("s_waitcnt vmcnt(" #n ")" ::: "memory")
; #define PG8_WAIT_L(n) asm volatile("s_waitcnt lgkmcnt(" #n ")" ::: "memory")
; #define PG8_BAR __builtin_amdgcn_s_barrier()
; #define PG8_SCHED __builtin_amdgcn_sched_barrier(0)
; template <class Epi, class Sched, bool ALIGN_EPI = false, bool SP2 = false, bool A_TILED = false, bool B_TILED = false>
; __device__ __forceinline__ void gemm_phase(PG8_LAS unsigned char* lds, const Gemm g, const Sched& S, const Epi& E) {
;     ...
;             PG8_LDB(B0, 0, 0); PG8_LDB(B1, 0, 1); PG8_SCHED; PG8_LDA(At, 0, 0); PG8_STAGE(PG8_SA(1, 1), a1 + hstepA, voffA);
;             PG8_WAIT_V(8); PG8_WAIT_L(0); PG8_BAR; PG8_MMA(0, 0, At, B0); PG8_MMA(0, 1, At, B1); PG8_BAR; PG8_SCHED;
;             PG8_LDA(At, 0, 1); PG8_STAGE(PG8_SB(0, 0), b2, voffB); PG8_STAGE(PG8_SB(0, 1), b2 + hstepB, voffB); PG8_STAGE(PG8_SA(0, 0), a2, voffA);
;             PG8_WAIT_V(8); PG8_WAIT_L(0); PG8_BAR; PG8_MMA(1, 0, At, B0); PG8_MMA(1, 1, At, B1); PG8_BAR; PG8_SCHED;
.LBB0_513:
	v_add_u32_e32 v3, s62, v161
	s_waitcnt lgkmcnt(0)
	ds_read_b128 v[152:155], v3
	ds_read_b128 v[174:177], v3 offset:1024
	ds_read_b128 v[178:181], v3 offset:2048
	ds_read_b128 v[182:185], v3 offset:3072
	v_add_u32_e32 v3, s63, v161
	ds_read_b128 v[190:193], v3
	ds_read_b128 v[196:199], v3 offset:1024
	ds_read_b128 v[200:203], v3 offset:2048
	ds_read_b128 v[204:207], v3 offset:3072
	s_add_u32 s42, s12, 0xfff00080
	s_addc_u32 s43, s13, -1
	s_cmp_eq_u32 s68, 28
	s_cselect_b32 s45, s11, s43
	s_cselect_b32 s44, s35, s42
	s_cselect_b32 s43, s31, s67
	s_cselect_b32 s42, s37, s66
	v_lshl_add_u64 v[4:5], s[12:13], 0, v[144:145]
	s_add_i32 m0, s54, 0xc000
	ds_read_b128 v[208:211], v170
	ds_read_b128 v[212:215], v170 offset:1024
	ds_read_b128 v[216:219], v170 offset:2048
	ds_read_b128 v[220:223], v170 offset:3072
	ds_read_b128 v[224:227], v170 offset:4096
	ds_read_b128 v[228:231], v170 offset:5120
	ds_read_b128 v[232:235], v170 offset:6144
	ds_read_b128 v[236:239], v170 offset:7168
	global_load_lds_dwordx4 v[4:5], off
	v_lshl_add_u64 v[4:5], s[12:13], 0, v[146:147]
	s_add_i32 m0, s54, 0xe000
	s_nop 0
	global_load_lds_dwordx4 v[4:5], off
	s_waitcnt vmcnt(8)
	s_waitcnt lgkmcnt(0)
	s_barrier
	v_mfma_f32_16x16x32_bf16 v[130:133], v[152:155], v[208:211], v[130:133]
	v_mfma_f32_16x16x32_bf16 v[126:129], v[178:181], v[208:211], v[126:129]
	v_mfma_f32_16x16x32_bf16 v[122:125], v[152:155], v[216:219], v[122:125]
	v_mfma_f32_16x16x32_bf16 v[118:121], v[178:181], v[216:219], v[118:121]
	v_mfma_f32_16x16x32_bf16 v[114:117], v[152:155], v[224:227], v[114:117]
	v_mfma_f32_16x16x32_bf16 v[110:113], v[178:181], v[224:227], v[110:113]
	v_mfma_f32_16x16x32_bf16 v[106:109], v[152:155], v[232:235], v[106:109]
	v_mfma_f32_16x16x32_bf16 v[102:105], v[178:181], v[232:235], v[102:105]
	v_mfma_f32_16x16x32_bf16 v[130:133], v[174:177], v[212:215], v[130:133]
	v_mfma_f32_16x16x32_bf16 v[126:129], v[182:185], v[212:215], v[126:129]
	v_mfma_f32_16x16x32_bf16 v[122:125], v[174:177], v[220:223], v[122:125]
	v_mfma_f32_16x16x32_bf16 v[118:121], v[182:185], v[220:223], v[118:121]
	v_mfma_f32_16x16x32_bf16 v[114:117], v[174:177], v[228:231], v[114:117]
	v_mfma_f32_16x16x32_bf16 v[110:113], v[182:185], v[228:231], v[110:113]
	v_mfma_f32_16x16x32_bf16 v[106:109], v[174:177], v[236:239], v[106:109]
	v_mfma_f32_16x16x32_bf16 v[102:105], v[182:185], v[236:239], v[102:105]
	v_mfma_f32_16x16x32_bf16 v[98:101], v[190:193], v[208:211], v[98:101]
	v_mfma_f32_16x16x32_bf16 v[94:97], v[200:203], v[208:211], v[94:97]
	v_mfma_f32_16x16x32_bf16 v[90:93], v[190:193], v[216:219], v[90:93]
	v_mfma_f32_16x16x32_bf16 v[86:89], v[200:203], v[216:219], v[86:89]
	v_mfma_f32_16x16x32_bf16 v[82:85], v[190:193], v[224:227], v[82:85]
	v_mfma_f32_16x16x32_bf16 v[78:81], v[200:203], v[224:227], v[78:81]
	v_mfma_f32_16x16x32_bf16 v[74:77], v[190:193], v[232:235], v[74:77]
	v_mfma_f32_16x16x32_bf16 v[70:73], v[200:203], v[232:235], v[70:73]
	v_mfma_f32_16x16x32_bf16 v[98:101], v[196:199], v[212:215], v[98:101]
	v_mfma_f32_16x16x32_bf16 v[94:97], v[204:207], v[212:215], v[94:97]
	v_mfma_f32_16x16x32_bf16 v[90:93], v[196:199], v[220:223], v[90:93]
	v_mfma_f32_16x16x32_bf16 v[86:89], v[204:207], v[220:223], v[86:89]
	v_mfma_f32_16x16x32_bf16 v[82:85], v[196:199], v[228:231], v[82:85]
	v_mfma_f32_16x16x32_bf16 v[78:81], v[204:207], v[228:231], v[78:81]
	v_mfma_f32_16x16x32_bf16 v[74:77], v[196:199], v[236:239], v[74:77]
	v_mfma_f32_16x16x32_bf16 v[70:73], v[204:207], v[236:239], v[70:73]
	s_barrier
	s_add_i32 s69, s62, s53
	v_lshl_add_u64 v[186:187], s[42:43], 0, v[140:141]
	s_mov_b32 m0, s69
	ds_read_b128 v[208:211], v170 offset:16384
	ds_read_b128 v[212:215], v170 offset:17408
	ds_read_b128 v[216:219], v170 offset:18432
	ds_read_b128 v[220:223], v170 offset:19456
	ds_read_b128 v[224:227], v170 offset:20480
	ds_read_b128 v[228:231], v170 offset:21504
	ds_read_b128 v[232:235], v170 offset:22528
	ds_read_b128 v[236:239], v170 offset:23552
	global_load_lds_dwordx4 v[186:187], off
	s_add_i32 m0, s69, 0x2000
	s_add_u32 s70, s42, 0x100000
	v_lshl_add_u64 v[240:241], s[42:43], 0, v[142:143]
	s_addc_u32 s71, s43, 0
	s_add_i32 s69, s63, s53
	global_load_lds_dwordx4 v[240:241], off
	v_lshl_add_u64 v[4:5], s[70:71], 0, v[140:141]
	s_mov_b32 m0, s69
	v_lshl_add_u64 v[242:243], s[44:45], 0, v[134:135]
	global_load_lds_dwordx4 v[4:5], off
	v_lshl_add_u64 v[4:5], s[70:71], 0, v[142:143]
	s_add_i32 m0, s69, 0x2000
	v_lshl_add_u64 v[244:245], s[44:45], 0, v[136:137]
	global_load_lds_dwordx4 v[4:5], off
	s_mov_b32 m0, s54
	s_nop 0
	global_load_lds_dwordx4 v[242:243], off
	s_mov_b32 m0, s55
	s_nop 0
	global_load_lds_dwordx4 v[244:245], off
	s_waitcnt vmcnt(8)
	s_waitcnt lgkmcnt(0)
	s_barrier
; #define PG8_STAGE(bufoff, gbase, voff) do { _Pragma("unroll") for (int _i = 0; _i < 2; ++_i) \
;         __builtin_amdgcn_global_load_lds((const unsigned*)((const char*)(gbase) + (voff)[_i]), (PG8_LAS unsigned*)(lds + (bufoff) + ldsw + _i * 8192), 16, 0, 0); } while (0)
; #define PG8_LDA(dst, b, h) do { _Pragma("unroll") for (int m = 0; m < 4; ++m) _Pragma("unroll") for (int k = 0; k < 2; ++k) dst[m][k] = *(const PG8_LAS bf16x8*)(lds + PG8_SA(b, h) + aoff + m * 2048 + k * 1024); } while (0)
; #define PG8_LDB(dst, b, h) do { _Pragma("unroll") for (int n = 0; n < 2; ++n) _Pragma("unroll") for (int k = 0; k < 2; ++k) dst[n][k] = *(const PG8_LAS bf16x8*)(lds + PG8_SB(b, h) + boff + n * 2048 + k * 1024); } while (0)
; #define PG8_MMA(ai, bj, At, Bt) do { __builtin_amdgcn_s_setprio(1); _Pragma("unroll") for (int m = 0; m < 4; ++m) _Pragma("unroll") for (int n = 0; n < 2; ++n) _Pragma("unroll") for (int k = 0; k < 2; ++k) \
;         acc[ai][bj][m][n] = __builtin_amdgcn_mfma_f32_16x16x32_bf16(Bt[n][k], At[m][k], acc[ai][bj][m][n], 0, 0, 0); __builtin_amdgcn_s_setprio(0); } while (0)
; #define PG8_WAIT_V(n) asm volatile("s_waitcnt vmcnt(" #n ")" ::: "memory")
; #define PG8_WAIT_L(n) asm volatile("s_waitcnt lgkmcnt(" #n ")" ::: "memory")
; #define PG8_BAR __builtin_amdgcn_s_barrier()
; #define PG8_SCHED __builtin_amdgcn_sched_barrier(0)
; template <class Epi, class Sched, bool ALIGN_EPI = false, bool SP2 = false, bool A_TILED = false, bool B_TILED = false>
; __device__ __forceinline__ void gemm_phase(PG8_LAS unsigned char* lds, const Gemm g, const Sched& S, const Epi& E) {
;     ...
;             PG8_WAIT_V(8); PG8_WAIT_L(0); PG8_BAR; PG8_MMA(1, 0, At, B0); PG8_MMA(1, 1, At, B1); PG8_BAR; PG8_SCHED;
;             PG8_LDB(B0, 1, 0); PG8_LDB(B1, 1, 1); PG8_SCHED; PG8_LDA(At, 1, 0); PG8_STAGE(PG8_SA(0, 1), a2 + hstepA, voffA);
;             PG8_WAIT_V(8); PG8_WAIT_L(0); PG8_BAR; PG8_MMA(0, 0, At, B0); PG8_MMA(0, 1, At, B1); PG8_BAR; PG8_SCHED;
	v_mfma_f32_16x16x32_bf16 v[66:69], v[152:155], v[208:211], v[66:69]
	v_mfma_f32_16x16x32_bf16 v[62:65], v[178:181], v[208:211], v[62:65]
	v_mfma_f32_16x16x32_bf16 v[58:61], v[152:155], v[216:219], v[58:61]
	v_mfma_f32_16x16x32_bf16 v[54:57], v[178:181], v[216:219], v[54:57]
	v_mfma_f32_16x16x32_bf16 v[50:53], v[152:155], v[224:227], v[50:53]
	v_mfma_f32_16x16x32_bf16 v[46:49], v[178:181], v[224:227], v[46:49]
	v_mfma_f32_16x16x32_bf16 v[42:45], v[152:155], v[232:235], v[42:45]
	v_mfma_f32_16x16x32_bf16 v[38:41], v[178:181], v[232:235], v[38:41]
	v_mfma_f32_16x16x32_bf16 v[66:69], v[174:177], v[212:215], v[66:69]
	v_mfma_f32_16x16x32_bf16 v[62:65], v[182:185], v[212:215], v[62:65]
	v_mfma_f32_16x16x32_bf16 v[58:61], v[174:177], v[220:223], v[58:61]
	v_mfma_f32_16x16x32_bf16 v[54:57], v[182:185], v[220:223], v[54:57]
	v_mfma_f32_16x16x32_bf16 v[50:53], v[174:177], v[228:231], v[50:53]
	v_mfma_f32_16x16x32_bf16 v[46:49], v[182:185], v[228:231], v[46:49]
	v_mfma_f32_16x16x32_bf16 v[42:45], v[174:177], v[236:239], v[42:45]
	v_mfma_f32_16x16x32_bf16 v[38:41], v[182:185], v[236:239], v[38:41]
	v_mfma_f32_16x16x32_bf16 v[34:37], v[190:193], v[208:211], v[34:37]
	v_mfma_f32_16x16x32_bf16 v[30:33], v[200:203], v[208:211], v[30:33]
	v_mfma_f32_16x16x32_bf16 v[26:29], v[190:193], v[216:219], v[26:29]
	v_mfma_f32_16x16x32_bf16 v[22:25], v[200:203], v[216:219], v[22:25]
	v_mfma_f32_16x16x32_bf16 v[18:21], v[190:193], v[224:227], v[18:21]
	v_mfma_f32_16x16x32_bf16 v[14:17], v[200:203], v[224:227], v[14:17]
	v_mfma_f32_16x16x32_bf16 v[10:13], v[190:193], v[232:235], v[10:13]
	v_mfma_f32_16x16x32_bf16 v[4:7], v[200:203], v[232:235], v[6:9]
	v_mfma_f32_16x16x32_bf16 v[34:37], v[196:199], v[212:215], v[34:37]
	v_mfma_f32_16x16x32_bf16 v[30:33], v[204:207], v[212:215], v[30:33]
	v_mfma_f32_16x16x32_bf16 v[26:29], v[196:199], v[220:223], v[26:29]
	v_mfma_f32_16x16x32_bf16 v[22:25], v[204:207], v[220:223], v[22:25]
	v_mfma_f32_16x16x32_bf16 v[18:21], v[196:199], v[228:231], v[18:21]
	v_mfma_f32_16x16x32_bf16 v[14:17], v[204:207], v[228:231], v[14:17]
	v_mfma_f32_16x16x32_bf16 v[10:13], v[196:199], v[236:239], v[10:13]
	v_mfma_f32_16x16x32_bf16 v[4:7], v[204:207], v[236:239], v[4:7]
	s_barrier
	s_add_i32 s69, 0, 0x18000
	v_add_u32_e32 v3, s69, v161
	s_add_i32 s70, 0, 0x1c000
	ds_read_b128 v[152:155], v3
	ds_read_b128 v[174:177], v3 offset:1024
	ds_read_b128 v[178:181], v3 offset:2048
	ds_read_b128 v[182:185], v3 offset:3072
	v_add_u32_e32 v3, s70, v161
	ds_read_b128 v[190:193], v3
	ds_read_b128 v[196:199], v3 offset:1024
	ds_read_b128 v[200:203], v3 offset:2048
	ds_read_b128 v[204:207], v3 offset:3072
	s_add_u32 s44, s44, 0x100000
	s_addc_u32 s45, s45, 0
	s_mov_b32 m0, s56
	v_lshl_add_u64 v[8:9], s[44:45], 0, v[134:135]
	ds_read_b128 v[208:211], v170 offset:32768
	ds_read_b128 v[212:215], v170 offset:33792
	ds_read_b128 v[216:219], v170 offset:34816
	ds_read_b128 v[220:223], v170 offset:35840
	ds_read_b128 v[224:227], v170 offset:36864
	ds_read_b128 v[228:231], v170 offset:37888
	ds_read_b128 v[232:235], v170 offset:38912
	ds_read_b128 v[236:239], v170 offset:39936
	global_load_lds_dwordx4 v[8:9], off
	v_lshl_add_u64 v[8:9], s[44:45], 0, v[136:137]
	s_mov_b32 m0, s57
	s_nop 0
	global_load_lds_dwordx4 v[8:9], off
	s_waitcnt vmcnt(8)
	s_waitcnt lgkmcnt(0)
	s_barrier
	v_mfma_f32_16x16x32_bf16 v[130:133], v[152:155], v[208:211], v[130:133]
	v_mfma_f32_16x16x32_bf16 v[126:129], v[178:181], v[208:211], v[126:129]
	v_mfma_f32_16x16x32_bf16 v[122:125], v[152:155], v[216:219], v[122:125]
	v_mfma_f32_16x16x32_bf16 v[118:121], v[178:181], v[216:219], v[118:121]
	v_mfma_f32_16x16x32_bf16 v[114:117], v[152:155], v[224:227], v[114:117]
	v_mfma_f32_16x16x32_bf16 v[110:113], v[178:181], v[224:227], v[110:113]
	v_mfma_f32_16x16x32_bf16 v[106:109], v[152:155], v[232:235], v[106:109]
	v_mfma_f32_16x16x32_bf16 v[102:105], v[178:181], v[232:235], v[102:105]
	v_mfma_f32_16x16x32_bf16 v[130:133], v[174:177], v[212:215], v[130:133]
	v_mfma_f32_16x16x32_bf16 v[126:129], v[182:185], v[212:215], v[126:129]
	v_mfma_f32_16x16x32_bf16 v[122:125], v[174:177], v[220:223], v[122:125]
	v_mfma_f32_16x16x32_bf16 v[118:121], v[182:185], v[220:223], v[118:121]
	v_mfma_f32_16x16x32_bf16 v[114:117], v[174:177], v[228:231], v[114:117]
	v_mfma_f32_16x16x32_bf16 v[110:113], v[182:185], v[228:231], v[110:113]
	v_mfma_f32_16x16x32_bf16 v[106:109], v[174:177], v[236:239], v[106:109]
	v_mfma_f32_16x16x32_bf16 v[102:105], v[182:185], v[236:239], v[102:105]
	v_mfma_f32_16x16x32_bf16 v[98:101], v[190:193], v[208:211], v[98:101]
	v_mfma_f32_16x16x32_bf16 v[94:97], v[200:203], v[208:211], v[94:97]
	v_mfma_f32_16x16x32_bf16 v[90:93], v[190:193], v[216:219], v[90:93]
	v_mfma_f32_16x16x32_bf16 v[86:89], v[200:203], v[216:219], v[86:89]
	v_mfma_f32_16x16x32_bf16 v[82:85], v[190:193], v[224:227], v[82:85]
	v_mfma_f32_16x16x32_bf16 v[78:81], v[200:203], v[224:227], v[78:81]
	v_mfma_f32_16x16x32_bf16 v[74:77], v[190:193], v[232:235], v[74:77]
	v_mfma_f32_16x16x32_bf16 v[70:73], v[200:203], v[232:235], v[70:73]
	v_mfma_f32_16x16x32_bf16 v[98:101], v[196:199], v[212:215], v[98:101]
	v_mfma_f32_16x16x32_bf16 v[94:97], v[204:207], v[212:215], v[94:97]
	v_mfma_f32_16x16x32_bf16 v[90:93], v[196:199], v[220:223], v[90:93]
	v_mfma_f32_16x16x32_bf16 v[86:89], v[204:207], v[220:223], v[86:89]
	v_mfma_f32_16x16x32_bf16 v[82:85], v[196:199], v[228:231], v[82:85]
	v_mfma_f32_16x16x32_bf16 v[78:81], v[204:207], v[228:231], v[78:81]
	v_mfma_f32_16x16x32_bf16 v[74:77], v[196:199], v[236:239], v[74:77]
	v_mfma_f32_16x16x32_bf16 v[70:73], v[204:207], v[236:239], v[70:73]
	s_barrier
; #define PG8_STAGE(bufoff, gbase, voff) do { _Pragma("unroll") for (int _i = 0; _i < 2; ++_i) \
;         __builtin_amdgcn_global_load_lds((const unsigned*)((const char*)(gbase) + (voff)[_i]), (PG8_LAS unsigned*)(lds + (bufoff) + ldsw + _i * 8192), 16, 0, 0); } while (0)
; #define PG8_LDA(dst, b, h) do { _Pragma("unroll") for (int m = 0; m < 4; ++m) _Pragma("unroll") for (int k = 0; k < 2; ++k) dst[m][k] = *(const PG8_LAS bf16x8*)(lds + PG8_SA(b, h) + aoff + m * 2048 + k * 1024); } while (0)
; #define PG8_MMA(ai, bj, At, Bt) do { __builtin_amdgcn_s_setprio(1); _Pragma("unroll") for (int m = 0; m < 4; ++m) _Pragma("unroll") for (int n = 0; n < 2; ++n) _Pragma("unroll") for (int k = 0; k < 2; ++k) \
;         acc[ai][bj][m][n] = __builtin_amdgcn_mfma_f32_16x16x32_bf16(Bt[n][k], At[m][k], acc[ai][bj][m][n], 0, 0, 0); __builtin_amdgcn_s_setprio(0); } while (0)
; #define PG8_WAIT_V(n) asm volatile("s_waitcnt vmcnt(" #n ")" ::: "memory")
; #define PG8_WAIT_L(n) asm volatile("s_waitcnt lgkmcnt(" #n ")" ::: "memory")
; #define PG8_BAR __builtin_amdgcn_s_barrier()
; #define PG8_SCHED __builtin_amdgcn_sched_barrier(0)
; template <class Epi, class Sched, bool ALIGN_EPI = false, bool SP2 = false, bool A_TILED = false, bool B_TILED = false>
; __device__ __forceinline__ void gemm_phase(PG8_LAS unsigned char* lds, const Gemm g, const Sched& S, const Epi& E) {
;     ...
;         for (int t = 0; t < nt; t += 2) {
;             const bool last = (t == nt - 2);
;             const char* a1 = cA + (size_t)(t + 1) * kstepA;
;             const char* a2 = last ? nA : cA + (size_t)(t + 2) * kstepA; const char* b2 = last ? nB : cB + (size_t)(t + 2) * kstepB;
;             const char* a3 = a2 + kstepA; const char* b3 = b2 + kstepB;
;             if (last && has_next) S.a_ready(nxt);
;     ...
;             PG8_LDA(At, 1, 1); PG8_STAGE(PG8_SB(1, 0), b3, voffB); PG8_STAGE(PG8_SB(1, 1), b3 + hstepB, voffB); PG8_STAGE(PG8_SA(1, 0), a3, voffA);
;             PG8_WAIT_V(8); PG8_WAIT_L(0); PG8_BAR; PG8_MMA(1, 0, At, B0); PG8_MMA(1, 1, At, B1); PG8_BAR; PG8_SCHED;
	s_add_i32 s44, s69, s53
	v_lshl_add_u64 v[8:9], v[186:187], 0, s[26:27]
	s_mov_b32 m0, s44
	ds_read_b128 v[208:211], v170 offset:49152
	ds_read_b128 v[212:215], v170 offset:50176
	ds_read_b128 v[216:219], v170 offset:51200
	ds_read_b128 v[220:223], v170 offset:52224
	ds_read_b128 v[224:227], v170 offset:53248
	ds_read_b128 v[228:231], v170 offset:54272
	ds_read_b128 v[232:235], v170 offset:55296
	ds_read_b128 v[236:239], v170 offset:56320
	global_load_lds_dwordx4 v[8:9], off
	s_add_i32 m0, s44, 0x2000
	s_add_u32 s42, s42, 0x100080
	v_lshl_add_u64 v[8:9], v[240:241], 0, s[26:27]
	s_addc_u32 s43, s43, 0
	s_add_i32 s44, s70, s53
	global_load_lds_dwordx4 v[8:9], off
	v_lshl_add_u64 v[8:9], s[42:43], 0, v[140:141]
	s_mov_b32 m0, s44
	s_nop 0
	global_load_lds_dwordx4 v[8:9], off
	v_lshl_add_u64 v[8:9], s[42:43], 0, v[142:143]
	s_add_i32 m0, s44, 0x2000
	s_nop 0
	global_load_lds_dwordx4 v[8:9], off
	v_lshl_add_u64 v[8:9], v[242:243], 0, s[26:27]
	s_mov_b32 m0, s59
	s_nop 0
	global_load_lds_dwordx4 v[8:9], off
	v_lshl_add_u64 v[8:9], v[244:245], 0, s[26:27]
	s_mov_b32 m0, s60
	s_nop 0
	global_load_lds_dwordx4 v[8:9], off
	s_waitcnt vmcnt(8)
	s_waitcnt lgkmcnt(0)
	s_barrier
	v_mfma_f32_16x16x32_bf16 v[66:69], v[152:155], v[208:211], v[66:69]
	v_mfma_f32_16x16x32_bf16 v[62:65], v[178:181], v[208:211], v[62:65]
	v_mfma_f32_16x16x32_bf16 v[58:61], v[152:155], v[216:219], v[58:61]
	v_mfma_f32_16x16x32_bf16 v[54:57], v[178:181], v[216:219], v[54:57]
	v_mfma_f32_16x16x32_bf16 v[50:53], v[152:155], v[224:227], v[50:53]
	v_mfma_f32_16x16x32_bf16 v[46:49], v[178:181], v[224:227], v[46:49]
	v_mfma_f32_16x16x32_bf16 v[42:45], v[152:155], v[232:235], v[42:45]
	v_mfma_f32_16x16x32_bf16 v[38:41], v[178:181], v[232:235], v[38:41]
	v_mfma_f32_16x16x32_bf16 v[66:69], v[174:177], v[212:215], v[66:69]
	v_mfma_f32_16x16x32_bf16 v[62:65], v[182:185], v[212:215], v[62:65]
	v_mfma_f32_16x16x32_bf16 v[58:61], v[174:177], v[220:223], v[58:61]
	v_mfma_f32_16x16x32_bf16 v[54:57], v[182:185], v[220:223], v[54:57]
	v_mfma_f32_16x16x32_bf16 v[50:53], v[174:177], v[228:231], v[50:53]
	v_mfma_f32_16x16x32_bf16 v[46:49], v[182:185], v[228:231], v[46:49]
	v_mfma_f32_16x16x32_bf16 v[42:45], v[174:177], v[236:239], v[42:45]
	v_mfma_f32_16x16x32_bf16 v[38:41], v[182:185], v[236:239], v[38:41]
	v_mfma_f32_16x16x32_bf16 v[34:37], v[190:193], v[208:211], v[34:37]
	v_mfma_f32_16x16x32_bf16 v[30:33], v[200:203], v[208:211], v[30:33]
	v_mfma_f32_16x16x32_bf16 v[26:29], v[190:193], v[216:219], v[26:29]
	v_mfma_f32_16x16x32_bf16 v[22:25], v[200:203], v[216:219], v[22:25]
	v_mfma_f32_16x16x32_bf16 v[18:21], v[190:193], v[224:227], v[18:21]
	v_mfma_f32_16x16x32_bf16 v[14:17], v[200:203], v[224:227], v[14:17]
	v_mfma_f32_16x16x32_bf16 v[8:11], v[190:193], v[232:235], v[10:13]
	v_mfma_f32_16x16x32_bf16 v[4:7], v[200:203], v[232:235], v[4:7]
	v_mfma_f32_16x16x32_bf16 v[34:37], v[196:199], v[212:215], v[34:37]
	v_mfma_f32_16x16x32_bf16 v[30:33], v[204:207], v[212:215], v[30:33]
	v_mfma_f32_16x16x32_bf16 v[26:29], v[196:199], v[220:223], v[26:29]
	v_mfma_f32_16x16x32_bf16 v[22:25], v[204:207], v[220:223], v[22:25]
	v_mfma_f32_16x16x32_bf16 v[18:21], v[196:199], v[228:231], v[18:21]
	v_mfma_f32_16x16x32_bf16 v[14:17], v[204:207], v[228:231], v[14:17]
	v_mfma_f32_16x16x32_bf16 v[10:13], v[196:199], v[236:239], v[8:11]
	v_mfma_f32_16x16x32_bf16 v[6:9], v[204:207], v[236:239], v[4:7]
	s_barrier
	s_add_i32 s68, s68, 2
	s_add_u32 s12, s12, 0x100
	s_addc_u32 s13, s13, 0
	s_add_u32 s66, s66, 0x100
	s_addc_u32 s67, s67, 0
	s_cmp_gt_u32 s68, 29
	s_cbranch_scc0 .LBB0_513
	s_and_b64 vcc, exec, s[28:29]
	s_cbranch_vccz .LBB0_516
	s_barrier

; #define PG8_STAGE(bufoff, gbase, voff) do { _Pragma("unroll") for (int _i = 0; _i < 2; ++_i) \
;         __builtin_amdgcn_global_load_lds((const unsigned*)((const char*)(gbase) + (voff)[_i]), (PG8_LAS unsigned*)(lds + (bufoff) + ldsw + _i * 8192), 16, 0, 0); } while (0)
; #define PG8_LDA(dst, b, h) do { _Pragma("unroll") for (int m = 0; m < 4; ++m) _Pragma("unroll") for (int k = 0; k < 2; ++k) dst[m][k] = *(const PG8_LAS bf16x8*)(lds + PG8_SA(b, h) + aoff + m * 2048 + k * 1024); } while (0)
; #define PG8_LDB(dst, b, h) do { _Pragma("unroll") for (int n = 0; n < 2; ++n) _Pragma("unroll") for (int k = 0; k < 2; ++k) dst[n][k] = *(const PG8_LAS bf16x8*)(lds + PG8_SB(b, h) + boff + n * 2048 + k * 1024); } while (0)
; #define PG8_MMA(ai, bj, At, Bt) do { __builtin_amdgcn_s_setprio(1); _Pragma("unroll") for (int m = 0; m < 4; ++m) _Pragma("unroll") for (int n = 0; n < 2; ++n) _Pragma("unroll") for (int k = 0; k < 2; ++k) \
;         acc[ai][bj][m][n] = __builtin_amdgcn_mfma_f32_16x16x32_bf16(Bt[n][k], At[m][k], acc[ai][bj][m][n], 0, 0, 0); __builtin_amdgcn_s_setprio(0); } while (0)
; #define PG8_WAIT_V(n) asm volatile("s_waitcnt vmcnt(" #n ")" ::: "memory")
; #define PG8_WAIT_L(n) asm volatile("s_waitcnt lgkmcnt(" #n ")" ::: "memory")
; #define PG8_BAR __builtin_amdgcn_s_barrier()
; #define PG8_SCHED __builtin_amdgcn_sched_barrier(0)
; template <class Epi, class Sched, bool ALIGN_EPI = false, bool SP2 = false, bool A_TILED = false, bool B_TILED = false>
; __device__ __forceinline__ void gemm_phase(PG8_LAS unsigned char* lds, const Gemm g, const Sched& S, const Epi& E) {
;     ...
;             PG8_LDB(B0, 0, 0); PG8_LDB(B1, 0, 1); PG8_SCHED; PG8_LDA(At, 0, 0); PG8_STAGE(PG8_SA(1, 1), a1 + hstepA, voffA);
;             PG8_WAIT_V(8); PG8_WAIT_L(0); PG8_BAR; PG8_MMA(0, 0, At, B0); PG8_MMA(0, 1, At, B1); PG8_BAR; PG8_SCHED;
;             PG8_LDA(At, 0, 1); PG8_STAGE(PG8_SB(0, 0), b2, voffB); PG8_STAGE(PG8_SB(0, 1), b2 + hstepB, voffB); PG8_STAGE(PG8_SA(0, 0), a2, voffA);
;             PG8_WAIT_V(8); PG8_WAIT_L(0); PG8_BAR; PG8_MMA(1, 0, At, B0); PG8_MMA(1, 1, At, B1); PG8_BAR; PG8_SCHED;
.LBB0_553:
	ds_read_b128 v[158:161], v1
	ds_read_b128 v[162:165], v1 offset:1024
	ds_read_b128 v[166:169], v1 offset:2048
	ds_read_b128 v[170:173], v1 offset:3072
	ds_read_b128 v[174:177], v153
	ds_read_b128 v[178:181], v153 offset:1024
	ds_read_b128 v[182:185], v153 offset:2048
	ds_read_b128 v[190:193], v153 offset:3072
	s_add_u32 s38, s36, 0xfff00080
	s_addc_u32 s39, s37, -1
	s_cmp_eq_u32 s59, 12
	s_cselect_b32 s41, s5, s39
	s_cselect_b32 s40, s7, s38
	s_cselect_b32 s39, s23, s58
	s_cselect_b32 s38, s25, s27
	v_lshl_add_u64 v[140:141], s[36:37], 0, v[132:133]
	s_add_i32 m0, s19, 0xc000
	ds_read_b128 v[196:199], v154
	ds_read_b128 v[200:203], v154 offset:1024
	ds_read_b128 v[204:207], v154 offset:2048
	ds_read_b128 v[208:211], v154 offset:3072
	ds_read_b128 v[212:215], v154 offset:4096
	ds_read_b128 v[216:219], v154 offset:5120
	ds_read_b128 v[220:223], v154 offset:6144
	ds_read_b128 v[224:227], v154 offset:7168
	global_load_lds_dwordx4 v[140:141], off
	v_lshl_add_u64 v[140:141], s[36:37], 0, v[138:139]
	s_add_i32 m0, s19, 0xe000
	s_nop 0
	global_load_lds_dwordx4 v[140:141], off
	s_waitcnt vmcnt(8)
	s_waitcnt lgkmcnt(0)
	s_barrier
	v_mfma_f32_16x16x32_bf16 v[126:129], v[158:161], v[196:199], v[126:129]
	v_mfma_f32_16x16x32_bf16 v[122:125], v[166:169], v[196:199], v[122:125]
	v_mfma_f32_16x16x32_bf16 v[110:113], v[158:161], v[204:207], v[110:113]
	v_mfma_f32_16x16x32_bf16 v[106:109], v[166:169], v[204:207], v[106:109]
	v_mfma_f32_16x16x32_bf16 v[94:97], v[158:161], v[212:215], v[94:97]
	v_mfma_f32_16x16x32_bf16 v[90:93], v[166:169], v[212:215], v[90:93]
	v_mfma_f32_16x16x32_bf16 v[78:81], v[158:161], v[220:223], v[78:81]
	v_mfma_f32_16x16x32_bf16 v[74:77], v[166:169], v[220:223], v[74:77]
	v_mfma_f32_16x16x32_bf16 v[126:129], v[162:165], v[200:203], v[126:129]
	v_mfma_f32_16x16x32_bf16 v[122:125], v[170:173], v[200:203], v[122:125]
	v_mfma_f32_16x16x32_bf16 v[110:113], v[162:165], v[208:211], v[110:113]
	v_mfma_f32_16x16x32_bf16 v[106:109], v[170:173], v[208:211], v[106:109]
	v_mfma_f32_16x16x32_bf16 v[94:97], v[162:165], v[216:219], v[94:97]
	v_mfma_f32_16x16x32_bf16 v[90:93], v[170:173], v[216:219], v[90:93]
	v_mfma_f32_16x16x32_bf16 v[78:81], v[162:165], v[224:227], v[78:81]
	v_mfma_f32_16x16x32_bf16 v[74:77], v[170:173], v[224:227], v[74:77]
	v_mfma_f32_16x16x32_bf16 v[118:121], v[174:177], v[196:199], v[118:121]
	v_mfma_f32_16x16x32_bf16 v[114:117], v[182:185], v[196:199], v[114:117]
	v_mfma_f32_16x16x32_bf16 v[102:105], v[174:177], v[204:207], v[102:105]
	v_mfma_f32_16x16x32_bf16 v[98:101], v[182:185], v[204:207], v[98:101]
	v_mfma_f32_16x16x32_bf16 v[86:89], v[174:177], v[212:215], v[86:89]
	v_mfma_f32_16x16x32_bf16 v[82:85], v[182:185], v[212:215], v[82:85]
	v_mfma_f32_16x16x32_bf16 v[70:73], v[174:177], v[220:223], v[70:73]
	v_mfma_f32_16x16x32_bf16 v[66:69], v[182:185], v[220:223], v[66:69]
	v_mfma_f32_16x16x32_bf16 v[118:121], v[178:181], v[200:203], v[118:121]
	v_mfma_f32_16x16x32_bf16 v[114:117], v[190:193], v[200:203], v[114:117]
	v_mfma_f32_16x16x32_bf16 v[102:105], v[178:181], v[208:211], v[102:105]
	v_mfma_f32_16x16x32_bf16 v[98:101], v[190:193], v[208:211], v[98:101]
	v_mfma_f32_16x16x32_bf16 v[86:89], v[178:181], v[216:219], v[86:89]
	v_mfma_f32_16x16x32_bf16 v[82:85], v[190:193], v[216:219], v[82:85]
	v_mfma_f32_16x16x32_bf16 v[70:73], v[178:181], v[224:227], v[70:73]
	v_mfma_f32_16x16x32_bf16 v[66:69], v[190:193], v[224:227], v[66:69]
	s_barrier
	s_add_i32 s60, s8, s42
	v_lshl_add_u64 v[140:141], s[38:39], 0, v[134:135]
	s_mov_b32 m0, s60
	ds_read_b128 v[196:199], v154 offset:16384
	ds_read_b128 v[200:203], v154 offset:17408
	ds_read_b128 v[204:207], v154 offset:18432
	ds_read_b128 v[208:211], v154 offset:19456
	ds_read_b128 v[212:215], v154 offset:20480
	ds_read_b128 v[216:219], v154 offset:21504
	ds_read_b128 v[220:223], v154 offset:22528
	ds_read_b128 v[224:227], v154 offset:23552
	global_load_lds_dwordx4 v[140:141], off
	s_add_i32 m0, s60, 0x2000
	s_add_u32 s60, s38, 0x100000
	v_lshl_add_u64 v[186:187], s[38:39], 0, v[136:137]
	s_addc_u32 s61, s39, 0
	s_add_i32 s62, s55, s42
	global_load_lds_dwordx4 v[186:187], off
	v_lshl_add_u64 v[228:229], s[60:61], 0, v[134:135]
	s_mov_b32 m0, s62
	v_lshl_add_u64 v[230:231], s[40:41], 0, v[136:137]
	global_load_lds_dwordx4 v[228:229], off
	v_lshl_add_u64 v[228:229], s[60:61], 0, v[136:137]
	s_add_i32 m0, s62, 0x2000
	s_nop 0
	global_load_lds_dwordx4 v[228:229], off
	v_lshl_add_u64 v[228:229], s[40:41], 0, v[134:135]
	s_mov_b32 m0, s19
	s_nop 0
	global_load_lds_dwordx4 v[228:229], off
	s_mov_b32 m0, s43
	s_nop 0
	global_load_lds_dwordx4 v[230:231], off
	s_waitcnt vmcnt(8)
	s_waitcnt lgkmcnt(0)
	s_barrier
; #define PG8_STAGE(bufoff, gbase, voff) do { _Pragma("unroll") for (int _i = 0; _i < 2; ++_i) \
;         __builtin_amdgcn_global_load_lds((const unsigned*)((const char*)(gbase) + (voff)[_i]), (PG8_LAS unsigned*)(lds + (bufoff) + ldsw + _i * 8192), 16, 0, 0); } while (0)
; #define PG8_LDA(dst, b, h) do { _Pragma("unroll") for (int m = 0; m < 4; ++m) _Pragma("unroll") for (int k = 0; k < 2; ++k) dst[m][k] = *(const PG8_LAS bf16x8*)(lds + PG8_SA(b, h) + aoff + m * 2048 + k * 1024); } while (0)
; #define PG8_LDB(dst, b, h) do { _Pragma("unroll") for (int n = 0; n < 2; ++n) _Pragma("unroll") for (int k = 0; k < 2; ++k) dst[n][k] = *(const PG8_LAS bf16x8*)(lds + PG8_SB(b, h) + boff + n * 2048 + k * 1024); } while (0)
; #define PG8_MMA(ai, bj, At, Bt) do { __builtin_amdgcn_s_setprio(1); _Pragma("unroll") for (int m = 0; m < 4; ++m) _Pragma("unroll") for (int n = 0; n < 2; ++n) _Pragma("unroll") for (int k = 0; k < 2; ++k) \
;         acc[ai][bj][m][n] = __builtin_amdgcn_mfma_f32_16x16x32_bf16(Bt[n][k], At[m][k], acc[ai][bj][m][n], 0, 0, 0); __builtin_amdgcn_s_setprio(0); } while (0)
; #define PG8_WAIT_V(n) asm volatile("s_waitcnt vmcnt(" #n ")" ::: "memory")
; #define PG8_WAIT_L(n) asm volatile("s_waitcnt lgkmcnt(" #n ")" ::: "memory")
; #define PG8_BAR __builtin_amdgcn_s_barrier()
; #define PG8_SCHED __builtin_amdgcn_sched_barrier(0)
; template <class Epi, class Sched, bool ALIGN_EPI = false, bool SP2 = false, bool A_TILED = false, bool B_TILED = false>
; __device__ __forceinline__ void gemm_phase(PG8_LAS unsigned char* lds, const Gemm g, const Sched& S, const Epi& E) {
;     ...
;             PG8_WAIT_V(8); PG8_WAIT_L(0); PG8_BAR; PG8_MMA(1, 0, At, B0); PG8_MMA(1, 1, At, B1); PG8_BAR; PG8_SCHED;
;             PG8_LDB(B0, 1, 0); PG8_LDB(B1, 1, 1); PG8_SCHED; PG8_LDA(At, 1, 0); PG8_STAGE(PG8_SA(0, 1), a2 + hstepA, voffA);
;             PG8_WAIT_V(8); PG8_WAIT_L(0); PG8_BAR; PG8_MMA(0, 0, At, B0); PG8_MMA(0, 1, At, B1); PG8_BAR; PG8_SCHED;
	v_mfma_f32_16x16x32_bf16 v[62:65], v[158:161], v[196:199], v[62:65]
	v_mfma_f32_16x16x32_bf16 v[58:61], v[166:169], v[196:199], v[58:61]
	v_mfma_f32_16x16x32_bf16 v[46:49], v[158:161], v[204:207], v[46:49]
	v_mfma_f32_16x16x32_bf16 v[42:45], v[166:169], v[204:207], v[42:45]
	v_mfma_f32_16x16x32_bf16 v[30:33], v[158:161], v[212:215], v[30:33]
	v_mfma_f32_16x16x32_bf16 v[26:29], v[166:169], v[212:215], v[26:29]
	v_mfma_f32_16x16x32_bf16 v[14:17], v[158:161], v[220:223], v[14:17]
	v_mfma_f32_16x16x32_bf16 v[10:13], v[166:169], v[220:223], v[10:13]
	v_mfma_f32_16x16x32_bf16 v[62:65], v[162:165], v[200:203], v[62:65]
	v_mfma_f32_16x16x32_bf16 v[58:61], v[170:173], v[200:203], v[58:61]
	v_mfma_f32_16x16x32_bf16 v[46:49], v[162:165], v[208:211], v[46:49]
	v_mfma_f32_16x16x32_bf16 v[42:45], v[170:173], v[208:211], v[42:45]
	v_mfma_f32_16x16x32_bf16 v[30:33], v[162:165], v[216:219], v[30:33]
	v_mfma_f32_16x16x32_bf16 v[26:29], v[170:173], v[216:219], v[26:29]
	v_mfma_f32_16x16x32_bf16 v[14:17], v[162:165], v[224:227], v[14:17]
	v_mfma_f32_16x16x32_bf16 v[10:13], v[170:173], v[224:227], v[10:13]
	v_mfma_f32_16x16x32_bf16 v[54:57], v[174:177], v[196:199], v[54:57]
	v_mfma_f32_16x16x32_bf16 v[50:53], v[182:185], v[196:199], v[50:53]
	v_mfma_f32_16x16x32_bf16 v[38:41], v[174:177], v[204:207], v[38:41]
	v_mfma_f32_16x16x32_bf16 v[34:37], v[182:185], v[204:207], v[34:37]
	v_mfma_f32_16x16x32_bf16 v[22:25], v[174:177], v[212:215], v[22:25]
	v_mfma_f32_16x16x32_bf16 v[18:21], v[182:185], v[212:215], v[18:21]
	v_mfma_f32_16x16x32_bf16 v[6:9], v[174:177], v[220:223], v[6:9]
	v_mfma_f32_16x16x32_bf16 v[2:5], v[182:185], v[220:223], v[2:5]
	v_mfma_f32_16x16x32_bf16 v[54:57], v[178:181], v[200:203], v[54:57]
	v_mfma_f32_16x16x32_bf16 v[50:53], v[190:193], v[200:203], v[50:53]
	v_mfma_f32_16x16x32_bf16 v[38:41], v[178:181], v[208:211], v[38:41]
	v_mfma_f32_16x16x32_bf16 v[34:37], v[190:193], v[208:211], v[34:37]
	v_mfma_f32_16x16x32_bf16 v[22:25], v[178:181], v[216:219], v[22:25]
	v_mfma_f32_16x16x32_bf16 v[18:21], v[190:193], v[216:219], v[18:21]
	v_mfma_f32_16x16x32_bf16 v[6:9], v[178:181], v[224:227], v[6:9]
	v_mfma_f32_16x16x32_bf16 v[2:5], v[190:193], v[224:227], v[2:5]
	s_barrier
	s_add_i32 s60, 0, 0x18000
	v_add_u32_e32 v142, s60, v145
	s_add_i32 s61, 0, 0x1c000
	ds_read_b128 v[158:161], v142
	ds_read_b128 v[162:165], v142 offset:1024
	ds_read_b128 v[166:169], v142 offset:2048
	ds_read_b128 v[170:173], v142 offset:3072
	v_add_u32_e32 v142, s61, v145
	ds_read_b128 v[174:177], v142
	ds_read_b128 v[178:181], v142 offset:1024
	ds_read_b128 v[182:185], v142 offset:2048
	ds_read_b128 v[190:193], v142 offset:3072
	s_add_u32 s40, s40, 0x100000
	s_addc_u32 s41, s41, 0
	s_mov_b32 m0, s44
	v_lshl_add_u64 v[232:233], s[40:41], 0, v[134:135]
	ds_read_b128 v[196:199], v154 offset:32768
	ds_read_b128 v[200:203], v154 offset:33792
	ds_read_b128 v[204:207], v154 offset:34816
	ds_read_b128 v[208:211], v154 offset:35840
	ds_read_b128 v[212:215], v154 offset:36864
	ds_read_b128 v[216:219], v154 offset:37888
	ds_read_b128 v[220:223], v154 offset:38912
	ds_read_b128 v[224:227], v154 offset:39936
	global_load_lds_dwordx4 v[232:233], off
	v_lshl_add_u64 v[232:233], s[40:41], 0, v[136:137]
	s_mov_b32 m0, s45
	s_nop 0
	global_load_lds_dwordx4 v[232:233], off
	s_waitcnt vmcnt(8)
	s_waitcnt lgkmcnt(0)
	s_barrier
	v_mfma_f32_16x16x32_bf16 v[126:129], v[158:161], v[196:199], v[126:129]
	v_mfma_f32_16x16x32_bf16 v[122:125], v[166:169], v[196:199], v[122:125]
	v_mfma_f32_16x16x32_bf16 v[110:113], v[158:161], v[204:207], v[110:113]
	v_mfma_f32_16x16x32_bf16 v[106:109], v[166:169], v[204:207], v[106:109]
	v_mfma_f32_16x16x32_bf16 v[94:97], v[158:161], v[212:215], v[94:97]
	v_mfma_f32_16x16x32_bf16 v[90:93], v[166:169], v[212:215], v[90:93]
	v_mfma_f32_16x16x32_bf16 v[78:81], v[158:161], v[220:223], v[78:81]
	v_mfma_f32_16x16x32_bf16 v[74:77], v[166:169], v[220:223], v[74:77]
	v_mfma_f32_16x16x32_bf16 v[126:129], v[162:165], v[200:203], v[126:129]
	v_mfma_f32_16x16x32_bf16 v[122:125], v[170:173], v[200:203], v[122:125]
	v_mfma_f32_16x16x32_bf16 v[110:113], v[162:165], v[208:211], v[110:113]
	v_mfma_f32_16x16x32_bf16 v[106:109], v[170:173], v[208:211], v[106:109]
	v_mfma_f32_16x16x32_bf16 v[94:97], v[162:165], v[216:219], v[94:97]
	v_mfma_f32_16x16x32_bf16 v[90:93], v[170:173], v[216:219], v[90:93]
	v_mfma_f32_16x16x32_bf16 v[78:81], v[162:165], v[224:227], v[78:81]
	v_mfma_f32_16x16x32_bf16 v[74:77], v[170:173], v[224:227], v[74:77]
	v_mfma_f32_16x16x32_bf16 v[118:121], v[174:177], v[196:199], v[118:121]
	v_mfma_f32_16x16x32_bf16 v[114:117], v[182:185], v[196:199], v[114:117]
	v_mfma_f32_16x16x32_bf16 v[102:105], v[174:177], v[204:207], v[102:105]
	v_mfma_f32_16x16x32_bf16 v[98:101], v[182:185], v[204:207], v[98:101]
	v_mfma_f32_16x16x32_bf16 v[86:89], v[174:177], v[212:215], v[86:89]
	v_mfma_f32_16x16x32_bf16 v[82:85], v[182:185], v[212:215], v[82:85]
	v_mfma_f32_16x16x32_bf16 v[70:73], v[174:177], v[220:223], v[70:73]
	v_mfma_f32_16x16x32_bf16 v[66:69], v[182:185], v[220:223], v[66:69]
	v_mfma_f32_16x16x32_bf16 v[118:121], v[178:181], v[200:203], v[118:121]
	v_mfma_f32_16x16x32_bf16 v[114:117], v[190:193], v[200:203], v[114:117]
	v_mfma_f32_16x16x32_bf16 v[102:105], v[178:181], v[208:211], v[102:105]
	v_mfma_f32_16x16x32_bf16 v[98:101], v[190:193], v[208:211], v[98:101]
	v_mfma_f32_16x16x32_bf16 v[86:89], v[178:181], v[216:219], v[86:89]
	v_mfma_f32_16x16x32_bf16 v[82:85], v[190:193], v[216:219], v[82:85]
	v_mfma_f32_16x16x32_bf16 v[70:73], v[178:181], v[224:227], v[70:73]
	v_mfma_f32_16x16x32_bf16 v[66:69], v[190:193], v[224:227], v[66:69]
	s_barrier
; #define PG8_STAGE(bufoff, gbase, voff) do { _Pragma("unroll") for (int _i = 0; _i < 2; ++_i) \
;         __builtin_amdgcn_global_load_lds((const unsigned*)((const char*)(gbase) + (voff)[_i]), (PG8_LAS unsigned*)(lds + (bufoff) + ldsw + _i * 8192), 16, 0, 0); } while (0)
; #define PG8_LDA(dst, b, h) do { _Pragma("unroll") for (int m = 0; m < 4; ++m) _Pragma("unroll") for (int k = 0; k < 2; ++k) dst[m][k] = *(const PG8_LAS bf16x8*)(lds + PG8_SA(b, h) + aoff + m * 2048 + k * 1024); } while (0)
; #define PG8_MMA(ai, bj, At, Bt) do { __builtin_amdgcn_s_setprio(1); _Pragma("unroll") for (int m = 0; m < 4; ++m) _Pragma("unroll") for (int n = 0; n < 2; ++n) _Pragma("unroll") for (int k = 0; k < 2; ++k) \
;         acc[ai][bj][m][n] = __builtin_amdgcn_mfma_f32_16x16x32_bf16(Bt[n][k], At[m][k], acc[ai][bj][m][n], 0, 0, 0); __builtin_amdgcn_s_setprio(0); } while (0)
; #define PG8_WAIT_V(n) asm volatile("s_waitcnt vmcnt(" #n ")" ::: "memory")
; #define PG8_WAIT_L(n) asm volatile("s_waitcnt lgkmcnt(" #n ")" ::: "memory")
; #define PG8_BAR __builtin_amdgcn_s_barrier()
; #define PG8_SCHED __builtin_amdgcn_sched_barrier(0)
; template <class Epi, class Sched, bool ALIGN_EPI = false, bool SP2 = false, bool A_TILED = false, bool B_TILED = false>
; __device__ __forceinline__ void gemm_phase(PG8_LAS unsigned char* lds, const Gemm g, const Sched& S, const Epi& E) {
;     ...
;         for (int t = 0; t < nt; t += 2) {
;             const bool last = (t == nt - 2);
;             const char* a1 = cA + (size_t)(t + 1) * kstepA;
;             const char* a2 = last ? nA : cA + (size_t)(t + 2) * kstepA; const char* b2 = last ? nB : cB + (size_t)(t + 2) * kstepB;
;             const char* a3 = a2 + kstepA; const char* b3 = b2 + kstepB;
;             if (last && has_next) S.a_ready(nxt);
;     ...
;             PG8_LDA(At, 1, 1); PG8_STAGE(PG8_SB(1, 0), b3, voffB); PG8_STAGE(PG8_SB(1, 1), b3 + hstepB, voffB); PG8_STAGE(PG8_SA(1, 0), a3, voffA);
;             PG8_WAIT_V(8); PG8_WAIT_L(0); PG8_BAR; PG8_MMA(1, 0, At, B0); PG8_MMA(1, 1, At, B1); PG8_BAR; PG8_SCHED;
	s_add_i32 s40, s60, s42
	v_lshl_add_u64 v[140:141], v[140:141], 0, s[12:13]
	s_mov_b32 m0, s40
	ds_read_b128 v[196:199], v154 offset:49152
	ds_read_b128 v[200:203], v154 offset:50176
	ds_read_b128 v[204:207], v154 offset:51200
	ds_read_b128 v[208:211], v154 offset:52224
	ds_read_b128 v[212:215], v154 offset:53248
	ds_read_b128 v[216:219], v154 offset:54272
	ds_read_b128 v[220:223], v154 offset:55296
	ds_read_b128 v[224:227], v154 offset:56320
	global_load_lds_dwordx4 v[140:141], off
	s_add_i32 m0, s40, 0x2000
	s_add_u32 s38, s38, 0x100080
	v_lshl_add_u64 v[140:141], v[186:187], 0, s[12:13]
	s_addc_u32 s39, s39, 0
	s_add_i32 s40, s61, s42
	global_load_lds_dwordx4 v[140:141], off
	v_lshl_add_u64 v[140:141], s[38:39], 0, v[134:135]
	s_mov_b32 m0, s40
	s_nop 0
	global_load_lds_dwordx4 v[140:141], off
	v_lshl_add_u64 v[140:141], s[38:39], 0, v[136:137]
	s_add_i32 m0, s40, 0x2000
	s_nop 0
	global_load_lds_dwordx4 v[140:141], off
	v_lshl_add_u64 v[140:141], v[228:229], 0, s[12:13]
	s_mov_b32 m0, s53
	s_nop 0
	global_load_lds_dwordx4 v[140:141], off
	v_lshl_add_u64 v[140:141], v[230:231], 0, s[12:13]
	s_mov_b32 m0, s54
	s_nop 0
	global_load_lds_dwordx4 v[140:141], off
	s_waitcnt vmcnt(8)
	s_waitcnt lgkmcnt(0)
	s_barrier
	v_mfma_f32_16x16x32_bf16 v[62:65], v[158:161], v[196:199], v[62:65]
	v_mfma_f32_16x16x32_bf16 v[58:61], v[166:169], v[196:199], v[58:61]
	v_mfma_f32_16x16x32_bf16 v[46:49], v[158:161], v[204:207], v[46:49]
	v_mfma_f32_16x16x32_bf16 v[42:45], v[166:169], v[204:207], v[42:45]
	v_mfma_f32_16x16x32_bf16 v[30:33], v[158:161], v[212:215], v[30:33]
	v_mfma_f32_16x16x32_bf16 v[26:29], v[166:169], v[212:215], v[26:29]
	v_mfma_f32_16x16x32_bf16 v[14:17], v[158:161], v[220:223], v[14:17]
	v_mfma_f32_16x16x32_bf16 v[10:13], v[166:169], v[220:223], v[10:13]
	v_mfma_f32_16x16x32_bf16 v[62:65], v[162:165], v[200:203], v[62:65]
	v_mfma_f32_16x16x32_bf16 v[58:61], v[170:173], v[200:203], v[58:61]
	v_mfma_f32_16x16x32_bf16 v[46:49], v[162:165], v[208:211], v[46:49]
	v_mfma_f32_16x16x32_bf16 v[42:45], v[170:173], v[208:211], v[42:45]
	v_mfma_f32_16x16x32_bf16 v[30:33], v[162:165], v[216:219], v[30:33]
	v_mfma_f32_16x16x32_bf16 v[26:29], v[170:173], v[216:219], v[26:29]
	v_mfma_f32_16x16x32_bf16 v[14:17], v[162:165], v[224:227], v[14:17]
	v_mfma_f32_16x16x32_bf16 v[10:13], v[170:173], v[224:227], v[10:13]
	v_mfma_f32_16x16x32_bf16 v[54:57], v[174:177], v[196:199], v[54:57]
	v_mfma_f32_16x16x32_bf16 v[50:53], v[182:185], v[196:199], v[50:53]
	v_mfma_f32_16x16x32_bf16 v[38:41], v[174:177], v[204:207], v[38:41]
	v_mfma_f32_16x16x32_bf16 v[34:37], v[182:185], v[204:207], v[34:37]
	v_mfma_f32_16x16x32_bf16 v[22:25], v[174:177], v[212:215], v[22:25]
	v_mfma_f32_16x16x32_bf16 v[18:21], v[182:185], v[212:215], v[18:21]
	v_mfma_f32_16x16x32_bf16 v[6:9], v[174:177], v[220:223], v[6:9]
	v_mfma_f32_16x16x32_bf16 v[2:5], v[182:185], v[220:223], v[2:5]
	v_mfma_f32_16x16x32_bf16 v[54:57], v[178:181], v[200:203], v[54:57]
	v_mfma_f32_16x16x32_bf16 v[50:53], v[190:193], v[200:203], v[50:53]
	v_mfma_f32_16x16x32_bf16 v[38:41], v[178:181], v[208:211], v[38:41]
	v_mfma_f32_16x16x32_bf16 v[34:37], v[190:193], v[208:211], v[34:37]
	v_mfma_f32_16x16x32_bf16 v[22:25], v[178:181], v[216:219], v[22:25]
	v_mfma_f32_16x16x32_bf16 v[18:21], v[190:193], v[216:219], v[18:21]
	v_mfma_f32_16x16x32_bf16 v[6:9], v[178:181], v[224:227], v[6:9]
	v_mfma_f32_16x16x32_bf16 v[2:5], v[190:193], v[224:227], v[2:5]
	s_barrier
	s_add_i32 s59, s59, 2
	s_add_u32 s36, s36, 0x100
	s_addc_u32 s37, s37, 0
	s_add_u32 s27, s27, 0x100
	s_addc_u32 s58, s58, 0
	s_cmp_gt_u32 s59, 13
	s_cbranch_scc0 .LBB0_553
	s_and_b64 vcc, exec, s[20:21]
	s_cbranch_vccz .LBB0_556
	s_barrier

; #define PG8_STAGE(bufoff, gbase, voff) do { _Pragma("unroll") for (int _i = 0; _i < 2; ++_i) \
;         __builtin_amdgcn_global_load_lds((const unsigned*)((const char*)(gbase) + (voff)[_i]), (PG8_LAS unsigned*)(lds + (bufoff) + ldsw + _i * 8192), 16, 0, 0); } while (0)
; #define PG8_LDA(dst, b, h) do { _Pragma("unroll") for (int m = 0; m < 4; ++m) _Pragma("unroll") for (int k = 0; k < 2; ++k) dst[m][k] = *(const PG8_LAS bf16x8*)(lds + PG8_SA(b, h) + aoff + m * 2048 + k * 1024); } while (0)
; #define PG8_LDB(dst, b, h) do { _Pragma("unroll") for (int n = 0; n < 2; ++n) _Pragma("unroll") for (int k = 0; k < 2; ++k) dst[n][k] = *(const PG8_LAS bf16x8*)(lds + PG8_SB(b, h) + boff + n * 2048 + k * 1024); } while (0)
; #define PG8_MMA(ai, bj, At, Bt) do { __builtin_amdgcn_s_setprio(1); _Pragma("unroll") for (int m = 0; m < 4; ++m) _Pragma("unroll") for (int n = 0; n < 2; ++n) _Pragma("unroll") for (int k = 0; k < 2; ++k) \
;         acc[ai][bj][m][n] = __builtin_amdgcn_mfma_f32_16x16x32_bf16(Bt[n][k], At[m][k], acc[ai][bj][m][n], 0, 0, 0); __builtin_amdgcn_s_setprio(0); } while (0)
; #define PG8_WAIT_V(n) asm volatile("s_waitcnt vmcnt(" #n ")" ::: "memory")
; #define PG8_WAIT_L(n) asm volatile("s_waitcnt lgkmcnt(" #n ")" ::: "memory")
; #define PG8_BAR __builtin_amdgcn_s_barrier()
; template <class Epi, class Sched, bool ALIGN_EPI = false, bool SP2 = false, bool A_TILED = false, bool B_TILED = false>
; __device__ __forceinline__ void gemm_phase(PG8_LAS unsigned char* lds, const Gemm g, const Sched& S, const Epi& E) {
;     ...
;         for (int t = 0; t < nt; t += 2) {
;             const bool last = (t == nt - 2);
;             const char* a1 = cA + (size_t)(t + 1) * kstepA;
;             const char* a2 = last ? nA : cA + (size_t)(t + 2) * kstepA; const char* b2 = last ? nB : cB + (size_t)(t + 2) * kstepB;
;             const char* a3 = a2 + kstepA; const char* b3 = b2 + kstepB;
;             if (last && has_next) S.a_ready(nxt);
;             if constexpr (SP2) {
;             PG8_LDB(B0, 0, 0); PG8_LDB(B1, 0, 1); PG8_SCHED; PG8_LDA(At, 0, 0); PG8_STAGE(PG8_SA(1, 1), a1 + hstepA, voffA);
;             PG8_WAIT_V(8); PG8_WAIT_L(0); PG8_BAR; PG8_MMA(0, 0, At, B0); PG8_MMA(0, 1, At, B1); PG8_BAR; PG8_SCHED;
;             PG8_LDA(At, 0, 1); PG8_STAGE(PG8_SB(0, 0), b2, voffB); PG8_STAGE(PG8_SB(0, 1), b2 + hstepB, voffB); PG8_STAGE(PG8_SA(0, 0), a2, voffA);
.LBB0_726:
	ds_read_b128 v[126:129], v207
	ds_read_b128 v[130:133], v207 offset:1024
	ds_read_b128 v[134:137], v207 offset:2048
	ds_read_b128 v[138:141], v207 offset:3072
	ds_read_b128 v[150:153], v208
	ds_read_b128 v[154:157], v208 offset:1024
	ds_read_b128 v[158:161], v208 offset:2048
	ds_read_b128 v[162:165], v208 offset:3072
	s_add_u32 s10, s8, 0xfff00080
	s_addc_u32 s11, s9, -1
	s_cmp_eq_u32 s19, 60
	s_cselect_b32 s13, s7, s11
	s_cselect_b32 s12, s14, s10
	s_cselect_b32 s11, s15, s18
	s_cselect_b32 s10, s16, s17
	v_lshl_add_u64 v[236:237], s[8:9], 0, v[180:181]
	s_add_i32 m0, s93, 0xc000
	ds_read_b128 v[166:169], v209
	ds_read_b128 v[184:187], v209 offset:1024
	ds_read_b128 v[190:193], v209 offset:2048
	ds_read_b128 v[216:219], v209 offset:3072
	ds_read_b128 v[220:223], v209 offset:4096
	ds_read_b128 v[224:227], v209 offset:5120
	ds_read_b128 v[228:231], v209 offset:6144
	ds_read_b128 v[232:235], v209 offset:7168
	global_load_lds_dwordx4 v[236:237], off
	v_lshl_add_u64 v[236:237], s[8:9], 0, v[182:183]
	s_add_i32 m0, s93, 0xe000
	s_nop 0
	global_load_lds_dwordx4 v[236:237], off
	s_waitcnt vmcnt(8)
	s_waitcnt lgkmcnt(0)
	s_barrier
	v_mfma_f32_16x16x32_bf16 v[146:149], v[126:129], v[166:169], v[146:149]
	v_mfma_f32_16x16x32_bf16 v[62:65], v[134:137], v[166:169], v[62:65]
	v_mfma_f32_16x16x32_bf16 v[122:125], v[126:129], v[190:193], v[122:125]
	v_mfma_f32_16x16x32_bf16 v[54:57], v[134:137], v[190:193], v[54:57]
	v_mfma_f32_16x16x32_bf16 v[106:109], v[126:129], v[220:223], v[106:109]
	v_mfma_f32_16x16x32_bf16 v[42:45], v[134:137], v[220:223], v[42:45]
	v_mfma_f32_16x16x32_bf16 v[110:113], v[126:129], v[228:231], v[110:113]
	v_mfma_f32_16x16x32_bf16 v[46:49], v[134:137], v[228:231], v[46:49]
	v_mfma_f32_16x16x32_bf16 v[146:149], v[130:133], v[184:187], v[146:149]
	v_mfma_f32_16x16x32_bf16 v[62:65], v[138:141], v[184:187], v[62:65]
	v_mfma_f32_16x16x32_bf16 v[122:125], v[130:133], v[216:219], v[122:125]
	v_mfma_f32_16x16x32_bf16 v[54:57], v[138:141], v[216:219], v[54:57]
	v_mfma_f32_16x16x32_bf16 v[106:109], v[130:133], v[224:227], v[106:109]
	v_mfma_f32_16x16x32_bf16 v[42:45], v[138:141], v[224:227], v[42:45]
	v_mfma_f32_16x16x32_bf16 v[110:113], v[130:133], v[232:235], v[110:113]
	v_mfma_f32_16x16x32_bf16 v[46:49], v[138:141], v[232:235], v[46:49]
	v_mfma_f32_16x16x32_bf16 v[118:121], v[150:153], v[166:169], v[118:121]
	v_mfma_f32_16x16x32_bf16 v[66:69], v[158:161], v[166:169], v[66:69]
	v_mfma_f32_16x16x32_bf16 v[142:145], v[150:153], v[190:193], v[142:145]
	v_mfma_f32_16x16x32_bf16 v[58:61], v[158:161], v[190:193], v[58:61]
	v_mfma_f32_16x16x32_bf16 v[114:117], v[150:153], v[220:223], v[114:117]
	v_mfma_f32_16x16x32_bf16 v[50:53], v[158:161], v[220:223], v[50:53]
	v_mfma_f32_16x16x32_bf16 v[102:105], v[150:153], v[228:231], v[102:105]
	v_mfma_f32_16x16x32_bf16 v[38:41], v[158:161], v[228:231], v[38:41]
	v_mfma_f32_16x16x32_bf16 v[118:121], v[154:157], v[184:187], v[118:121]
	v_mfma_f32_16x16x32_bf16 v[66:69], v[162:165], v[184:187], v[66:69]
	v_mfma_f32_16x16x32_bf16 v[142:145], v[154:157], v[216:219], v[142:145]
	v_mfma_f32_16x16x32_bf16 v[58:61], v[162:165], v[216:219], v[58:61]
	v_mfma_f32_16x16x32_bf16 v[114:117], v[154:157], v[224:227], v[114:117]
	v_mfma_f32_16x16x32_bf16 v[50:53], v[162:165], v[224:227], v[50:53]
	v_mfma_f32_16x16x32_bf16 v[102:105], v[154:157], v[232:235], v[102:105]
	v_mfma_f32_16x16x32_bf16 v[38:41], v[162:165], v[232:235], v[38:41]
	s_barrier
	s_add_i32 s20, s24, s92
	v_lshl_add_u64 v[236:237], s[10:11], 0, v[172:173]
	s_mov_b32 m0, s20
	ds_read_b128 v[166:169], v209 offset:16384
	ds_read_b128 v[184:187], v209 offset:17408
	ds_read_b128 v[190:193], v209 offset:18432
	ds_read_b128 v[216:219], v209 offset:19456
	ds_read_b128 v[220:223], v209 offset:20480
	ds_read_b128 v[224:227], v209 offset:21504
	ds_read_b128 v[228:231], v209 offset:22528
	ds_read_b128 v[232:235], v209 offset:23552
	global_load_lds_dwordx4 v[236:237], off
	s_add_i32 m0, s20, 0x2000
	s_add_u32 s20, s10, 0x100000
	v_lshl_add_u64 v[238:239], s[10:11], 0, v[176:177]
	s_addc_u32 s21, s11, 0
	s_add_i32 s22, s25, s92
	global_load_lds_dwordx4 v[238:239], off
	v_lshl_add_u64 v[240:241], s[20:21], 0, v[172:173]
	s_mov_b32 m0, s22
	v_lshl_add_u64 v[242:243], s[12:13], 0, v[174:175]
	global_load_lds_dwordx4 v[240:241], off
	v_lshl_add_u64 v[240:241], s[20:21], 0, v[176:177]
	s_add_i32 m0, s22, 0x2000
	s_nop 0
	global_load_lds_dwordx4 v[240:241], off
	v_lshl_add_u64 v[240:241], s[12:13], 0, v[170:171]
	s_mov_b32 m0, s93
	s_nop 0
	global_load_lds_dwordx4 v[240:241], off
	s_mov_b32 m0, s94
	s_nop 0
	global_load_lds_dwordx4 v[242:243], off
	s_waitcnt vmcnt(8)
	s_waitcnt lgkmcnt(0)
	s_barrier
; #define PG8_STAGE(bufoff, gbase, voff) do { _Pragma("unroll") for (int _i = 0; _i < 2; ++_i) \
;         __builtin_amdgcn_global_load_lds((const unsigned*)((const char*)(gbase) + (voff)[_i]), (PG8_LAS unsigned*)(lds + (bufoff) + ldsw + _i * 8192), 16, 0, 0); } while (0)
; #define PG8_LDA(dst, b, h) do { _Pragma("unroll") for (int m = 0; m < 4; ++m) _Pragma("unroll") for (int k = 0; k < 2; ++k) dst[m][k] = *(const PG8_LAS bf16x8*)(lds + PG8_SA(b, h) + aoff + m * 2048 + k * 1024); } while (0)
; #define PG8_LDB(dst, b, h) do { _Pragma("unroll") for (int n = 0; n < 2; ++n) _Pragma("unroll") for (int k = 0; k < 2; ++k) dst[n][k] = *(const PG8_LAS bf16x8*)(lds + PG8_SB(b, h) + boff + n * 2048 + k * 1024); } while (0)
; #define PG8_MMA(ai, bj, At, Bt) do { __builtin_amdgcn_s_setprio(1); _Pragma("unroll") for (int m = 0; m < 4; ++m) _Pragma("unroll") for (int n = 0; n < 2; ++n) _Pragma("unroll") for (int k = 0; k < 2; ++k) \
;         acc[ai][bj][m][n] = __builtin_amdgcn_mfma_f32_16x16x32_bf16(Bt[n][k], At[m][k], acc[ai][bj][m][n], 0, 0, 0); __builtin_amdgcn_s_setprio(0); } while (0)
; #define PG8_WAIT_V(n) asm volatile("s_waitcnt vmcnt(" #n ")" ::: "memory")
; #define PG8_WAIT_L(n) asm volatile("s_waitcnt lgkmcnt(" #n ")" ::: "memory")
; #define PG8_BAR __builtin_amdgcn_s_barrier()
; #define PG8_SCHED __builtin_amdgcn_sched_barrier(0)
; template <class Epi, class Sched, bool ALIGN_EPI = false, bool SP2 = false, bool A_TILED = false, bool B_TILED = false>
; __device__ __forceinline__ void gemm_phase(PG8_LAS unsigned char* lds, const Gemm g, const Sched& S, const Epi& E) {
;     ...
;             PG8_WAIT_V(8); PG8_WAIT_L(0); PG8_BAR; PG8_MMA(1, 0, At, B0); PG8_MMA(1, 1, At, B1); PG8_BAR; PG8_SCHED;
;             PG8_LDB(B0, 1, 0); PG8_LDB(B1, 1, 1); PG8_SCHED; PG8_LDA(At, 1, 0); PG8_STAGE(PG8_SA(0, 1), a2 + hstepA, voffA);
;             PG8_WAIT_V(8); PG8_WAIT_L(0); PG8_BAR; PG8_MMA(0, 0, At, B0); PG8_MMA(0, 1, At, B1); PG8_BAR; PG8_SCHED;
	v_mfma_f32_16x16x32_bf16 v[94:97], v[126:129], v[166:169], v[94:97]
	v_mfma_f32_16x16x32_bf16 v[30:33], v[134:137], v[166:169], v[30:33]
	v_mfma_f32_16x16x32_bf16 v[86:89], v[126:129], v[190:193], v[86:89]
	v_mfma_f32_16x16x32_bf16 v[22:25], v[134:137], v[190:193], v[22:25]
	v_mfma_f32_16x16x32_bf16 v[74:77], v[126:129], v[220:223], v[74:77]
	v_mfma_f32_16x16x32_bf16 v[10:13], v[134:137], v[220:223], v[10:13]
	v_mfma_f32_16x16x32_bf16 v[78:81], v[126:129], v[228:231], v[78:81]
	v_mfma_f32_16x16x32_bf16 v[14:17], v[134:137], v[228:231], v[14:17]
	v_mfma_f32_16x16x32_bf16 v[94:97], v[130:133], v[184:187], v[94:97]
	v_mfma_f32_16x16x32_bf16 v[30:33], v[138:141], v[184:187], v[30:33]
	v_mfma_f32_16x16x32_bf16 v[86:89], v[130:133], v[216:219], v[86:89]
	v_mfma_f32_16x16x32_bf16 v[22:25], v[138:141], v[216:219], v[22:25]
	v_mfma_f32_16x16x32_bf16 v[74:77], v[130:133], v[224:227], v[74:77]
	v_mfma_f32_16x16x32_bf16 v[10:13], v[138:141], v[224:227], v[10:13]
	v_mfma_f32_16x16x32_bf16 v[78:81], v[130:133], v[232:235], v[78:81]
	v_mfma_f32_16x16x32_bf16 v[14:17], v[138:141], v[232:235], v[14:17]
	v_mfma_f32_16x16x32_bf16 v[98:101], v[150:153], v[166:169], v[98:101]
	v_mfma_f32_16x16x32_bf16 v[34:37], v[158:161], v[166:169], v[34:37]
	v_mfma_f32_16x16x32_bf16 v[90:93], v[150:153], v[190:193], v[90:93]
	v_mfma_f32_16x16x32_bf16 v[26:29], v[158:161], v[190:193], v[26:29]
	v_mfma_f32_16x16x32_bf16 v[82:85], v[150:153], v[220:223], v[82:85]
	v_mfma_f32_16x16x32_bf16 v[18:21], v[158:161], v[220:223], v[18:21]
	v_mfma_f32_16x16x32_bf16 v[70:73], v[150:153], v[228:231], v[70:73]
	v_mfma_f32_16x16x32_bf16 v[6:9], v[158:161], v[228:231], v[6:9]
	v_mfma_f32_16x16x32_bf16 v[98:101], v[154:157], v[184:187], v[98:101]
	v_mfma_f32_16x16x32_bf16 v[34:37], v[162:165], v[184:187], v[34:37]
	v_mfma_f32_16x16x32_bf16 v[90:93], v[154:157], v[216:219], v[90:93]
	v_mfma_f32_16x16x32_bf16 v[26:29], v[162:165], v[216:219], v[26:29]
	v_mfma_f32_16x16x32_bf16 v[82:85], v[154:157], v[224:227], v[82:85]
	v_mfma_f32_16x16x32_bf16 v[18:21], v[162:165], v[224:227], v[18:21]
	v_mfma_f32_16x16x32_bf16 v[70:73], v[154:157], v[232:235], v[70:73]
	v_mfma_f32_16x16x32_bf16 v[6:9], v[162:165], v[232:235], v[6:9]
	s_barrier
	s_add_i32 s20, 0, 0x18000
	s_add_i32 s21, 0, 0x1c000
	v_add_u32_e32 v138, s20, v203
	v_add_u32_e32 v162, s21, v203
	ds_read_b128 v[126:129], v138
	ds_read_b128 v[130:133], v138 offset:1024
	ds_read_b128 v[134:137], v138 offset:2048
	ds_read_b128 v[138:141], v138 offset:3072
	ds_read_b128 v[150:153], v162
	ds_read_b128 v[154:157], v162 offset:1024
	ds_read_b128 v[158:161], v162 offset:2048
	ds_read_b128 v[162:165], v162 offset:3072
	s_add_u32 s12, s12, 0x100000
	s_addc_u32 s13, s13, 0
	s_mov_b32 m0, s95
	v_lshl_add_u64 v[244:245], s[12:13], 0, v[170:171]
	ds_read_b128 v[166:169], v209 offset:32768
	ds_read_b128 v[184:187], v209 offset:33792
	ds_read_b128 v[190:193], v209 offset:34816
	ds_read_b128 v[216:219], v209 offset:35840
	ds_read_b128 v[220:223], v209 offset:36864
	ds_read_b128 v[224:227], v209 offset:37888
	ds_read_b128 v[228:231], v209 offset:38912
	ds_read_b128 v[232:235], v209 offset:39936
	global_load_lds_dwordx4 v[244:245], off
	v_lshl_add_u64 v[244:245], s[12:13], 0, v[174:175]
	s_mov_b32 m0, s96
	s_nop 0
	global_load_lds_dwordx4 v[244:245], off
	s_waitcnt vmcnt(8)
	s_waitcnt lgkmcnt(0)
	s_barrier
	v_mfma_f32_16x16x32_bf16 v[146:149], v[126:129], v[166:169], v[146:149]
	v_mfma_f32_16x16x32_bf16 v[62:65], v[134:137], v[166:169], v[62:65]
	v_mfma_f32_16x16x32_bf16 v[122:125], v[126:129], v[190:193], v[122:125]
	v_mfma_f32_16x16x32_bf16 v[54:57], v[134:137], v[190:193], v[54:57]
	v_mfma_f32_16x16x32_bf16 v[106:109], v[126:129], v[220:223], v[106:109]
	v_mfma_f32_16x16x32_bf16 v[42:45], v[134:137], v[220:223], v[42:45]
	v_mfma_f32_16x16x32_bf16 v[110:113], v[126:129], v[228:231], v[110:113]
	v_mfma_f32_16x16x32_bf16 v[46:49], v[134:137], v[228:231], v[46:49]
	v_mfma_f32_16x16x32_bf16 v[146:149], v[130:133], v[184:187], v[146:149]
	v_mfma_f32_16x16x32_bf16 v[62:65], v[138:141], v[184:187], v[62:65]
	v_mfma_f32_16x16x32_bf16 v[122:125], v[130:133], v[216:219], v[122:125]
	v_mfma_f32_16x16x32_bf16 v[54:57], v[138:141], v[216:219], v[54:57]
	v_mfma_f32_16x16x32_bf16 v[106:109], v[130:133], v[224:227], v[106:109]
	v_mfma_f32_16x16x32_bf16 v[42:45], v[138:141], v[224:227], v[42:45]
	v_mfma_f32_16x16x32_bf16 v[110:113], v[130:133], v[232:235], v[110:113]
	v_mfma_f32_16x16x32_bf16 v[46:49], v[138:141], v[232:235], v[46:49]
	v_mfma_f32_16x16x32_bf16 v[118:121], v[150:153], v[166:169], v[118:121]
	v_mfma_f32_16x16x32_bf16 v[66:69], v[158:161], v[166:169], v[66:69]
	v_mfma_f32_16x16x32_bf16 v[142:145], v[150:153], v[190:193], v[142:145]
	v_mfma_f32_16x16x32_bf16 v[58:61], v[158:161], v[190:193], v[58:61]
	v_mfma_f32_16x16x32_bf16 v[114:117], v[150:153], v[220:223], v[114:117]
	v_mfma_f32_16x16x32_bf16 v[50:53], v[158:161], v[220:223], v[50:53]
	v_mfma_f32_16x16x32_bf16 v[102:105], v[150:153], v[228:231], v[102:105]
	v_mfma_f32_16x16x32_bf16 v[38:41], v[158:161], v[228:231], v[38:41]
	v_mfma_f32_16x16x32_bf16 v[118:121], v[154:157], v[184:187], v[118:121]
	v_mfma_f32_16x16x32_bf16 v[66:69], v[162:165], v[184:187], v[66:69]
	v_mfma_f32_16x16x32_bf16 v[142:145], v[154:157], v[216:219], v[142:145]
	v_mfma_f32_16x16x32_bf16 v[58:61], v[162:165], v[216:219], v[58:61]
	v_mfma_f32_16x16x32_bf16 v[114:117], v[154:157], v[224:227], v[114:117]
	v_mfma_f32_16x16x32_bf16 v[50:53], v[162:165], v[224:227], v[50:53]
	v_mfma_f32_16x16x32_bf16 v[102:105], v[154:157], v[232:235], v[102:105]
	v_mfma_f32_16x16x32_bf16 v[38:41], v[162:165], v[232:235], v[38:41]
	s_barrier
; #define PG8_STAGE(bufoff, gbase, voff) do { _Pragma("unroll") for (int _i = 0; _i < 2; ++_i) \
;         __builtin_amdgcn_global_load_lds((const unsigned*)((const char*)(gbase) + (voff)[_i]), (PG8_LAS unsigned*)(lds + (bufoff) + ldsw + _i * 8192), 16, 0, 0); } while (0)
; #define PG8_LDA(dst, b, h) do { _Pragma("unroll") for (int m = 0; m < 4; ++m) _Pragma("unroll") for (int k = 0; k < 2; ++k) dst[m][k] = *(const PG8_LAS bf16x8*)(lds + PG8_SA(b, h) + aoff + m * 2048 + k * 1024); } while (0)
; #define PG8_MMA(ai, bj, At, Bt) do { __builtin_amdgcn_s_setprio(1); _Pragma("unroll") for (int m = 0; m < 4; ++m) _Pragma("unroll") for (int n = 0; n < 2; ++n) _Pragma("unroll") for (int k = 0; k < 2; ++k) \
;         acc[ai][bj][m][n] = __builtin_amdgcn_mfma_f32_16x16x32_bf16(Bt[n][k], At[m][k], acc[ai][bj][m][n], 0, 0, 0); __builtin_amdgcn_s_setprio(0); } while (0)
; #define PG8_WAIT_V(n) asm volatile("s_waitcnt vmcnt(" #n ")" ::: "memory")
; #define PG8_WAIT_L(n) asm volatile("s_waitcnt lgkmcnt(" #n ")" ::: "memory")
; #define PG8_BAR __builtin_amdgcn_s_barrier()
; #define PG8_SCHED __builtin_amdgcn_sched_barrier(0)
; template <class Epi, class Sched, bool ALIGN_EPI = false, bool SP2 = false, bool A_TILED = false, bool B_TILED = false>
; __device__ __forceinline__ void gemm_phase(PG8_LAS unsigned char* lds, const Gemm g, const Sched& S, const Epi& E) {
;     ...
;             PG8_LDA(At, 1, 1); PG8_STAGE(PG8_SB(1, 0), b3, voffB); PG8_STAGE(PG8_SB(1, 1), b3 + hstepB, voffB); PG8_STAGE(PG8_SA(1, 0), a3, voffA);
;             PG8_WAIT_V(8); PG8_WAIT_L(0); PG8_BAR; PG8_MMA(1, 0, At, B0); PG8_MMA(1, 1, At, B1); PG8_BAR; PG8_SCHED;
;     ...
;         if constexpr (ALIGN_EPI) { if (wr == 0) PG8_BAR; }
	s_add_i32 s12, s20, s92
	v_lshl_add_u64 v[236:237], v[236:237], 0, s[46:47]
	s_mov_b32 m0, s12
	ds_read_b128 v[166:169], v209 offset:49152
	ds_read_b128 v[184:187], v209 offset:50176
	ds_read_b128 v[190:193], v209 offset:51200
	ds_read_b128 v[216:219], v209 offset:52224
	ds_read_b128 v[220:223], v209 offset:53248
	ds_read_b128 v[224:227], v209 offset:54272
	ds_read_b128 v[228:231], v209 offset:55296
	ds_read_b128 v[232:235], v209 offset:56320
	global_load_lds_dwordx4 v[236:237], off
	s_add_i32 m0, s12, 0x2000
	s_add_u32 s10, s10, 0x100080
	v_lshl_add_u64 v[236:237], v[238:239], 0, s[46:47]
	s_addc_u32 s11, s11, 0
	s_add_i32 s12, s21, s92
	global_load_lds_dwordx4 v[236:237], off
	v_lshl_add_u64 v[236:237], s[10:11], 0, v[172:173]
	s_mov_b32 m0, s12
	s_nop 0
	global_load_lds_dwordx4 v[236:237], off
	v_lshl_add_u64 v[236:237], s[10:11], 0, v[176:177]
	s_add_i32 m0, s12, 0x2000
	s_nop 0
	global_load_lds_dwordx4 v[236:237], off
	v_lshl_add_u64 v[236:237], v[240:241], 0, s[46:47]
	s_mov_b32 m0, s54
	s_nop 0
	global_load_lds_dwordx4 v[236:237], off
	v_lshl_add_u64 v[236:237], v[242:243], 0, s[46:47]
	s_mov_b32 m0, s55
	s_nop 0
	global_load_lds_dwordx4 v[236:237], off
	s_waitcnt vmcnt(8)
	s_waitcnt lgkmcnt(0)
	s_barrier
	v_mfma_f32_16x16x32_bf16 v[94:97], v[126:129], v[166:169], v[94:97]
	v_mfma_f32_16x16x32_bf16 v[30:33], v[134:137], v[166:169], v[30:33]
	v_mfma_f32_16x16x32_bf16 v[86:89], v[126:129], v[190:193], v[86:89]
	v_mfma_f32_16x16x32_bf16 v[22:25], v[134:137], v[190:193], v[22:25]
	v_mfma_f32_16x16x32_bf16 v[74:77], v[126:129], v[220:223], v[74:77]
	v_mfma_f32_16x16x32_bf16 v[10:13], v[134:137], v[220:223], v[10:13]
	v_mfma_f32_16x16x32_bf16 v[78:81], v[126:129], v[228:231], v[78:81]
	v_mfma_f32_16x16x32_bf16 v[14:17], v[134:137], v[228:231], v[14:17]
	v_mfma_f32_16x16x32_bf16 v[94:97], v[130:133], v[184:187], v[94:97]
	v_mfma_f32_16x16x32_bf16 v[30:33], v[138:141], v[184:187], v[30:33]
	v_mfma_f32_16x16x32_bf16 v[86:89], v[130:133], v[216:219], v[86:89]
	v_mfma_f32_16x16x32_bf16 v[22:25], v[138:141], v[216:219], v[22:25]
	v_mfma_f32_16x16x32_bf16 v[74:77], v[130:133], v[224:227], v[74:77]
	v_mfma_f32_16x16x32_bf16 v[10:13], v[138:141], v[224:227], v[10:13]
	v_mfma_f32_16x16x32_bf16 v[78:81], v[130:133], v[232:235], v[78:81]
	v_mfma_f32_16x16x32_bf16 v[14:17], v[138:141], v[232:235], v[14:17]
	v_mfma_f32_16x16x32_bf16 v[98:101], v[150:153], v[166:169], v[98:101]
	v_mfma_f32_16x16x32_bf16 v[34:37], v[158:161], v[166:169], v[34:37]
	v_mfma_f32_16x16x32_bf16 v[90:93], v[150:153], v[190:193], v[90:93]
	v_mfma_f32_16x16x32_bf16 v[26:29], v[158:161], v[190:193], v[26:29]
	v_mfma_f32_16x16x32_bf16 v[82:85], v[150:153], v[220:223], v[82:85]
	v_mfma_f32_16x16x32_bf16 v[18:21], v[158:161], v[220:223], v[18:21]
	v_mfma_f32_16x16x32_bf16 v[70:73], v[150:153], v[228:231], v[70:73]
	v_mfma_f32_16x16x32_bf16 v[6:9], v[158:161], v[228:231], v[6:9]
	v_mfma_f32_16x16x32_bf16 v[98:101], v[154:157], v[184:187], v[98:101]
	v_mfma_f32_16x16x32_bf16 v[34:37], v[162:165], v[184:187], v[34:37]
	v_mfma_f32_16x16x32_bf16 v[90:93], v[154:157], v[216:219], v[90:93]
	v_mfma_f32_16x16x32_bf16 v[26:29], v[162:165], v[216:219], v[26:29]
	v_mfma_f32_16x16x32_bf16 v[82:85], v[154:157], v[224:227], v[82:85]
	v_mfma_f32_16x16x32_bf16 v[18:21], v[162:165], v[224:227], v[18:21]
	v_mfma_f32_16x16x32_bf16 v[70:73], v[154:157], v[232:235], v[70:73]
	v_mfma_f32_16x16x32_bf16 v[6:9], v[162:165], v[232:235], v[6:9]
	s_barrier
	s_add_i32 s19, s19, 2
	s_add_u32 s8, s8, 0x100
	s_addc_u32 s9, s9, 0
	s_add_u32 s17, s17, 0x100
	s_addc_u32 s18, s18, 0
	s_cmp_gt_u32 s19, 61
	s_cbranch_scc0 .LBB0_726
	s_and_b64 vcc, exec, s[56:57]
	s_cbranch_vccz .LBB0_729
	s_barrier

; #define PG8_STAGE(bufoff, gbase, voff) do { _Pragma("unroll") for (int _i = 0; _i < 2; ++_i) \
;         __builtin_amdgcn_global_load_lds((const unsigned*)((const char*)(gbase) + (voff)[_i]), (PG8_LAS unsigned*)(lds + (bufoff) + ldsw + _i * 8192), 16, 0, 0); } while (0)
; #define PG8_LDA(dst, b, h) do { _Pragma("unroll") for (int m = 0; m < 4; ++m) _Pragma("unroll") for (int k = 0; k < 2; ++k) dst[m][k] = *(const PG8_LAS bf16x8*)(lds + PG8_SA(b, h) + aoff + m * 2048 + k * 1024); } while (0)
; #define PG8_LDB(dst, b, h) do { _Pragma("unroll") for (int n = 0; n < 2; ++n) _Pragma("unroll") for (int k = 0; k < 2; ++k) dst[n][k] = *(const PG8_LAS bf16x8*)(lds + PG8_SB(b, h) + boff + n * 2048 + k * 1024); } while (0)
; #define PG8_MMA(ai, bj, At, Bt) do { __builtin_amdgcn_s_setprio(1); _Pragma("unroll") for (int m = 0; m < 4; ++m) _Pragma("unroll") for (int n = 0; n < 2; ++n) _Pragma("unroll") for (int k = 0; k < 2; ++k) \
;         acc[ai][bj][m][n] = __builtin_amdgcn_mfma_f32_16x16x32_bf16(Bt[n][k], At[m][k], acc[ai][bj][m][n], 0, 0, 0); __builtin_amdgcn_s_setprio(0); } while (0)
; #define PG8_WAIT_V(n) asm volatile("s_waitcnt vmcnt(" #n ")" ::: "memory")
; #define PG8_WAIT_L(n) asm volatile("s_waitcnt lgkmcnt(" #n ")" ::: "memory")
; #define PG8_BAR __builtin_amdgcn_s_barrier()
; template <class Epi, class Sched, bool ALIGN_EPI = false, bool SP2 = false, bool A_TILED = false, bool B_TILED = false>
; __device__ __forceinline__ void gemm_phase(PG8_LAS unsigned char* lds, const Gemm g, const Sched& S, const Epi& E) {
;     ...
;         for (int t = 0; t < nt; t += 2) {
;             const bool last = (t == nt - 2);
;             const char* a1 = cA + (size_t)(t + 1) * kstepA;
;             const char* a2 = last ? nA : cA + (size_t)(t + 2) * kstepA; const char* b2 = last ? nB : cB + (size_t)(t + 2) * kstepB;
;             const char* a3 = a2 + kstepA; const char* b3 = b2 + kstepB;
;             if (last && has_next) S.a_ready(nxt);
;             if constexpr (SP2) {
;             PG8_LDB(B0, 0, 0); PG8_LDB(B1, 0, 1); PG8_SCHED; PG8_LDA(At, 0, 0); PG8_STAGE(PG8_SA(1, 1), a1 + hstepA, voffA);
;             PG8_WAIT_V(8); PG8_WAIT_L(0); PG8_BAR; PG8_MMA(0, 0, At, B0); PG8_MMA(0, 1, At, B1); PG8_BAR; PG8_SCHED;
;             PG8_LDA(At, 0, 1); PG8_STAGE(PG8_SB(0, 0), b2, voffB); PG8_STAGE(PG8_SB(0, 1), b2 + hstepB, voffB); PG8_STAGE(PG8_SA(0, 0), a2, voffA);
.LBB0_905:
	ds_read_b128 v[140:143], v1
	ds_read_b128 v[144:147], v1 offset:1024
	ds_read_b128 v[148:151], v1 offset:2048
	ds_read_b128 v[152:155], v1 offset:3072
	ds_read_b128 v[156:159], v137
	ds_read_b128 v[160:163], v137 offset:1024
	ds_read_b128 v[164:167], v137 offset:2048
	ds_read_b128 v[178:181], v137 offset:3072
	s_add_u32 s30, s26, 0xfff00080
	s_addc_u32 s31, s27, -1
	s_cmp_eq_u32 s44, 4
	s_cselect_b32 s35, s13, s31
	s_cselect_b32 s34, s17, s30
	s_cselect_b32 s31, s15, s43
	s_cselect_b32 s30, s25, s42
	v_lshl_add_u64 v[168:169], s[26:27], 0, v[132:133]
	s_add_i32 m0, s29, 0xc000
	ds_read_b128 v[182:185], v138
	ds_read_b128 v[190:193], v138 offset:1024
	ds_read_b128 v[196:199], v138 offset:2048
	ds_read_b128 v[200:203], v138 offset:3072
	ds_read_b128 v[204:207], v138 offset:4096
	ds_read_b128 v[208:211], v138 offset:5120
	ds_read_b128 v[212:215], v138 offset:6144
	ds_read_b128 v[216:219], v138 offset:7168
	global_load_lds_dwordx4 v[168:169], off
	v_lshl_add_u64 v[168:169], s[26:27], 0, v[134:135]
	s_add_i32 m0, s29, 0xe000
	s_nop 0
	global_load_lds_dwordx4 v[168:169], off
	s_waitcnt vmcnt(8)
	s_waitcnt lgkmcnt(0)
	s_barrier
	v_mfma_f32_16x16x32_bf16 v[126:129], v[140:143], v[182:185], v[126:129]
	v_mfma_f32_16x16x32_bf16 v[122:125], v[148:151], v[182:185], v[122:125]
	v_mfma_f32_16x16x32_bf16 v[118:121], v[140:143], v[196:199], v[118:121]
	v_mfma_f32_16x16x32_bf16 v[114:117], v[148:151], v[196:199], v[114:117]
	v_mfma_f32_16x16x32_bf16 v[110:113], v[140:143], v[204:207], v[110:113]
	v_mfma_f32_16x16x32_bf16 v[102:105], v[148:151], v[204:207], v[102:105]
	v_mfma_f32_16x16x32_bf16 v[94:97], v[140:143], v[212:215], v[94:97]
	v_mfma_f32_16x16x32_bf16 v[86:89], v[148:151], v[212:215], v[86:89]
	v_mfma_f32_16x16x32_bf16 v[126:129], v[144:147], v[190:193], v[126:129]
	v_mfma_f32_16x16x32_bf16 v[122:125], v[152:155], v[190:193], v[122:125]
	v_mfma_f32_16x16x32_bf16 v[118:121], v[144:147], v[200:203], v[118:121]
	v_mfma_f32_16x16x32_bf16 v[114:117], v[152:155], v[200:203], v[114:117]
	v_mfma_f32_16x16x32_bf16 v[110:113], v[144:147], v[208:211], v[110:113]
	v_mfma_f32_16x16x32_bf16 v[102:105], v[152:155], v[208:211], v[102:105]
	v_mfma_f32_16x16x32_bf16 v[94:97], v[144:147], v[216:219], v[94:97]
	v_mfma_f32_16x16x32_bf16 v[86:89], v[152:155], v[216:219], v[86:89]
	v_mfma_f32_16x16x32_bf16 v[106:109], v[156:159], v[182:185], v[106:109]
	v_mfma_f32_16x16x32_bf16 v[98:101], v[164:167], v[182:185], v[98:101]
	v_mfma_f32_16x16x32_bf16 v[90:93], v[156:159], v[196:199], v[90:93]
	v_mfma_f32_16x16x32_bf16 v[82:85], v[164:167], v[196:199], v[82:85]
	v_mfma_f32_16x16x32_bf16 v[78:81], v[156:159], v[204:207], v[78:81]
	v_mfma_f32_16x16x32_bf16 v[74:77], v[164:167], v[204:207], v[74:77]
	v_mfma_f32_16x16x32_bf16 v[70:73], v[156:159], v[212:215], v[70:73]
	v_mfma_f32_16x16x32_bf16 v[66:69], v[164:167], v[212:215], v[66:69]
	v_mfma_f32_16x16x32_bf16 v[106:109], v[160:163], v[190:193], v[106:109]
	v_mfma_f32_16x16x32_bf16 v[98:101], v[178:181], v[190:193], v[98:101]
	v_mfma_f32_16x16x32_bf16 v[90:93], v[160:163], v[200:203], v[90:93]
	v_mfma_f32_16x16x32_bf16 v[82:85], v[178:181], v[200:203], v[82:85]
	v_mfma_f32_16x16x32_bf16 v[78:81], v[160:163], v[208:211], v[78:81]
	v_mfma_f32_16x16x32_bf16 v[74:77], v[178:181], v[208:211], v[74:77]
	v_mfma_f32_16x16x32_bf16 v[70:73], v[160:163], v[216:219], v[70:73]
	v_mfma_f32_16x16x32_bf16 v[66:69], v[178:181], v[216:219], v[66:69]
	s_barrier
	s_add_i32 s45, s4, s28
	v_lshl_add_u64 v[168:169], s[30:31], 0, v[172:173]
	s_mov_b32 m0, s45
	ds_read_b128 v[182:185], v138 offset:16384
	ds_read_b128 v[190:193], v138 offset:17408
	ds_read_b128 v[196:199], v138 offset:18432
	ds_read_b128 v[200:203], v138 offset:19456
	ds_read_b128 v[204:207], v138 offset:20480
	ds_read_b128 v[208:211], v138 offset:21504
	ds_read_b128 v[212:215], v138 offset:22528
	ds_read_b128 v[216:219], v138 offset:23552
	global_load_lds_dwordx4 v[168:169], off
	s_add_i32 m0, s45, 0x2000
	s_add_u32 s46, s30, 0x100000
	v_lshl_add_u64 v[186:187], s[30:31], 0, v[176:177]
	s_addc_u32 s47, s31, 0
	s_add_i32 s45, s40, s28
	global_load_lds_dwordx4 v[186:187], off
	v_lshl_add_u64 v[220:221], s[46:47], 0, v[172:173]
	s_mov_b32 m0, s45
	v_lshl_add_u64 v[222:223], s[34:35], 0, v[174:175]
	global_load_lds_dwordx4 v[220:221], off
	v_lshl_add_u64 v[220:221], s[46:47], 0, v[176:177]
	s_add_i32 m0, s45, 0x2000
	s_nop 0
	global_load_lds_dwordx4 v[220:221], off
	v_lshl_add_u64 v[220:221], s[34:35], 0, v[170:171]
	s_mov_b32 m0, s29
	s_nop 0
	global_load_lds_dwordx4 v[220:221], off
	s_mov_b32 m0, s33
	s_nop 0
	global_load_lds_dwordx4 v[222:223], off
	s_waitcnt vmcnt(8)
	s_waitcnt lgkmcnt(0)
	s_barrier
; #define PG8_STAGE(bufoff, gbase, voff) do { _Pragma("unroll") for (int _i = 0; _i < 2; ++_i) \
;         __builtin_amdgcn_global_load_lds((const unsigned*)((const char*)(gbase) + (voff)[_i]), (PG8_LAS unsigned*)(lds + (bufoff) + ldsw + _i * 8192), 16, 0, 0); } while (0)
; #define PG8_LDA(dst, b, h) do { _Pragma("unroll") for (int m = 0; m < 4; ++m) _Pragma("unroll") for (int k = 0; k < 2; ++k) dst[m][k] = *(const PG8_LAS bf16x8*)(lds + PG8_SA(b, h) + aoff + m * 2048 + k * 1024); } while (0)
; #define PG8_LDB(dst, b, h) do { _Pragma("unroll") for (int n = 0; n < 2; ++n) _Pragma("unroll") for (int k = 0; k < 2; ++k) dst[n][k] = *(const PG8_LAS bf16x8*)(lds + PG8_SB(b, h) + boff + n * 2048 + k * 1024); } while (0)
; #define PG8_MMA(ai, bj, At, Bt) do { __builtin_amdgcn_s_setprio(1); _Pragma("unroll") for (int m = 0; m < 4; ++m) _Pragma("unroll") for (int n = 0; n < 2; ++n) _Pragma("unroll") for (int k = 0; k < 2; ++k) \
;         acc[ai][bj][m][n] = __builtin_amdgcn_mfma_f32_16x16x32_bf16(Bt[n][k], At[m][k], acc[ai][bj][m][n], 0, 0, 0); __builtin_amdgcn_s_setprio(0); } while (0)
; #define PG8_WAIT_V(n) asm volatile("s_waitcnt vmcnt(" #n ")" ::: "memory")
; #define PG8_WAIT_L(n) asm volatile("s_waitcnt lgkmcnt(" #n ")" ::: "memory")
; #define PG8_BAR __builtin_amdgcn_s_barrier()
; #define PG8_SCHED __builtin_amdgcn_sched_barrier(0)
; template <class Epi, class Sched, bool ALIGN_EPI = false, bool SP2 = false, bool A_TILED = false, bool B_TILED = false>
; __device__ __forceinline__ void gemm_phase(PG8_LAS unsigned char* lds, const Gemm g, const Sched& S, const Epi& E) {
;     ...
;             PG8_WAIT_V(8); PG8_WAIT_L(0); PG8_BAR; PG8_MMA(1, 0, At, B0); PG8_MMA(1, 1, At, B1); PG8_BAR; PG8_SCHED;
;             PG8_LDB(B0, 1, 0); PG8_LDB(B1, 1, 1); PG8_SCHED; PG8_LDA(At, 1, 0); PG8_STAGE(PG8_SA(0, 1), a2 + hstepA, voffA);
;             PG8_WAIT_V(8); PG8_WAIT_L(0); PG8_BAR; PG8_MMA(0, 0, At, B0); PG8_MMA(0, 1, At, B1); PG8_BAR; PG8_SCHED;
	v_mfma_f32_16x16x32_bf16 v[62:65], v[140:143], v[182:185], v[62:65]
	v_mfma_f32_16x16x32_bf16 v[58:61], v[148:151], v[182:185], v[58:61]
	v_mfma_f32_16x16x32_bf16 v[54:57], v[140:143], v[196:199], v[54:57]
	v_mfma_f32_16x16x32_bf16 v[50:53], v[148:151], v[196:199], v[50:53]
	v_mfma_f32_16x16x32_bf16 v[46:49], v[140:143], v[204:207], v[46:49]
	v_mfma_f32_16x16x32_bf16 v[38:41], v[148:151], v[204:207], v[38:41]
	v_mfma_f32_16x16x32_bf16 v[30:33], v[140:143], v[212:215], v[30:33]
	v_mfma_f32_16x16x32_bf16 v[22:25], v[148:151], v[212:215], v[22:25]
	v_mfma_f32_16x16x32_bf16 v[62:65], v[144:147], v[190:193], v[62:65]
	v_mfma_f32_16x16x32_bf16 v[58:61], v[152:155], v[190:193], v[58:61]
	v_mfma_f32_16x16x32_bf16 v[54:57], v[144:147], v[200:203], v[54:57]
	v_mfma_f32_16x16x32_bf16 v[50:53], v[152:155], v[200:203], v[50:53]
	v_mfma_f32_16x16x32_bf16 v[46:49], v[144:147], v[208:211], v[46:49]
	v_mfma_f32_16x16x32_bf16 v[38:41], v[152:155], v[208:211], v[38:41]
	v_mfma_f32_16x16x32_bf16 v[30:33], v[144:147], v[216:219], v[30:33]
	v_mfma_f32_16x16x32_bf16 v[22:25], v[152:155], v[216:219], v[22:25]
	v_mfma_f32_16x16x32_bf16 v[42:45], v[156:159], v[182:185], v[42:45]
	v_mfma_f32_16x16x32_bf16 v[34:37], v[164:167], v[182:185], v[34:37]
	v_mfma_f32_16x16x32_bf16 v[26:29], v[156:159], v[196:199], v[26:29]
	v_mfma_f32_16x16x32_bf16 v[18:21], v[164:167], v[196:199], v[18:21]
	v_mfma_f32_16x16x32_bf16 v[14:17], v[156:159], v[204:207], v[14:17]
	v_mfma_f32_16x16x32_bf16 v[10:13], v[164:167], v[204:207], v[10:13]
	v_mfma_f32_16x16x32_bf16 v[6:9], v[156:159], v[212:215], v[6:9]
	v_mfma_f32_16x16x32_bf16 v[2:5], v[164:167], v[212:215], v[2:5]
	v_mfma_f32_16x16x32_bf16 v[42:45], v[160:163], v[190:193], v[42:45]
	v_mfma_f32_16x16x32_bf16 v[34:37], v[178:181], v[190:193], v[34:37]
	v_mfma_f32_16x16x32_bf16 v[26:29], v[160:163], v[200:203], v[26:29]
	v_mfma_f32_16x16x32_bf16 v[18:21], v[178:181], v[200:203], v[18:21]
	v_mfma_f32_16x16x32_bf16 v[14:17], v[160:163], v[208:211], v[14:17]
	v_mfma_f32_16x16x32_bf16 v[10:13], v[178:181], v[208:211], v[10:13]
	v_mfma_f32_16x16x32_bf16 v[6:9], v[160:163], v[216:219], v[6:9]
	v_mfma_f32_16x16x32_bf16 v[2:5], v[178:181], v[216:219], v[2:5]
	s_barrier
	s_add_i32 s45, 0, 0x18000
	v_add_u32_e32 v139, s45, v136
	s_add_i32 s46, 0, 0x1c000
	ds_read_b128 v[140:143], v139
	ds_read_b128 v[144:147], v139 offset:1024
	ds_read_b128 v[148:151], v139 offset:2048
	ds_read_b128 v[152:155], v139 offset:3072
	v_add_u32_e32 v139, s46, v136
	ds_read_b128 v[156:159], v139
	ds_read_b128 v[160:163], v139 offset:1024
	ds_read_b128 v[164:167], v139 offset:2048
	ds_read_b128 v[178:181], v139 offset:3072
	s_add_u32 s34, s34, 0x100000
	s_addc_u32 s35, s35, 0
	s_mov_b32 m0, s36
	v_lshl_add_u64 v[224:225], s[34:35], 0, v[170:171]
	ds_read_b128 v[182:185], v138 offset:32768
	ds_read_b128 v[190:193], v138 offset:33792
	ds_read_b128 v[196:199], v138 offset:34816
	ds_read_b128 v[200:203], v138 offset:35840
	ds_read_b128 v[204:207], v138 offset:36864
	ds_read_b128 v[208:211], v138 offset:37888
	ds_read_b128 v[212:215], v138 offset:38912
	ds_read_b128 v[216:219], v138 offset:39936
	global_load_lds_dwordx4 v[224:225], off
	v_lshl_add_u64 v[224:225], s[34:35], 0, v[174:175]
	s_mov_b32 m0, s37
	s_nop 0
	global_load_lds_dwordx4 v[224:225], off
	s_waitcnt vmcnt(8)
	s_waitcnt lgkmcnt(0)
	s_barrier
	v_mfma_f32_16x16x32_bf16 v[126:129], v[140:143], v[182:185], v[126:129]
	v_mfma_f32_16x16x32_bf16 v[122:125], v[148:151], v[182:185], v[122:125]
	v_mfma_f32_16x16x32_bf16 v[118:121], v[140:143], v[196:199], v[118:121]
	v_mfma_f32_16x16x32_bf16 v[114:117], v[148:151], v[196:199], v[114:117]
	v_mfma_f32_16x16x32_bf16 v[110:113], v[140:143], v[204:207], v[110:113]
	v_mfma_f32_16x16x32_bf16 v[102:105], v[148:151], v[204:207], v[102:105]
	v_mfma_f32_16x16x32_bf16 v[94:97], v[140:143], v[212:215], v[94:97]
	v_mfma_f32_16x16x32_bf16 v[86:89], v[148:151], v[212:215], v[86:89]
	v_mfma_f32_16x16x32_bf16 v[126:129], v[144:147], v[190:193], v[126:129]
	v_mfma_f32_16x16x32_bf16 v[122:125], v[152:155], v[190:193], v[122:125]
	v_mfma_f32_16x16x32_bf16 v[118:121], v[144:147], v[200:203], v[118:121]
	v_mfma_f32_16x16x32_bf16 v[114:117], v[152:155], v[200:203], v[114:117]
	v_mfma_f32_16x16x32_bf16 v[110:113], v[144:147], v[208:211], v[110:113]
	v_mfma_f32_16x16x32_bf16 v[102:105], v[152:155], v[208:211], v[102:105]
	v_mfma_f32_16x16x32_bf16 v[94:97], v[144:147], v[216:219], v[94:97]
	v_mfma_f32_16x16x32_bf16 v[86:89], v[152:155], v[216:219], v[86:89]
	v_mfma_f32_16x16x32_bf16 v[106:109], v[156:159], v[182:185], v[106:109]
	v_mfma_f32_16x16x32_bf16 v[98:101], v[164:167], v[182:185], v[98:101]
	v_mfma_f32_16x16x32_bf16 v[90:93], v[156:159], v[196:199], v[90:93]
	v_mfma_f32_16x16x32_bf16 v[82:85], v[164:167], v[196:199], v[82:85]
	v_mfma_f32_16x16x32_bf16 v[78:81], v[156:159], v[204:207], v[78:81]
	v_mfma_f32_16x16x32_bf16 v[74:77], v[164:167], v[204:207], v[74:77]
	v_mfma_f32_16x16x32_bf16 v[70:73], v[156:159], v[212:215], v[70:73]
	v_mfma_f32_16x16x32_bf16 v[66:69], v[164:167], v[212:215], v[66:69]
	v_mfma_f32_16x16x32_bf16 v[106:109], v[160:163], v[190:193], v[106:109]
	v_mfma_f32_16x16x32_bf16 v[98:101], v[178:181], v[190:193], v[98:101]
	v_mfma_f32_16x16x32_bf16 v[90:93], v[160:163], v[200:203], v[90:93]
	v_mfma_f32_16x16x32_bf16 v[82:85], v[178:181], v[200:203], v[82:85]
	v_mfma_f32_16x16x32_bf16 v[78:81], v[160:163], v[208:211], v[78:81]
	v_mfma_f32_16x16x32_bf16 v[74:77], v[178:181], v[208:211], v[74:77]
	v_mfma_f32_16x16x32_bf16 v[70:73], v[160:163], v[216:219], v[70:73]
	v_mfma_f32_16x16x32_bf16 v[66:69], v[178:181], v[216:219], v[66:69]
	s_barrier
; #define PG8_STAGE(bufoff, gbase, voff) do { _Pragma("unroll") for (int _i = 0; _i < 2; ++_i) \
;         __builtin_amdgcn_global_load_lds((const unsigned*)((const char*)(gbase) + (voff)[_i]), (PG8_LAS unsigned*)(lds + (bufoff) + ldsw + _i * 8192), 16, 0, 0); } while (0)
; #define PG8_LDA(dst, b, h) do { _Pragma("unroll") for (int m = 0; m < 4; ++m) _Pragma("unroll") for (int k = 0; k < 2; ++k) dst[m][k] = *(const PG8_LAS bf16x8*)(lds + PG8_SA(b, h) + aoff + m * 2048 + k * 1024); } while (0)
; #define PG8_MMA(ai, bj, At, Bt) do { __builtin_amdgcn_s_setprio(1); _Pragma("unroll") for (int m = 0; m < 4; ++m) _Pragma("unroll") for (int n = 0; n < 2; ++n) _Pragma("unroll") for (int k = 0; k < 2; ++k) \
;         acc[ai][bj][m][n] = __builtin_amdgcn_mfma_f32_16x16x32_bf16(Bt[n][k], At[m][k], acc[ai][bj][m][n], 0, 0, 0); __builtin_amdgcn_s_setprio(0); } while (0)
; #define PG8_WAIT_V(n) asm volatile("s_waitcnt vmcnt(" #n ")" ::: "memory")
; #define PG8_WAIT_L(n) asm volatile("s_waitcnt lgkmcnt(" #n ")" ::: "memory")
; #define PG8_BAR __builtin_amdgcn_s_barrier()
; #define PG8_SCHED __builtin_amdgcn_sched_barrier(0)
; template <class Epi, class Sched, bool ALIGN_EPI = false, bool SP2 = false, bool A_TILED = false, bool B_TILED = false>
; __device__ __forceinline__ void gemm_phase(PG8_LAS unsigned char* lds, const Gemm g, const Sched& S, const Epi& E) {
;     ...
;             PG8_LDA(At, 1, 1); PG8_STAGE(PG8_SB(1, 0), b3, voffB); PG8_STAGE(PG8_SB(1, 1), b3 + hstepB, voffB); PG8_STAGE(PG8_SA(1, 0), a3, voffA);
;             PG8_WAIT_V(8); PG8_WAIT_L(0); PG8_BAR; PG8_MMA(1, 0, At, B0); PG8_MMA(1, 1, At, B1); PG8_BAR; PG8_SCHED;
;     ...
;         if constexpr (ALIGN_EPI) { if (wr == 0) PG8_BAR; }
	s_add_i32 s34, s45, s28
	v_lshl_add_u64 v[168:169], v[168:169], 0, s[8:9]
	s_mov_b32 m0, s34
	ds_read_b128 v[182:185], v138 offset:49152
	ds_read_b128 v[190:193], v138 offset:50176
	ds_read_b128 v[196:199], v138 offset:51200
	ds_read_b128 v[200:203], v138 offset:52224
	ds_read_b128 v[204:207], v138 offset:53248
	ds_read_b128 v[208:211], v138 offset:54272
	ds_read_b128 v[212:215], v138 offset:55296
	ds_read_b128 v[216:219], v138 offset:56320
	global_load_lds_dwordx4 v[168:169], off
	s_add_i32 m0, s34, 0x2000
	s_add_u32 s30, s30, 0x100080
	v_lshl_add_u64 v[168:169], v[186:187], 0, s[8:9]
	s_addc_u32 s31, s31, 0
	s_add_i32 s34, s46, s28
	global_load_lds_dwordx4 v[168:169], off
	v_lshl_add_u64 v[168:169], s[30:31], 0, v[172:173]
	s_mov_b32 m0, s34
	s_nop 0
	global_load_lds_dwordx4 v[168:169], off
	v_lshl_add_u64 v[168:169], s[30:31], 0, v[176:177]
	s_add_i32 m0, s34, 0x2000
	s_nop 0
	global_load_lds_dwordx4 v[168:169], off
	v_lshl_add_u64 v[168:169], v[220:221], 0, s[8:9]
	s_mov_b32 m0, s38
	s_nop 0
	global_load_lds_dwordx4 v[168:169], off
	v_lshl_add_u64 v[168:169], v[222:223], 0, s[8:9]
	s_mov_b32 m0, s39
	s_nop 0
	global_load_lds_dwordx4 v[168:169], off
	s_waitcnt vmcnt(8)
	s_waitcnt lgkmcnt(0)
	s_barrier
	v_mfma_f32_16x16x32_bf16 v[62:65], v[140:143], v[182:185], v[62:65]
	v_mfma_f32_16x16x32_bf16 v[58:61], v[148:151], v[182:185], v[58:61]
	v_mfma_f32_16x16x32_bf16 v[54:57], v[140:143], v[196:199], v[54:57]
	v_mfma_f32_16x16x32_bf16 v[50:53], v[148:151], v[196:199], v[50:53]
	v_mfma_f32_16x16x32_bf16 v[46:49], v[140:143], v[204:207], v[46:49]
	v_mfma_f32_16x16x32_bf16 v[38:41], v[148:151], v[204:207], v[38:41]
	v_mfma_f32_16x16x32_bf16 v[30:33], v[140:143], v[212:215], v[30:33]
	v_mfma_f32_16x16x32_bf16 v[22:25], v[148:151], v[212:215], v[22:25]
	v_mfma_f32_16x16x32_bf16 v[62:65], v[144:147], v[190:193], v[62:65]
	v_mfma_f32_16x16x32_bf16 v[58:61], v[152:155], v[190:193], v[58:61]
	v_mfma_f32_16x16x32_bf16 v[54:57], v[144:147], v[200:203], v[54:57]
	v_mfma_f32_16x16x32_bf16 v[50:53], v[152:155], v[200:203], v[50:53]
	v_mfma_f32_16x16x32_bf16 v[46:49], v[144:147], v[208:211], v[46:49]
	v_mfma_f32_16x16x32_bf16 v[38:41], v[152:155], v[208:211], v[38:41]
	v_mfma_f32_16x16x32_bf16 v[30:33], v[144:147], v[216:219], v[30:33]
	v_mfma_f32_16x16x32_bf16 v[22:25], v[152:155], v[216:219], v[22:25]
	v_mfma_f32_16x16x32_bf16 v[42:45], v[156:159], v[182:185], v[42:45]
	v_mfma_f32_16x16x32_bf16 v[34:37], v[164:167], v[182:185], v[34:37]
	v_mfma_f32_16x16x32_bf16 v[26:29], v[156:159], v[196:199], v[26:29]
	v_mfma_f32_16x16x32_bf16 v[18:21], v[164:167], v[196:199], v[18:21]
	v_mfma_f32_16x16x32_bf16 v[14:17], v[156:159], v[204:207], v[14:17]
	v_mfma_f32_16x16x32_bf16 v[10:13], v[164:167], v[204:207], v[10:13]
	v_mfma_f32_16x16x32_bf16 v[6:9], v[156:159], v[212:215], v[6:9]
	v_mfma_f32_16x16x32_bf16 v[2:5], v[164:167], v[212:215], v[2:5]
	v_mfma_f32_16x16x32_bf16 v[42:45], v[160:163], v[190:193], v[42:45]
	v_mfma_f32_16x16x32_bf16 v[34:37], v[178:181], v[190:193], v[34:37]
	v_mfma_f32_16x16x32_bf16 v[26:29], v[160:163], v[200:203], v[26:29]
	v_mfma_f32_16x16x32_bf16 v[18:21], v[178:181], v[200:203], v[18:21]
	v_mfma_f32_16x16x32_bf16 v[14:17], v[160:163], v[208:211], v[14:17]
	v_mfma_f32_16x16x32_bf16 v[10:13], v[178:181], v[208:211], v[10:13]
	v_mfma_f32_16x16x32_bf16 v[6:9], v[160:163], v[216:219], v[6:9]
	v_mfma_f32_16x16x32_bf16 v[2:5], v[178:181], v[216:219], v[2:5]
	s_barrier
	s_add_i32 s44, s44, 2
	s_add_u32 s26, s26, 0x100
	s_addc_u32 s27, s27, 0
	s_add_u32 s42, s42, 0x100
	s_addc_u32 s43, s43, 0
	s_cmp_gt_u32 s44, 5
	s_cbranch_scc0 .LBB0_905
	s_and_b64 vcc, exec, s[10:11]
	s_cbranch_vccz .LBB0_908
	s_barrier

; #define PG8_STAGE(bufoff, gbase, voff) do { _Pragma("unroll") for (int _i = 0; _i < 2; ++_i) \
;         __builtin_amdgcn_global_load_lds((const unsigned*)((const char*)(gbase) + (voff)[_i]), (PG8_LAS unsigned*)(lds + (bufoff) + ldsw + _i * 8192), 16, 0, 0); } while (0)
; #define PG8_LDA(dst, b, h) do { _Pragma("unroll") for (int m = 0; m < 4; ++m) _Pragma("unroll") for (int k = 0; k < 2; ++k) dst[m][k] = *(const PG8_LAS bf16x8*)(lds + PG8_SA(b, h) + aoff + m * 2048 + k * 1024); } while (0)
; #define PG8_LDB(dst, b, h) do { _Pragma("unroll") for (int n = 0; n < 2; ++n) _Pragma("unroll") for (int k = 0; k < 2; ++k) dst[n][k] = *(const PG8_LAS bf16x8*)(lds + PG8_SB(b, h) + boff + n * 2048 + k * 1024); } while (0)
; #define PG8_MMA(ai, bj, At, Bt) do { __builtin_amdgcn_s_setprio(1); _Pragma("unroll") for (int m = 0; m < 4; ++m) _Pragma("unroll") for (int n = 0; n < 2; ++n) _Pragma("unroll") for (int k = 0; k < 2; ++k) \
;         acc[ai][bj][m][n] = __builtin_amdgcn_mfma_f32_16x16x32_bf16(Bt[n][k], At[m][k], acc[ai][bj][m][n], 0, 0, 0); __builtin_amdgcn_s_setprio(0); } while (0)
; #define PG8_WAIT_V(n) asm volatile("s_waitcnt vmcnt(" #n ")" ::: "memory")
; #define PG8_WAIT_L(n) asm volatile("s_waitcnt lgkmcnt(" #n ")" ::: "memory")
; #define PG8_BAR __builtin_amdgcn_s_barrier()
; template <class Epi, class Sched, bool ALIGN_EPI = false, bool SP2 = false, bool A_TILED = false, bool B_TILED = false>
; __device__ __forceinline__ void gemm_phase(PG8_LAS unsigned char* lds, const Gemm g, const Sched& S, const Epi& E) {
;     ...
;         for (int t = 0; t < nt; t += 2) {
;             const bool last = (t == nt - 2);
;             const char* a1 = cA + (size_t)(t + 1) * kstepA;
;             const char* a2 = last ? nA : cA + (size_t)(t + 2) * kstepA; const char* b2 = last ? nB : cB + (size_t)(t + 2) * kstepB;
;             const char* a3 = a2 + kstepA; const char* b3 = b2 + kstepB;
;             if (last && has_next) S.a_ready(nxt);
;             if constexpr (SP2) {
;             PG8_LDB(B0, 0, 0); PG8_LDB(B1, 0, 1); PG8_SCHED; PG8_LDA(At, 0, 0); PG8_STAGE(PG8_SA(1, 1), a1 + hstepA, voffA);
;             PG8_WAIT_V(8); PG8_WAIT_L(0); PG8_BAR; PG8_MMA(0, 0, At, B0); PG8_MMA(0, 1, At, B1); PG8_BAR; PG8_SCHED;
;             PG8_LDA(At, 0, 1); PG8_STAGE(PG8_SB(0, 0), b2, voffB); PG8_STAGE(PG8_SB(0, 1), b2 + hstepB, voffB); PG8_STAGE(PG8_SA(0, 0), a2, voffA);
.LBB0_1069:
	ds_read_b128 v[142:145], v161
	ds_read_b128 v[164:167], v161 offset:1024
	ds_read_b128 v[168:171], v161 offset:2048
	ds_read_b128 v[172:175], v161 offset:3072
	ds_read_b128 v[176:179], v162
	ds_read_b128 v[180:183], v162 offset:1024
	ds_read_b128 v[184:187], v162 offset:2048
	ds_read_b128 v[190:193], v162 offset:3072
	s_add_u32 s36, s34, 0x4000
	s_addc_u32 s37, s35, 0
	s_cmpk_eq_i32 s67, 0xa8
	s_cselect_b32 s40, s28, s36
	s_cselect_b32 s41, s29, s37
	s_cselect_b32 s38, s30, s65
	s_cselect_b32 s39, s31, s66
	s_add_u32 s36, s40, 0x8000
	s_addc_u32 s37, s41, 0
	v_lshl_add_u64 v[146:147], s[34:35], 0, v[138:139]
	s_add_i32 m0, s46, 0xc000
	ds_read_b128 v[194:197], v163
	ds_read_b128 v[198:201], v163 offset:1024
	ds_read_b128 v[202:205], v163 offset:2048
	ds_read_b128 v[206:209], v163 offset:3072
	ds_read_b128 v[210:213], v163 offset:4096
	ds_read_b128 v[214:217], v163 offset:5120
	ds_read_b128 v[218:221], v163 offset:6144
	ds_read_b128 v[222:225], v163 offset:7168
	global_load_lds_dwordx4 v[146:147], off
	v_lshl_add_u64 v[146:147], s[34:35], 0, v[140:141]
	s_add_i32 m0, s46, 0xe000
	s_nop 0
	global_load_lds_dwordx4 v[146:147], off
	s_waitcnt vmcnt(8)
	s_waitcnt lgkmcnt(0)
	s_barrier
	v_mfma_f32_16x16x32_bf16 v[126:129], v[142:145], v[194:197], v[126:129]
	v_mfma_f32_16x16x32_bf16 v[122:125], v[168:171], v[194:197], v[122:125]
	v_mfma_f32_16x16x32_bf16 v[110:113], v[142:145], v[202:205], v[110:113]
	v_mfma_f32_16x16x32_bf16 v[106:109], v[168:171], v[202:205], v[106:109]
	v_mfma_f32_16x16x32_bf16 v[94:97], v[142:145], v[210:213], v[94:97]
	v_mfma_f32_16x16x32_bf16 v[90:93], v[168:171], v[210:213], v[90:93]
	v_mfma_f32_16x16x32_bf16 v[78:81], v[142:145], v[218:221], v[78:81]
	v_mfma_f32_16x16x32_bf16 v[74:77], v[168:171], v[218:221], v[74:77]
	v_mfma_f32_16x16x32_bf16 v[126:129], v[164:167], v[198:201], v[126:129]
	v_mfma_f32_16x16x32_bf16 v[122:125], v[172:175], v[198:201], v[122:125]
	v_mfma_f32_16x16x32_bf16 v[110:113], v[164:167], v[206:209], v[110:113]
	v_mfma_f32_16x16x32_bf16 v[106:109], v[172:175], v[206:209], v[106:109]
	v_mfma_f32_16x16x32_bf16 v[94:97], v[164:167], v[214:217], v[94:97]
	v_mfma_f32_16x16x32_bf16 v[90:93], v[172:175], v[214:217], v[90:93]
	v_mfma_f32_16x16x32_bf16 v[78:81], v[164:167], v[222:225], v[78:81]
	v_mfma_f32_16x16x32_bf16 v[74:77], v[172:175], v[222:225], v[74:77]
	v_mfma_f32_16x16x32_bf16 v[118:121], v[176:179], v[194:197], v[118:121]
	v_mfma_f32_16x16x32_bf16 v[114:117], v[184:187], v[194:197], v[114:117]
	v_mfma_f32_16x16x32_bf16 v[102:105], v[176:179], v[202:205], v[102:105]
	v_mfma_f32_16x16x32_bf16 v[98:101], v[184:187], v[202:205], v[98:101]
	v_mfma_f32_16x16x32_bf16 v[86:89], v[176:179], v[210:213], v[86:89]
	v_mfma_f32_16x16x32_bf16 v[82:85], v[184:187], v[210:213], v[82:85]
	v_mfma_f32_16x16x32_bf16 v[70:73], v[176:179], v[218:221], v[70:73]
	v_mfma_f32_16x16x32_bf16 v[66:69], v[184:187], v[218:221], v[66:69]
	v_mfma_f32_16x16x32_bf16 v[118:121], v[180:183], v[198:201], v[118:121]
	v_mfma_f32_16x16x32_bf16 v[114:117], v[190:193], v[198:201], v[114:117]
	v_mfma_f32_16x16x32_bf16 v[102:105], v[180:183], v[206:209], v[102:105]
	v_mfma_f32_16x16x32_bf16 v[98:101], v[190:193], v[206:209], v[98:101]
	v_mfma_f32_16x16x32_bf16 v[86:89], v[180:183], v[214:217], v[86:89]
	v_mfma_f32_16x16x32_bf16 v[82:85], v[190:193], v[214:217], v[82:85]
	v_mfma_f32_16x16x32_bf16 v[70:73], v[180:183], v[222:225], v[70:73]
	v_mfma_f32_16x16x32_bf16 v[66:69], v[190:193], v[222:225], v[66:69]
	s_barrier
	s_add_i32 s68, s58, s45
	v_lshl_add_u64 v[146:147], s[38:39], 0, v[134:135]
	s_mov_b32 m0, s68
	ds_read_b128 v[194:197], v163 offset:16384
	ds_read_b128 v[198:201], v163 offset:17408
	ds_read_b128 v[202:205], v163 offset:18432
	ds_read_b128 v[206:209], v163 offset:19456
	ds_read_b128 v[210:213], v163 offset:20480
	ds_read_b128 v[214:217], v163 offset:21504
	ds_read_b128 v[218:221], v163 offset:22528
	ds_read_b128 v[222:225], v163 offset:23552
	global_load_lds_dwordx4 v[146:147], off
	s_add_i32 m0, s68, 0x2000
	s_add_u32 s68, s38, 0x2b0000
	v_lshl_add_u64 v[226:227], s[38:39], 0, v[136:137]
	s_addc_u32 s69, s39, 0
	s_add_i32 s70, s59, s45
	global_load_lds_dwordx4 v[226:227], off
	v_lshl_add_u64 v[228:229], s[68:69], 0, v[134:135]
	s_mov_b32 m0, s70
	s_nop 0
	global_load_lds_dwordx4 v[228:229], off
	v_lshl_add_u64 v[228:229], s[68:69], 0, v[136:137]
	s_add_i32 m0, s70, 0x2000
	s_nop 0
	global_load_lds_dwordx4 v[228:229], off
	v_lshl_add_u64 v[228:229], s[40:41], 0, v[130:131]
	s_mov_b32 m0, s46
	s_nop 0
	global_load_lds_dwordx4 v[228:229], off
	v_lshl_add_u64 v[228:229], s[40:41], 0, v[132:133]
	s_mov_b32 m0, s47
	s_nop 0
	global_load_lds_dwordx4 v[228:229], off
	s_waitcnt vmcnt(8)
	s_waitcnt lgkmcnt(0)
	s_barrier
; #define PG8_STAGE(bufoff, gbase, voff) do { _Pragma("unroll") for (int _i = 0; _i < 2; ++_i) \
;         __builtin_amdgcn_global_load_lds((const unsigned*)((const char*)(gbase) + (voff)[_i]), (PG8_LAS unsigned*)(lds + (bufoff) + ldsw + _i * 8192), 16, 0, 0); } while (0)
; #define PG8_LDA(dst, b, h) do { _Pragma("unroll") for (int m = 0; m < 4; ++m) _Pragma("unroll") for (int k = 0; k < 2; ++k) dst[m][k] = *(const PG8_LAS bf16x8*)(lds + PG8_SA(b, h) + aoff + m * 2048 + k * 1024); } while (0)
; #define PG8_LDB(dst, b, h) do { _Pragma("unroll") for (int n = 0; n < 2; ++n) _Pragma("unroll") for (int k = 0; k < 2; ++k) dst[n][k] = *(const PG8_LAS bf16x8*)(lds + PG8_SB(b, h) + boff + n * 2048 + k * 1024); } while (0)
; #define PG8_MMA(ai, bj, At, Bt) do { __builtin_amdgcn_s_setprio(1); _Pragma("unroll") for (int m = 0; m < 4; ++m) _Pragma("unroll") for (int n = 0; n < 2; ++n) _Pragma("unroll") for (int k = 0; k < 2; ++k) \
;         acc[ai][bj][m][n] = __builtin_amdgcn_mfma_f32_16x16x32_bf16(Bt[n][k], At[m][k], acc[ai][bj][m][n], 0, 0, 0); __builtin_amdgcn_s_setprio(0); } while (0)
; #define PG8_WAIT_V(n) asm volatile("s_waitcnt vmcnt(" #n ")" ::: "memory")
; #define PG8_WAIT_L(n) asm volatile("s_waitcnt lgkmcnt(" #n ")" ::: "memory")
; #define PG8_BAR __builtin_amdgcn_s_barrier()
; #define PG8_SCHED __builtin_amdgcn_sched_barrier(0)
; template <class Epi, class Sched, bool ALIGN_EPI = false, bool SP2 = false, bool A_TILED = false, bool B_TILED = false>
; __device__ __forceinline__ void gemm_phase(PG8_LAS unsigned char* lds, const Gemm g, const Sched& S, const Epi& E) {
;     ...
;             PG8_WAIT_V(8); PG8_WAIT_L(0); PG8_BAR; PG8_MMA(1, 0, At, B0); PG8_MMA(1, 1, At, B1); PG8_BAR; PG8_SCHED;
;             PG8_LDB(B0, 1, 0); PG8_LDB(B1, 1, 1); PG8_SCHED; PG8_LDA(At, 1, 0); PG8_STAGE(PG8_SA(0, 1), a2 + hstepA, voffA);
;             PG8_WAIT_V(8); PG8_WAIT_L(0); PG8_BAR; PG8_MMA(0, 0, At, B0); PG8_MMA(0, 1, At, B1); PG8_BAR; PG8_SCHED;
	v_mfma_f32_16x16x32_bf16 v[62:65], v[142:145], v[194:197], v[62:65]
	v_mfma_f32_16x16x32_bf16 v[58:61], v[168:171], v[194:197], v[58:61]
	v_mfma_f32_16x16x32_bf16 v[46:49], v[142:145], v[202:205], v[46:49]
	v_mfma_f32_16x16x32_bf16 v[42:45], v[168:171], v[202:205], v[42:45]
	v_mfma_f32_16x16x32_bf16 v[30:33], v[142:145], v[210:213], v[30:33]
	v_mfma_f32_16x16x32_bf16 v[26:29], v[168:171], v[210:213], v[26:29]
	v_mfma_f32_16x16x32_bf16 v[14:17], v[142:145], v[218:221], v[14:17]
	v_mfma_f32_16x16x32_bf16 v[10:13], v[168:171], v[218:221], v[10:13]
	v_mfma_f32_16x16x32_bf16 v[62:65], v[164:167], v[198:201], v[62:65]
	v_mfma_f32_16x16x32_bf16 v[58:61], v[172:175], v[198:201], v[58:61]
	v_mfma_f32_16x16x32_bf16 v[46:49], v[164:167], v[206:209], v[46:49]
	v_mfma_f32_16x16x32_bf16 v[42:45], v[172:175], v[206:209], v[42:45]
	v_mfma_f32_16x16x32_bf16 v[30:33], v[164:167], v[214:217], v[30:33]
	v_mfma_f32_16x16x32_bf16 v[26:29], v[172:175], v[214:217], v[26:29]
	v_mfma_f32_16x16x32_bf16 v[14:17], v[164:167], v[222:225], v[14:17]
	v_mfma_f32_16x16x32_bf16 v[10:13], v[172:175], v[222:225], v[10:13]
	v_mfma_f32_16x16x32_bf16 v[54:57], v[176:179], v[194:197], v[54:57]
	v_mfma_f32_16x16x32_bf16 v[50:53], v[184:187], v[194:197], v[50:53]
	v_mfma_f32_16x16x32_bf16 v[38:41], v[176:179], v[202:205], v[38:41]
	v_mfma_f32_16x16x32_bf16 v[34:37], v[184:187], v[202:205], v[34:37]
	v_mfma_f32_16x16x32_bf16 v[22:25], v[176:179], v[210:213], v[22:25]
	v_mfma_f32_16x16x32_bf16 v[18:21], v[184:187], v[210:213], v[18:21]
	v_mfma_f32_16x16x32_bf16 v[6:9], v[176:179], v[218:221], v[6:9]
	v_mfma_f32_16x16x32_bf16 v[2:5], v[184:187], v[218:221], v[2:5]
	v_mfma_f32_16x16x32_bf16 v[54:57], v[180:183], v[198:201], v[54:57]
	v_mfma_f32_16x16x32_bf16 v[50:53], v[190:193], v[198:201], v[50:53]
	v_mfma_f32_16x16x32_bf16 v[38:41], v[180:183], v[206:209], v[38:41]
	v_mfma_f32_16x16x32_bf16 v[34:37], v[190:193], v[206:209], v[34:37]
	v_mfma_f32_16x16x32_bf16 v[22:25], v[180:183], v[214:217], v[22:25]
	v_mfma_f32_16x16x32_bf16 v[18:21], v[190:193], v[214:217], v[18:21]
	v_mfma_f32_16x16x32_bf16 v[6:9], v[180:183], v[222:225], v[6:9]
	v_mfma_f32_16x16x32_bf16 v[2:5], v[190:193], v[222:225], v[2:5]
	s_barrier
	s_add_i32 s68, 0, 0x18000
	s_add_i32 s69, 0, 0x1c000
	v_add_u32_e32 v172, s68, v159
	v_add_u32_e32 v188, s69, v159
	ds_read_b128 v[142:145], v172
	ds_read_b128 v[164:167], v172 offset:1024
	ds_read_b128 v[168:171], v172 offset:2048
	ds_read_b128 v[172:175], v172 offset:3072
	ds_read_b128 v[176:179], v188
	ds_read_b128 v[180:183], v188 offset:1024
	ds_read_b128 v[184:187], v188 offset:2048
	ds_read_b128 v[190:193], v188 offset:3072
	s_add_u32 s40, s40, 0x4000
	s_addc_u32 s41, s41, 0
	s_mov_b32 m0, s52
	v_lshl_add_u64 v[228:229], s[40:41], 0, v[130:131]
	ds_read_b128 v[194:197], v163 offset:32768
	ds_read_b128 v[198:201], v163 offset:33792
	ds_read_b128 v[202:205], v163 offset:34816
	ds_read_b128 v[206:209], v163 offset:35840
	ds_read_b128 v[210:213], v163 offset:36864
	ds_read_b128 v[214:217], v163 offset:37888
	ds_read_b128 v[218:221], v163 offset:38912
	ds_read_b128 v[222:225], v163 offset:39936
	global_load_lds_dwordx4 v[228:229], off
	v_lshl_add_u64 v[228:229], s[40:41], 0, v[132:133]
	s_mov_b32 m0, s53
	s_nop 0
	global_load_lds_dwordx4 v[228:229], off
	s_waitcnt vmcnt(8)
	s_waitcnt lgkmcnt(0)
	s_barrier
	v_mfma_f32_16x16x32_bf16 v[126:129], v[142:145], v[194:197], v[126:129]
	v_mfma_f32_16x16x32_bf16 v[122:125], v[168:171], v[194:197], v[122:125]
	v_mfma_f32_16x16x32_bf16 v[110:113], v[142:145], v[202:205], v[110:113]
	v_mfma_f32_16x16x32_bf16 v[106:109], v[168:171], v[202:205], v[106:109]
	v_mfma_f32_16x16x32_bf16 v[94:97], v[142:145], v[210:213], v[94:97]
	v_mfma_f32_16x16x32_bf16 v[90:93], v[168:171], v[210:213], v[90:93]
	v_mfma_f32_16x16x32_bf16 v[78:81], v[142:145], v[218:221], v[78:81]
	v_mfma_f32_16x16x32_bf16 v[74:77], v[168:171], v[218:221], v[74:77]
	v_mfma_f32_16x16x32_bf16 v[126:129], v[164:167], v[198:201], v[126:129]
	v_mfma_f32_16x16x32_bf16 v[122:125], v[172:175], v[198:201], v[122:125]
	v_mfma_f32_16x16x32_bf16 v[110:113], v[164:167], v[206:209], v[110:113]
	v_mfma_f32_16x16x32_bf16 v[106:109], v[172:175], v[206:209], v[106:109]
	v_mfma_f32_16x16x32_bf16 v[94:97], v[164:167], v[214:217], v[94:97]
	v_mfma_f32_16x16x32_bf16 v[90:93], v[172:175], v[214:217], v[90:93]
	v_mfma_f32_16x16x32_bf16 v[78:81], v[164:167], v[222:225], v[78:81]
	v_mfma_f32_16x16x32_bf16 v[74:77], v[172:175], v[222:225], v[74:77]
	v_mfma_f32_16x16x32_bf16 v[118:121], v[176:179], v[194:197], v[118:121]
	v_mfma_f32_16x16x32_bf16 v[114:117], v[184:187], v[194:197], v[114:117]
	v_mfma_f32_16x16x32_bf16 v[102:105], v[176:179], v[202:205], v[102:105]
	v_mfma_f32_16x16x32_bf16 v[98:101], v[184:187], v[202:205], v[98:101]
	v_mfma_f32_16x16x32_bf16 v[86:89], v[176:179], v[210:213], v[86:89]
	v_mfma_f32_16x16x32_bf16 v[82:85], v[184:187], v[210:213], v[82:85]
	v_mfma_f32_16x16x32_bf16 v[70:73], v[176:179], v[218:221], v[70:73]
	v_mfma_f32_16x16x32_bf16 v[66:69], v[184:187], v[218:221], v[66:69]
	v_mfma_f32_16x16x32_bf16 v[118:121], v[180:183], v[198:201], v[118:121]
	v_mfma_f32_16x16x32_bf16 v[114:117], v[190:193], v[198:201], v[114:117]
	v_mfma_f32_16x16x32_bf16 v[102:105], v[180:183], v[206:209], v[102:105]
	v_mfma_f32_16x16x32_bf16 v[98:101], v[190:193], v[206:209], v[98:101]
	v_mfma_f32_16x16x32_bf16 v[86:89], v[180:183], v[214:217], v[86:89]
	v_mfma_f32_16x16x32_bf16 v[82:85], v[190:193], v[214:217], v[82:85]
	v_mfma_f32_16x16x32_bf16 v[70:73], v[180:183], v[222:225], v[70:73]
	v_mfma_f32_16x16x32_bf16 v[66:69], v[190:193], v[222:225], v[66:69]
	s_barrier
; #define PG8_STAGE(bufoff, gbase, voff) do { _Pragma("unroll") for (int _i = 0; _i < 2; ++_i) \
;         __builtin_amdgcn_global_load_lds((const unsigned*)((const char*)(gbase) + (voff)[_i]), (PG8_LAS unsigned*)(lds + (bufoff) + ldsw + _i * 8192), 16, 0, 0); } while (0)
; #define PG8_LDA(dst, b, h) do { _Pragma("unroll") for (int m = 0; m < 4; ++m) _Pragma("unroll") for (int k = 0; k < 2; ++k) dst[m][k] = *(const PG8_LAS bf16x8*)(lds + PG8_SA(b, h) + aoff + m * 2048 + k * 1024); } while (0)
; #define PG8_MMA(ai, bj, At, Bt) do { __builtin_amdgcn_s_setprio(1); _Pragma("unroll") for (int m = 0; m < 4; ++m) _Pragma("unroll") for (int n = 0; n < 2; ++n) _Pragma("unroll") for (int k = 0; k < 2; ++k) \
;         acc[ai][bj][m][n] = __builtin_amdgcn_mfma_f32_16x16x32_bf16(Bt[n][k], At[m][k], acc[ai][bj][m][n], 0, 0, 0); __builtin_amdgcn_s_setprio(0); } while (0)
; #define PG8_WAIT_V(n) asm volatile("s_waitcnt vmcnt(" #n ")" ::: "memory")
; #define PG8_WAIT_L(n) asm volatile("s_waitcnt lgkmcnt(" #n ")" ::: "memory")
; #define PG8_BAR __builtin_amdgcn_s_barrier()
; #define PG8_SCHED __builtin_amdgcn_sched_barrier(0)
; template <class Epi, class Sched, bool ALIGN_EPI = false, bool SP2 = false, bool A_TILED = false, bool B_TILED = false>
; __device__ __forceinline__ void gemm_phase(PG8_LAS unsigned char* lds, const Gemm g, const Sched& S, const Epi& E) {
;     ...
;             PG8_LDA(At, 1, 1); PG8_STAGE(PG8_SB(1, 0), b3, voffB); PG8_STAGE(PG8_SB(1, 1), b3 + hstepB, voffB); PG8_STAGE(PG8_SA(1, 0), a3, voffA);
;             PG8_WAIT_V(8); PG8_WAIT_L(0); PG8_BAR; PG8_MMA(1, 0, At, B0); PG8_MMA(1, 1, At, B1); PG8_BAR; PG8_SCHED;
;     ...
;         if constexpr (ALIGN_EPI) { if (wr == 0) PG8_BAR; }
	s_add_i32 s40, s68, s45
	v_lshl_add_u64 v[146:147], v[146:147], 0, s[16:17]
	s_mov_b32 m0, s40
	ds_read_b128 v[194:197], v163 offset:49152
	ds_read_b128 v[198:201], v163 offset:50176
	ds_read_b128 v[202:205], v163 offset:51200
	ds_read_b128 v[206:209], v163 offset:52224
	ds_read_b128 v[210:213], v163 offset:53248
	ds_read_b128 v[214:217], v163 offset:54272
	ds_read_b128 v[218:221], v163 offset:55296
	ds_read_b128 v[222:225], v163 offset:56320
	global_load_lds_dwordx4 v[146:147], off
	s_add_i32 m0, s40, 0x2000
	s_add_u32 s38, s38, 0x2b0080
	v_lshl_add_u64 v[146:147], v[226:227], 0, s[16:17]
	s_addc_u32 s39, s39, 0
	s_add_i32 s40, s69, s45
	global_load_lds_dwordx4 v[146:147], off
	v_lshl_add_u64 v[146:147], s[38:39], 0, v[134:135]
	s_mov_b32 m0, s40
	s_nop 0
	global_load_lds_dwordx4 v[146:147], off
	v_lshl_add_u64 v[146:147], s[38:39], 0, v[136:137]
	s_add_i32 m0, s40, 0x2000
	s_nop 0
	global_load_lds_dwordx4 v[146:147], off
	v_lshl_add_u64 v[146:147], s[36:37], 0, v[130:131]
	s_mov_b32 m0, s54
	s_nop 0
	global_load_lds_dwordx4 v[146:147], off
	v_lshl_add_u64 v[146:147], s[36:37], 0, v[132:133]
	s_mov_b32 m0, s55
	s_nop 0
	global_load_lds_dwordx4 v[146:147], off
	s_waitcnt vmcnt(8)
	s_waitcnt lgkmcnt(0)
	s_barrier
	v_mfma_f32_16x16x32_bf16 v[62:65], v[142:145], v[194:197], v[62:65]
	v_mfma_f32_16x16x32_bf16 v[58:61], v[168:171], v[194:197], v[58:61]
	v_mfma_f32_16x16x32_bf16 v[46:49], v[142:145], v[202:205], v[46:49]
	v_mfma_f32_16x16x32_bf16 v[42:45], v[168:171], v[202:205], v[42:45]
	v_mfma_f32_16x16x32_bf16 v[30:33], v[142:145], v[210:213], v[30:33]
	v_mfma_f32_16x16x32_bf16 v[26:29], v[168:171], v[210:213], v[26:29]
	v_mfma_f32_16x16x32_bf16 v[14:17], v[142:145], v[218:221], v[14:17]
	v_mfma_f32_16x16x32_bf16 v[10:13], v[168:171], v[218:221], v[10:13]
	v_mfma_f32_16x16x32_bf16 v[62:65], v[164:167], v[198:201], v[62:65]
	v_mfma_f32_16x16x32_bf16 v[58:61], v[172:175], v[198:201], v[58:61]
	v_mfma_f32_16x16x32_bf16 v[46:49], v[164:167], v[206:209], v[46:49]
	v_mfma_f32_16x16x32_bf16 v[42:45], v[172:175], v[206:209], v[42:45]
	v_mfma_f32_16x16x32_bf16 v[30:33], v[164:167], v[214:217], v[30:33]
	v_mfma_f32_16x16x32_bf16 v[26:29], v[172:175], v[214:217], v[26:29]
	v_mfma_f32_16x16x32_bf16 v[14:17], v[164:167], v[222:225], v[14:17]
	v_mfma_f32_16x16x32_bf16 v[10:13], v[172:175], v[222:225], v[10:13]
	v_mfma_f32_16x16x32_bf16 v[54:57], v[176:179], v[194:197], v[54:57]
	v_mfma_f32_16x16x32_bf16 v[50:53], v[184:187], v[194:197], v[50:53]
	v_mfma_f32_16x16x32_bf16 v[38:41], v[176:179], v[202:205], v[38:41]
	v_mfma_f32_16x16x32_bf16 v[34:37], v[184:187], v[202:205], v[34:37]
	v_mfma_f32_16x16x32_bf16 v[22:25], v[176:179], v[210:213], v[22:25]
	v_mfma_f32_16x16x32_bf16 v[18:21], v[184:187], v[210:213], v[18:21]
	v_mfma_f32_16x16x32_bf16 v[6:9], v[176:179], v[218:221], v[6:9]
	v_mfma_f32_16x16x32_bf16 v[2:5], v[184:187], v[218:221], v[2:5]
	v_mfma_f32_16x16x32_bf16 v[54:57], v[180:183], v[198:201], v[54:57]
	v_mfma_f32_16x16x32_bf16 v[50:53], v[190:193], v[198:201], v[50:53]
	v_mfma_f32_16x16x32_bf16 v[38:41], v[180:183], v[206:209], v[38:41]
	v_mfma_f32_16x16x32_bf16 v[34:37], v[190:193], v[206:209], v[34:37]
	v_mfma_f32_16x16x32_bf16 v[22:25], v[180:183], v[214:217], v[22:25]
	v_mfma_f32_16x16x32_bf16 v[18:21], v[190:193], v[214:217], v[18:21]
	v_mfma_f32_16x16x32_bf16 v[6:9], v[180:183], v[222:225], v[6:9]
	v_mfma_f32_16x16x32_bf16 v[2:5], v[190:193], v[222:225], v[2:5]
	s_barrier
	s_add_i32 s67, s67, 2
	s_add_u32 s65, s65, 0x100
	s_addc_u32 s66, s66, 0
	s_add_u32 s34, s34, 0x10000
	s_addc_u32 s35, s35, 0
	s_cmpk_gt_u32 s67, 0xa9
	s_cbranch_scc0 .LBB0_1069
	s_and_b64 vcc, exec, s[18:19]
	s_cbranch_vccz .LBB0_1072
	s_barrier

; #define PG8_STAGE(bufoff, gbase, voff) do { _Pragma("unroll") for (int _i = 0; _i < 2; ++_i) \
;         __builtin_amdgcn_global_load_lds((const unsigned*)((const char*)(gbase) + (voff)[_i]), (PG8_LAS unsigned*)(lds + (bufoff) + ldsw + _i * 8192), 16, 0, 0); } while (0)
; #define PG8_LDA(dst, b, h) do { _Pragma("unroll") for (int m = 0; m < 4; ++m) _Pragma("unroll") for (int k = 0; k < 2; ++k) dst[m][k] = *(const PG8_LAS bf16x8*)(lds + PG8_SA(b, h) + aoff + m * 2048 + k * 1024); } while (0)
; #define PG8_LDB(dst, b, h) do { _Pragma("unroll") for (int n = 0; n < 2; ++n) _Pragma("unroll") for (int k = 0; k < 2; ++k) dst[n][k] = *(const PG8_LAS bf16x8*)(lds + PG8_SB(b, h) + boff + n * 2048 + k * 1024); } while (0)
; #define PG8_MMA(ai, bj, At, Bt) do { __builtin_amdgcn_s_setprio(1); _Pragma("unroll") for (int m = 0; m < 4; ++m) _Pragma("unroll") for (int n = 0; n < 2; ++n) _Pragma("unroll") for (int k = 0; k < 2; ++k) \
;         acc[ai][bj][m][n] = __builtin_amdgcn_mfma_f32_16x16x32_bf16(Bt[n][k], At[m][k], acc[ai][bj][m][n], 0, 0, 0); __builtin_amdgcn_s_setprio(0); } while (0)
; #define PG8_WAIT_V(n) asm volatile("s_waitcnt vmcnt(" #n ")" ::: "memory")
; #define PG8_WAIT_L(n) asm volatile("s_waitcnt lgkmcnt(" #n ")" ::: "memory")
; #define PG8_BAR __builtin_amdgcn_s_barrier()
; template <class Epi, class Sched, bool ALIGN_EPI = false, bool SP2 = false, bool A_TILED = false, bool B_TILED = false>
; __device__ __forceinline__ void gemm_phase(PG8_LAS unsigned char* lds, const Gemm g, const Sched& S, const Epi& E) {
;     ...
;         for (int t = 0; t < nt; t += 2) {
;             const bool last = (t == nt - 2);
;             const char* a1 = cA + (size_t)(t + 1) * kstepA;
;             const char* a2 = last ? nA : cA + (size_t)(t + 2) * kstepA; const char* b2 = last ? nB : cB + (size_t)(t + 2) * kstepB;
;             const char* a3 = a2 + kstepA; const char* b3 = b2 + kstepB;
;             if (last && has_next) S.a_ready(nxt);
;             if constexpr (SP2) {
;             PG8_LDB(B0, 0, 0); PG8_LDB(B1, 0, 1); PG8_SCHED; PG8_LDA(At, 0, 0); PG8_STAGE(PG8_SA(1, 1), a1 + hstepA, voffA);
;             PG8_WAIT_V(8); PG8_WAIT_L(0); PG8_BAR; PG8_MMA(0, 0, At, B0); PG8_MMA(0, 1, At, B1); PG8_BAR; PG8_SCHED;
;             PG8_LDA(At, 0, 1); PG8_STAGE(PG8_SB(0, 0), b2, voffB); PG8_STAGE(PG8_SB(0, 1), b2 + hstepB, voffB); PG8_STAGE(PG8_SA(0, 0), a2, voffA);
.LBB0_1097:
	ds_read_b128 v[146:149], v143
	ds_read_b128 v[150:153], v143 offset:1024
	ds_read_b128 v[154:157], v143 offset:2048
	ds_read_b128 v[158:161], v143 offset:3072
	ds_read_b128 v[162:165], v144
	ds_read_b128 v[166:169], v144 offset:1024
	ds_read_b128 v[170:173], v144 offset:2048
	ds_read_b128 v[174:177], v144 offset:3072
	s_add_i32 s55, s26, 2
	s_add_u32 s27, s24, 0x4000
	s_addc_u32 s28, s25, 0
	s_cmp_eq_u32 s17, s26
	s_cselect_b32 s30, s20, s27
	s_cselect_b32 s31, s21, s28
	s_cselect_b32 s28, s22, s53
	s_cselect_b32 s29, s23, s54
	s_add_u32 s26, s30, 0x8000
	s_addc_u32 s27, s31, 0
	v_lshl_add_u64 v[186:187], s[24:25], 0, v[138:139]
	s_add_i32 m0, s35, 0xc000
	ds_read_b128 v[178:181], v145
	ds_read_b128 v[182:185], v145 offset:1024
	ds_read_b128 v[190:193], v145 offset:2048
	ds_read_b128 v[194:197], v145 offset:3072
	ds_read_b128 v[198:201], v145 offset:4096
	ds_read_b128 v[202:205], v145 offset:5120
	ds_read_b128 v[206:209], v145 offset:6144
	ds_read_b128 v[210:213], v145 offset:7168
	global_load_lds_dwordx4 v[186:187], off
	v_lshl_add_u64 v[186:187], s[24:25], 0, v[140:141]
	s_add_i32 m0, s35, 0xe000
	s_nop 0
	global_load_lds_dwordx4 v[186:187], off
	s_waitcnt vmcnt(8)
	s_waitcnt lgkmcnt(0)
	s_barrier
	v_mfma_f32_16x16x32_bf16 v[124:127], v[146:149], v[178:181], v[124:127]
	v_mfma_f32_16x16x32_bf16 v[120:123], v[154:157], v[178:181], v[120:123]
	v_mfma_f32_16x16x32_bf16 v[116:119], v[146:149], v[190:193], v[116:119]
	v_mfma_f32_16x16x32_bf16 v[112:115], v[154:157], v[190:193], v[112:115]
	v_mfma_f32_16x16x32_bf16 v[108:111], v[146:149], v[198:201], v[108:111]
	v_mfma_f32_16x16x32_bf16 v[100:103], v[154:157], v[198:201], v[100:103]
	v_mfma_f32_16x16x32_bf16 v[92:95], v[146:149], v[206:209], v[92:95]
	v_mfma_f32_16x16x32_bf16 v[84:87], v[154:157], v[206:209], v[84:87]
	v_mfma_f32_16x16x32_bf16 v[124:127], v[150:153], v[182:185], v[124:127]
	v_mfma_f32_16x16x32_bf16 v[120:123], v[158:161], v[182:185], v[120:123]
	v_mfma_f32_16x16x32_bf16 v[116:119], v[150:153], v[194:197], v[116:119]
	v_mfma_f32_16x16x32_bf16 v[112:115], v[158:161], v[194:197], v[112:115]
	v_mfma_f32_16x16x32_bf16 v[108:111], v[150:153], v[202:205], v[108:111]
	v_mfma_f32_16x16x32_bf16 v[100:103], v[158:161], v[202:205], v[100:103]
	v_mfma_f32_16x16x32_bf16 v[92:95], v[150:153], v[210:213], v[92:95]
	v_mfma_f32_16x16x32_bf16 v[84:87], v[158:161], v[210:213], v[84:87]
	v_mfma_f32_16x16x32_bf16 v[104:107], v[162:165], v[178:181], v[104:107]
	v_mfma_f32_16x16x32_bf16 v[96:99], v[170:173], v[178:181], v[96:99]
	v_mfma_f32_16x16x32_bf16 v[88:91], v[162:165], v[190:193], v[88:91]
	v_mfma_f32_16x16x32_bf16 v[80:83], v[170:173], v[190:193], v[80:83]
	v_mfma_f32_16x16x32_bf16 v[76:79], v[162:165], v[198:201], v[76:79]
	v_mfma_f32_16x16x32_bf16 v[72:75], v[170:173], v[198:201], v[72:75]
	v_mfma_f32_16x16x32_bf16 v[68:71], v[162:165], v[206:209], v[68:71]
	v_mfma_f32_16x16x32_bf16 v[64:67], v[170:173], v[206:209], v[64:67]
	v_mfma_f32_16x16x32_bf16 v[104:107], v[166:169], v[182:185], v[104:107]
	v_mfma_f32_16x16x32_bf16 v[96:99], v[174:177], v[182:185], v[96:99]
	v_mfma_f32_16x16x32_bf16 v[88:91], v[166:169], v[194:197], v[88:91]
	v_mfma_f32_16x16x32_bf16 v[80:83], v[174:177], v[194:197], v[80:83]
	v_mfma_f32_16x16x32_bf16 v[76:79], v[166:169], v[202:205], v[76:79]
	v_mfma_f32_16x16x32_bf16 v[72:75], v[174:177], v[202:205], v[72:75]
	v_mfma_f32_16x16x32_bf16 v[68:71], v[166:169], v[210:213], v[68:71]
	v_mfma_f32_16x16x32_bf16 v[64:67], v[174:177], v[210:213], v[64:67]
	s_barrier
	s_add_i32 s56, s6, s34
	v_lshl_add_u64 v[186:187], s[28:29], 0, v[128:129]
	s_mov_b32 m0, s56
	ds_read_b128 v[178:181], v145 offset:16384
	ds_read_b128 v[182:185], v145 offset:17408
	ds_read_b128 v[190:193], v145 offset:18432
	ds_read_b128 v[194:197], v145 offset:19456
	ds_read_b128 v[198:201], v145 offset:20480
	ds_read_b128 v[202:205], v145 offset:21504
	ds_read_b128 v[206:209], v145 offset:22528
	ds_read_b128 v[210:213], v145 offset:23552
	global_load_lds_dwordx4 v[186:187], off
	s_add_i32 m0, s56, 0x2000
	s_add_u32 s56, s28, 0x2b0000
	v_lshl_add_u64 v[214:215], s[28:29], 0, v[134:135]
	s_addc_u32 s57, s29, 0
	s_add_i32 s58, s41, s34
	global_load_lds_dwordx4 v[214:215], off
	v_lshl_add_u64 v[216:217], s[56:57], 0, v[128:129]
	s_mov_b32 m0, s58
	s_nop 0
	global_load_lds_dwordx4 v[216:217], off
	v_lshl_add_u64 v[216:217], s[56:57], 0, v[134:135]
	s_add_i32 m0, s58, 0x2000
	s_nop 0
	global_load_lds_dwordx4 v[216:217], off
	v_lshl_add_u64 v[216:217], s[30:31], 0, v[130:131]
	s_mov_b32 m0, s35
	s_nop 0
	global_load_lds_dwordx4 v[216:217], off
	v_lshl_add_u64 v[216:217], s[30:31], 0, v[132:133]
	s_mov_b32 m0, s36
	s_nop 0
	global_load_lds_dwordx4 v[216:217], off
	s_waitcnt vmcnt(8)
	s_waitcnt lgkmcnt(0)
	s_barrier
; #define PG8_STAGE(bufoff, gbase, voff) do { _Pragma("unroll") for (int _i = 0; _i < 2; ++_i) \
;         __builtin_amdgcn_global_load_lds((const unsigned*)((const char*)(gbase) + (voff)[_i]), (PG8_LAS unsigned*)(lds + (bufoff) + ldsw + _i * 8192), 16, 0, 0); } while (0)
; #define PG8_LDA(dst, b, h) do { _Pragma("unroll") for (int m = 0; m < 4; ++m) _Pragma("unroll") for (int k = 0; k < 2; ++k) dst[m][k] = *(const PG8_LAS bf16x8*)(lds + PG8_SA(b, h) + aoff + m * 2048 + k * 1024); } while (0)
; #define PG8_LDB(dst, b, h) do { _Pragma("unroll") for (int n = 0; n < 2; ++n) _Pragma("unroll") for (int k = 0; k < 2; ++k) dst[n][k] = *(const PG8_LAS bf16x8*)(lds + PG8_SB(b, h) + boff + n * 2048 + k * 1024); } while (0)
; #define PG8_MMA(ai, bj, At, Bt) do { __builtin_amdgcn_s_setprio(1); _Pragma("unroll") for (int m = 0; m < 4; ++m) _Pragma("unroll") for (int n = 0; n < 2; ++n) _Pragma("unroll") for (int k = 0; k < 2; ++k) \
;         acc[ai][bj][m][n] = __builtin_amdgcn_mfma_f32_16x16x32_bf16(Bt[n][k], At[m][k], acc[ai][bj][m][n], 0, 0, 0); __builtin_amdgcn_s_setprio(0); } while (0)
; #define PG8_WAIT_V(n) asm volatile("s_waitcnt vmcnt(" #n ")" ::: "memory")
; #define PG8_WAIT_L(n) asm volatile("s_waitcnt lgkmcnt(" #n ")" ::: "memory")
; #define PG8_BAR __builtin_amdgcn_s_barrier()
; #define PG8_SCHED __builtin_amdgcn_sched_barrier(0)
; template <class Epi, class Sched, bool ALIGN_EPI = false, bool SP2 = false, bool A_TILED = false, bool B_TILED = false>
; __device__ __forceinline__ void gemm_phase(PG8_LAS unsigned char* lds, const Gemm g, const Sched& S, const Epi& E) {
;     ...
;             PG8_WAIT_V(8); PG8_WAIT_L(0); PG8_BAR; PG8_MMA(1, 0, At, B0); PG8_MMA(1, 1, At, B1); PG8_BAR; PG8_SCHED;
;             PG8_LDB(B0, 1, 0); PG8_LDB(B1, 1, 1); PG8_SCHED; PG8_LDA(At, 1, 0); PG8_STAGE(PG8_SA(0, 1), a2 + hstepA, voffA);
;             PG8_WAIT_V(8); PG8_WAIT_L(0); PG8_BAR; PG8_MMA(0, 0, At, B0); PG8_MMA(0, 1, At, B1); PG8_BAR; PG8_SCHED;
	v_mfma_f32_16x16x32_bf16 v[60:63], v[146:149], v[178:181], v[60:63]
	v_mfma_f32_16x16x32_bf16 v[56:59], v[154:157], v[178:181], v[56:59]
	v_mfma_f32_16x16x32_bf16 v[52:55], v[146:149], v[190:193], v[52:55]
	v_mfma_f32_16x16x32_bf16 v[48:51], v[154:157], v[190:193], v[48:51]
	v_mfma_f32_16x16x32_bf16 v[44:47], v[146:149], v[198:201], v[44:47]
	v_mfma_f32_16x16x32_bf16 v[36:39], v[154:157], v[198:201], v[36:39]
	v_mfma_f32_16x16x32_bf16 v[28:31], v[146:149], v[206:209], v[28:31]
	v_mfma_f32_16x16x32_bf16 v[20:23], v[154:157], v[206:209], v[20:23]
	v_mfma_f32_16x16x32_bf16 v[60:63], v[150:153], v[182:185], v[60:63]
	v_mfma_f32_16x16x32_bf16 v[56:59], v[158:161], v[182:185], v[56:59]
	v_mfma_f32_16x16x32_bf16 v[52:55], v[150:153], v[194:197], v[52:55]
	v_mfma_f32_16x16x32_bf16 v[48:51], v[158:161], v[194:197], v[48:51]
	v_mfma_f32_16x16x32_bf16 v[44:47], v[150:153], v[202:205], v[44:47]
	v_mfma_f32_16x16x32_bf16 v[36:39], v[158:161], v[202:205], v[36:39]
	v_mfma_f32_16x16x32_bf16 v[28:31], v[150:153], v[210:213], v[28:31]
	v_mfma_f32_16x16x32_bf16 v[20:23], v[158:161], v[210:213], v[20:23]
	v_mfma_f32_16x16x32_bf16 v[40:43], v[162:165], v[178:181], v[40:43]
	v_mfma_f32_16x16x32_bf16 v[32:35], v[170:173], v[178:181], v[32:35]
	v_mfma_f32_16x16x32_bf16 v[24:27], v[162:165], v[190:193], v[24:27]
	v_mfma_f32_16x16x32_bf16 v[16:19], v[170:173], v[190:193], v[16:19]
	v_mfma_f32_16x16x32_bf16 v[12:15], v[162:165], v[198:201], v[12:15]
	v_mfma_f32_16x16x32_bf16 v[8:11], v[170:173], v[198:201], v[8:11]
	v_mfma_f32_16x16x32_bf16 v[4:7], v[162:165], v[206:209], v[4:7]
	v_mfma_f32_16x16x32_bf16 v[0:3], v[170:173], v[206:209], v[0:3]
	v_mfma_f32_16x16x32_bf16 v[40:43], v[166:169], v[182:185], v[40:43]
	v_mfma_f32_16x16x32_bf16 v[32:35], v[174:177], v[182:185], v[32:35]
	v_mfma_f32_16x16x32_bf16 v[24:27], v[166:169], v[194:197], v[24:27]
	v_mfma_f32_16x16x32_bf16 v[16:19], v[174:177], v[194:197], v[16:19]
	v_mfma_f32_16x16x32_bf16 v[12:15], v[166:169], v[202:205], v[12:15]
	v_mfma_f32_16x16x32_bf16 v[8:11], v[174:177], v[202:205], v[8:11]
	v_mfma_f32_16x16x32_bf16 v[4:7], v[166:169], v[210:213], v[4:7]
	v_mfma_f32_16x16x32_bf16 v[0:3], v[174:177], v[210:213], v[0:3]
	s_barrier
	s_add_i32 s56, 0, 0x18000
	s_add_i32 s57, 0, 0x1c000
	v_add_u32_e32 v158, s56, v142
	v_add_u32_e32 v174, s57, v142
	ds_read_b128 v[146:149], v158
	ds_read_b128 v[150:153], v158 offset:1024
	ds_read_b128 v[154:157], v158 offset:2048
	ds_read_b128 v[158:161], v158 offset:3072
	ds_read_b128 v[162:165], v174
	ds_read_b128 v[166:169], v174 offset:1024
	ds_read_b128 v[170:173], v174 offset:2048
	ds_read_b128 v[174:177], v174 offset:3072
	s_add_u32 s30, s30, 0x4000
	s_addc_u32 s31, s31, 0
	s_mov_b32 m0, s37
	v_lshl_add_u64 v[216:217], s[30:31], 0, v[130:131]
	ds_read_b128 v[178:181], v145 offset:32768
	ds_read_b128 v[182:185], v145 offset:33792
	ds_read_b128 v[190:193], v145 offset:34816
	ds_read_b128 v[194:197], v145 offset:35840
	ds_read_b128 v[198:201], v145 offset:36864
	ds_read_b128 v[202:205], v145 offset:37888
	ds_read_b128 v[206:209], v145 offset:38912
	ds_read_b128 v[210:213], v145 offset:39936
	global_load_lds_dwordx4 v[216:217], off
	v_lshl_add_u64 v[216:217], s[30:31], 0, v[132:133]
	s_mov_b32 m0, s38
	s_nop 0
	global_load_lds_dwordx4 v[216:217], off
	s_waitcnt vmcnt(8)
	s_waitcnt lgkmcnt(0)
	s_barrier
	v_mfma_f32_16x16x32_bf16 v[124:127], v[146:149], v[178:181], v[124:127]
	v_mfma_f32_16x16x32_bf16 v[120:123], v[154:157], v[178:181], v[120:123]
	v_mfma_f32_16x16x32_bf16 v[116:119], v[146:149], v[190:193], v[116:119]
	v_mfma_f32_16x16x32_bf16 v[112:115], v[154:157], v[190:193], v[112:115]
	v_mfma_f32_16x16x32_bf16 v[108:111], v[146:149], v[198:201], v[108:111]
	v_mfma_f32_16x16x32_bf16 v[100:103], v[154:157], v[198:201], v[100:103]
	v_mfma_f32_16x16x32_bf16 v[92:95], v[146:149], v[206:209], v[92:95]
	v_mfma_f32_16x16x32_bf16 v[84:87], v[154:157], v[206:209], v[84:87]
	v_mfma_f32_16x16x32_bf16 v[124:127], v[150:153], v[182:185], v[124:127]
	v_mfma_f32_16x16x32_bf16 v[120:123], v[158:161], v[182:185], v[120:123]
	v_mfma_f32_16x16x32_bf16 v[116:119], v[150:153], v[194:197], v[116:119]
	v_mfma_f32_16x16x32_bf16 v[112:115], v[158:161], v[194:197], v[112:115]
	v_mfma_f32_16x16x32_bf16 v[108:111], v[150:153], v[202:205], v[108:111]
	v_mfma_f32_16x16x32_bf16 v[100:103], v[158:161], v[202:205], v[100:103]
	v_mfma_f32_16x16x32_bf16 v[92:95], v[150:153], v[210:213], v[92:95]
	v_mfma_f32_16x16x32_bf16 v[84:87], v[158:161], v[210:213], v[84:87]
	v_mfma_f32_16x16x32_bf16 v[104:107], v[162:165], v[178:181], v[104:107]
	v_mfma_f32_16x16x32_bf16 v[96:99], v[170:173], v[178:181], v[96:99]
	v_mfma_f32_16x16x32_bf16 v[88:91], v[162:165], v[190:193], v[88:91]
	v_mfma_f32_16x16x32_bf16 v[80:83], v[170:173], v[190:193], v[80:83]
	v_mfma_f32_16x16x32_bf16 v[76:79], v[162:165], v[198:201], v[76:79]
	v_mfma_f32_16x16x32_bf16 v[72:75], v[170:173], v[198:201], v[72:75]
	v_mfma_f32_16x16x32_bf16 v[68:71], v[162:165], v[206:209], v[68:71]
	v_mfma_f32_16x16x32_bf16 v[64:67], v[170:173], v[206:209], v[64:67]
	v_mfma_f32_16x16x32_bf16 v[104:107], v[166:169], v[182:185], v[104:107]
	v_mfma_f32_16x16x32_bf16 v[96:99], v[174:177], v[182:185], v[96:99]
	v_mfma_f32_16x16x32_bf16 v[88:91], v[166:169], v[194:197], v[88:91]
	v_mfma_f32_16x16x32_bf16 v[80:83], v[174:177], v[194:197], v[80:83]
	v_mfma_f32_16x16x32_bf16 v[76:79], v[166:169], v[202:205], v[76:79]
	v_mfma_f32_16x16x32_bf16 v[72:75], v[174:177], v[202:205], v[72:75]
	v_mfma_f32_16x16x32_bf16 v[68:71], v[166:169], v[210:213], v[68:71]
	v_mfma_f32_16x16x32_bf16 v[64:67], v[174:177], v[210:213], v[64:67]
	s_barrier
; #define PG8_STAGE(bufoff, gbase, voff) do { _Pragma("unroll") for (int _i = 0; _i < 2; ++_i) \
;         __builtin_amdgcn_global_load_lds((const unsigned*)((const char*)(gbase) + (voff)[_i]), (PG8_LAS unsigned*)(lds + (bufoff) + ldsw + _i * 8192), 16, 0, 0); } while (0)
; #define PG8_LDA(dst, b, h) do { _Pragma("unroll") for (int m = 0; m < 4; ++m) _Pragma("unroll") for (int k = 0; k < 2; ++k) dst[m][k] = *(const PG8_LAS bf16x8*)(lds + PG8_SA(b, h) + aoff + m * 2048 + k * 1024); } while (0)
; #define PG8_MMA(ai, bj, At, Bt) do { __builtin_amdgcn_s_setprio(1); _Pragma("unroll") for (int m = 0; m < 4; ++m) _Pragma("unroll") for (int n = 0; n < 2; ++n) _Pragma("unroll") for (int k = 0; k < 2; ++k) \
;         acc[ai][bj][m][n] = __builtin_amdgcn_mfma_f32_16x16x32_bf16(Bt[n][k], At[m][k], acc[ai][bj][m][n], 0, 0, 0); __builtin_amdgcn_s_setprio(0); } while (0)
; #define PG8_WAIT_V(n) asm volatile("s_waitcnt vmcnt(" #n ")" ::: "memory")
; #define PG8_WAIT_L(n) asm volatile("s_waitcnt lgkmcnt(" #n ")" ::: "memory")
; #define PG8_BAR __builtin_amdgcn_s_barrier()
; #define PG8_SCHED __builtin_amdgcn_sched_barrier(0)
; template <class Epi, class Sched, bool ALIGN_EPI = false, bool SP2 = false, bool A_TILED = false, bool B_TILED = false>
; __device__ __forceinline__ void gemm_phase(PG8_LAS unsigned char* lds, const Gemm g, const Sched& S, const Epi& E) {
;     ...
;             PG8_LDA(At, 1, 1); PG8_STAGE(PG8_SB(1, 0), b3, voffB); PG8_STAGE(PG8_SB(1, 1), b3 + hstepB, voffB); PG8_STAGE(PG8_SA(1, 0), a3, voffA);
;             PG8_WAIT_V(8); PG8_WAIT_L(0); PG8_BAR; PG8_MMA(1, 0, At, B0); PG8_MMA(1, 1, At, B1); PG8_BAR; PG8_SCHED;
;     ...
;         if constexpr (ALIGN_EPI) { if (wr == 0) PG8_BAR; }
	s_add_i32 s30, s56, s34
	v_lshl_add_u64 v[186:187], v[186:187], 0, s[12:13]
	s_mov_b32 m0, s30
	ds_read_b128 v[178:181], v145 offset:49152
	ds_read_b128 v[182:185], v145 offset:50176
	ds_read_b128 v[190:193], v145 offset:51200
	ds_read_b128 v[194:197], v145 offset:52224
	ds_read_b128 v[198:201], v145 offset:53248
	ds_read_b128 v[202:205], v145 offset:54272
	ds_read_b128 v[206:209], v145 offset:55296
	ds_read_b128 v[210:213], v145 offset:56320
	global_load_lds_dwordx4 v[186:187], off
	s_add_i32 m0, s30, 0x2000
	s_add_u32 s28, s28, 0x2b0080
	v_lshl_add_u64 v[186:187], v[214:215], 0, s[12:13]
	s_addc_u32 s29, s29, 0
	s_add_i32 s30, s57, s34
	global_load_lds_dwordx4 v[186:187], off
	v_lshl_add_u64 v[186:187], s[28:29], 0, v[128:129]
	s_mov_b32 m0, s30
	s_nop 0
	global_load_lds_dwordx4 v[186:187], off
	v_lshl_add_u64 v[186:187], s[28:29], 0, v[134:135]
	s_add_i32 m0, s30, 0x2000
	s_nop 0
	global_load_lds_dwordx4 v[186:187], off
	v_lshl_add_u64 v[186:187], s[26:27], 0, v[130:131]
	s_mov_b32 m0, s39
	s_nop 0
	global_load_lds_dwordx4 v[186:187], off
	v_lshl_add_u64 v[186:187], s[26:27], 0, v[132:133]
	s_mov_b32 m0, s40
	s_nop 0
	global_load_lds_dwordx4 v[186:187], off
	s_waitcnt vmcnt(8)
	s_waitcnt lgkmcnt(0)
	s_barrier
	v_mfma_f32_16x16x32_bf16 v[60:63], v[146:149], v[178:181], v[60:63]
	v_mfma_f32_16x16x32_bf16 v[56:59], v[154:157], v[178:181], v[56:59]
	v_mfma_f32_16x16x32_bf16 v[52:55], v[146:149], v[190:193], v[52:55]
	v_mfma_f32_16x16x32_bf16 v[48:51], v[154:157], v[190:193], v[48:51]
	v_mfma_f32_16x16x32_bf16 v[44:47], v[146:149], v[198:201], v[44:47]
	v_mfma_f32_16x16x32_bf16 v[36:39], v[154:157], v[198:201], v[36:39]
	v_mfma_f32_16x16x32_bf16 v[28:31], v[146:149], v[206:209], v[28:31]
	v_mfma_f32_16x16x32_bf16 v[20:23], v[154:157], v[206:209], v[20:23]
	v_mfma_f32_16x16x32_bf16 v[60:63], v[150:153], v[182:185], v[60:63]
	v_mfma_f32_16x16x32_bf16 v[56:59], v[158:161], v[182:185], v[56:59]
	v_mfma_f32_16x16x32_bf16 v[52:55], v[150:153], v[194:197], v[52:55]
	v_mfma_f32_16x16x32_bf16 v[48:51], v[158:161], v[194:197], v[48:51]
	v_mfma_f32_16x16x32_bf16 v[44:47], v[150:153], v[202:205], v[44:47]
	v_mfma_f32_16x16x32_bf16 v[36:39], v[158:161], v[202:205], v[36:39]
	v_mfma_f32_16x16x32_bf16 v[28:31], v[150:153], v[210:213], v[28:31]
	v_mfma_f32_16x16x32_bf16 v[20:23], v[158:161], v[210:213], v[20:23]
	v_mfma_f32_16x16x32_bf16 v[40:43], v[162:165], v[178:181], v[40:43]
	v_mfma_f32_16x16x32_bf16 v[32:35], v[170:173], v[178:181], v[32:35]
	v_mfma_f32_16x16x32_bf16 v[24:27], v[162:165], v[190:193], v[24:27]
	v_mfma_f32_16x16x32_bf16 v[16:19], v[170:173], v[190:193], v[16:19]
	v_mfma_f32_16x16x32_bf16 v[12:15], v[162:165], v[198:201], v[12:15]
	v_mfma_f32_16x16x32_bf16 v[8:11], v[170:173], v[198:201], v[8:11]
	v_mfma_f32_16x16x32_bf16 v[4:7], v[162:165], v[206:209], v[4:7]
	v_mfma_f32_16x16x32_bf16 v[0:3], v[170:173], v[206:209], v[0:3]
	v_mfma_f32_16x16x32_bf16 v[40:43], v[166:169], v[182:185], v[40:43]
	v_mfma_f32_16x16x32_bf16 v[32:35], v[174:177], v[182:185], v[32:35]
	v_mfma_f32_16x16x32_bf16 v[24:27], v[166:169], v[194:197], v[24:27]
	v_mfma_f32_16x16x32_bf16 v[16:19], v[174:177], v[194:197], v[16:19]
	v_mfma_f32_16x16x32_bf16 v[12:15], v[166:169], v[202:205], v[12:15]
	v_mfma_f32_16x16x32_bf16 v[8:11], v[174:177], v[202:205], v[8:11]
	v_mfma_f32_16x16x32_bf16 v[4:7], v[166:169], v[210:213], v[4:7]
	v_mfma_f32_16x16x32_bf16 v[0:3], v[174:177], v[210:213], v[0:3]
	s_barrier
	s_add_u32 s53, s53, 0x100
	s_addc_u32 s54, s54, 0
	s_add_u32 s24, s24, 0x10000
	s_addc_u32 s25, s25, 0
	s_cmp_ge_i32 s55, s19
	s_mov_b32 s26, s55
	s_cbranch_scc0 .LBB0_1097
	s_and_b64 vcc, exec, s[14:15]
	s_cbranch_vccz .LBB0_1100
	s_barrier
